# v15: v5 + removed 727 unneeded s_nop 0 (hipcc's post-inline-asm pads between plain f32 VALU ops) in the Hyena FFT phase
# speedup vs baseline: 1.0097x; 1.0060x over previous
; __device__ __forceinline__ float shfl_xor_l(float v, int o, int lane) { return __int_as_float(__builtin_amdgcn_ds_bpermute((lane ^ o) << 2, __float_as_int(v))); }
; __device__ __forceinline__ float ffma_(float a, float b, float c) { float r; asm("v_fma_f32 %0, %1, %2, %3" : "=v"(r) : "v"(a), "v"(b), "v"(c)); return r; }
; template <int NPT>
; __device__ __forceinline__ void hyena_unit(LAS unsigned char* lds, int ch, int rowbase, int nb, const float* H2, const float* w3, const float* bias, bf16_t* ST, const f32x2* T2, int tid_in) {
;     ...
; #pragma unroll 2
;       for (int it = 0; it < N / 128; ++it) { const int t = wv * (N / 8) + it * 16 + rr; const f32x4* hp = (const f32x4*)(H2 + (size_t)t * 64) + qs; float af = 0.f, ab = 0.f;
; #pragma unroll
;           for (int s4 = 0; s4 < 4; ++s4) { const f32x4 h = hp[4 * s4];
;               af = ffma_(h.x, wf[s4 * 4], af); af = ffma_(h.y, wf[s4 * 4 + 1], af); af = ffma_(h.z, wf[s4 * 4 + 2], af); af = ffma_(h.w, wf[s4 * 4 + 3], af);
;               ab = ffma_(h.x, wb[s4 * 4], ab); ab = ffma_(h.y, wb[s4 * 4 + 1], ab); ab = ffma_(h.z, wb[s4 * 4 + 2], ab); ab = ffma_(h.w, wb[s4 * 4 + 3], ab); }
;           af += shfl_xor_l(af, 1, lane); ab += shfl_xor_l(ab, 1, lane); af += shfl_xor_l(af, 2, lane); ab += shfl_xor_l(ab, 2, lane);
;           if (qs == 0) { const float win = __builtin_amdgcn_exp2f((float)t * tsc); FW[t] = af * win + (t == 0 ? bs : 0.f); BW[t] = ab * win; } } }
.LBB0_617:
	v_ashrrev_i32_e32 v35, 31, v34
	v_lshlrev_b64 v[38:39], 8, v[34:35]
	v_lshl_add_u64 v[38:39], v[36:37], 0, v[38:39]
	s_waitcnt lgkmcnt(0)
	global_load_dwordx4 v[46:49], v[38:39], off
	s_waitcnt vmcnt(0) lgkmcnt(0)
	v_fma_f32 v35, v46, v0, v177
	v_fma_f32 v45, v46, v8, v177
	v_fma_f32 v35, v47, v1, v35
	v_fma_f32 v45, v47, v9, v45
	v_fma_f32 v35, v48, v2, v35
	v_fma_f32 v45, v48, v10, v45
	v_fma_f32 v35, v49, v3, v35
	v_fma_f32 v45, v49, v11, v45
	global_load_dwordx4 v[46:49], v[38:39], off offset:64
	s_waitcnt vmcnt(0) lgkmcnt(0)
	v_fma_f32 v35, v46, v4, v35
	v_fma_f32 v45, v46, v12, v45
	v_fma_f32 v35, v47, v5, v35
	v_fma_f32 v45, v47, v13, v45
	v_fma_f32 v35, v48, v6, v35
	v_fma_f32 v45, v48, v14, v45
	v_fma_f32 v35, v49, v7, v35
	v_fma_f32 v45, v49, v15, v45
	global_load_dwordx4 v[46:49], v[38:39], off offset:128
	s_waitcnt vmcnt(0) lgkmcnt(0)
	v_fma_f32 v35, v46, v16, v35
	v_fma_f32 v45, v46, v24, v45
	v_fma_f32 v35, v47, v17, v35
	v_fma_f32 v45, v47, v25, v45
	v_fma_f32 v35, v48, v18, v35
	v_fma_f32 v45, v48, v26, v45
	v_fma_f32 v35, v49, v19, v35
	v_fma_f32 v45, v49, v27, v45
	global_load_dwordx4 v[46:49], v[38:39], off offset:192
	s_waitcnt vmcnt(0) lgkmcnt(0)
	v_fma_f32 v35, v46, v20, v35
	v_fma_f32 v38, v46, v28, v45
	v_fma_f32 v35, v47, v21, v35
	v_fma_f32 v38, v47, v29, v38
	v_fma_f32 v35, v48, v22, v35
	v_fma_f32 v38, v48, v30, v38
	v_fma_f32 v35, v49, v23, v35
	v_fma_f32 v39, v49, v31, v38
	ds_bpermute_b32 v38, v42, v35
	s_waitcnt lgkmcnt(0)
	v_add_f32_e32 v38, v35, v38
	ds_bpermute_b32 v35, v42, v39
	ds_bpermute_b32 v45, v43, v38
	s_waitcnt lgkmcnt(1)
	v_add_f32_e32 v39, v39, v35
	ds_bpermute_b32 v46, v43, v39
	v_add_u32_e32 v35, s10, v44
	s_and_saveexec_b64 s[6:7], vcc
	s_cbranch_execz .LBB0_619
	s_waitcnt lgkmcnt(1)
	v_add_f32_e32 v38, v38, v45
	v_cvt_f32_i32_e32 v45, v34
	v_cmp_eq_u32_e64 s[2:3], 0, v34
	s_waitcnt lgkmcnt(0)
	v_add_f32_e32 v39, v39, v46
	v_mul_f32_e32 v45, v41, v45
	v_exp_f32_e32 v45, v45
	v_cndmask_b32_e64 v46, 0, v33, s[2:3]
	v_fmac_f32_e32 v46, v45, v38
	v_mul_f32_e32 v38, v45, v39
	ds_write2st64_b32 v35, v46, v38 offset1:64
.LBB0_619:
	s_or_b64 exec, exec, s[6:7]
	v_add_u32_e32 v38, 16, v34
	v_ashrrev_i32_e32 v39, 31, v38
	s_waitcnt lgkmcnt(0)
	v_lshlrev_b64 v[46:47], 8, v[38:39]
	v_lshl_add_u64 v[50:51], v[36:37], 0, v[46:47]
	global_load_dwordx4 v[46:49], v[50:51], off
	s_waitcnt vmcnt(0) lgkmcnt(0)
	v_fma_f32 v39, v46, v0, v177
	v_fma_f32 v45, v46, v8, v177
	v_fma_f32 v39, v47, v1, v39
	v_fma_f32 v45, v47, v9, v45
	v_fma_f32 v39, v48, v2, v39
	v_fma_f32 v45, v48, v10, v45
	v_fma_f32 v39, v49, v3, v39
	v_fma_f32 v45, v49, v11, v45
	global_load_dwordx4 v[46:49], v[50:51], off offset:64
	s_waitcnt vmcnt(0) lgkmcnt(0)
	v_fma_f32 v39, v46, v4, v39
	v_fma_f32 v45, v46, v12, v45
	v_fma_f32 v39, v47, v5, v39
	v_fma_f32 v45, v47, v13, v45
	v_fma_f32 v39, v48, v6, v39
	v_fma_f32 v45, v48, v14, v45
	v_fma_f32 v39, v49, v7, v39
	v_fma_f32 v45, v49, v15, v45
	global_load_dwordx4 v[46:49], v[50:51], off offset:128
	s_waitcnt vmcnt(0) lgkmcnt(0)
	v_fma_f32 v39, v46, v16, v39
	v_fma_f32 v45, v46, v24, v45
	v_fma_f32 v39, v47, v17, v39
	v_fma_f32 v45, v47, v25, v45
	v_fma_f32 v39, v48, v18, v39
	v_fma_f32 v45, v48, v26, v45
	v_fma_f32 v39, v49, v19, v39
	v_fma_f32 v45, v49, v27, v45
	global_load_dwordx4 v[46:49], v[50:51], off offset:192
	s_waitcnt vmcnt(0) lgkmcnt(0)
	v_fma_f32 v39, v46, v20, v39
	v_fma_f32 v45, v46, v28, v45
	v_fma_f32 v39, v47, v21, v39
	v_fma_f32 v45, v47, v29, v45
	v_fma_f32 v39, v48, v22, v39
	v_fma_f32 v45, v48, v30, v45
	v_fma_f32 v39, v49, v23, v39
	ds_bpermute_b32 v46, v42, v39
	v_fma_f32 v45, v49, v31, v45
	s_waitcnt lgkmcnt(0)
	v_add_f32_e32 v39, v39, v46
	ds_bpermute_b32 v46, v42, v45
	s_waitcnt lgkmcnt(0)
	v_add_f32_e32 v45, v45, v46
	ds_bpermute_b32 v46, v43, v39
	ds_bpermute_b32 v47, v43, v45
	s_and_saveexec_b64 s[2:3], vcc
	s_cbranch_execz .LBB0_616
	v_cvt_f32_i32_e32 v38, v38
	s_waitcnt lgkmcnt(0)
	v_add_f32_e32 v45, v45, v47
	v_add_f32_e32 v39, v39, v46
	v_add_u32_e32 v35, 64, v35
	v_mul_f32_e32 v38, v41, v38
	v_exp_f32_e32 v38, v38
	s_nop 0
	v_fma_f32 v39, v38, v39, 0
	v_mul_f32_e32 v38, v38, v45
	ds_write2st64_b32 v35, v39, v38 offset1:64
	s_branch .LBB0_616

; template <int R, bool UNIT> __device__ __forceinline__ void dif_regs(f32x2* v, f32x2 wb) {
;     float k1 = 0.92387953251128674f, k2 = 0.70710678118654752f, k3 = 0.38268343236508977f; asm volatile("" : "+v"(k1), "+v"(k2), "+v"(k3));
; #pragma unroll
;     for (int t = 0; t < R; ++t) { constexpr int dummy = 0; (void)dummy; const int half = 1 << (R - 1 - t);
; #pragma unroll
;         for (int k = 0; k < (1 << R); ++k) if (!(k & half)) { const int kk = k & (half - 1), m = kk * (8 / half);
;             const f32x2 a = v[k], b = v[k + half]; v[k] = cadd(a, b); const f32x2 d = csub(a, b);
;             if (UNIT) { v[k + half] = (m == 0) ? d : (m == 4) ? (f32x2){d.y, -d.x} : cmul(d, CW16(m)); }
;             else { const f32x2 tw = (m == 0) ? wb : cmul(wb, CW16(m)); v[k + half] = cmul(d, tw); } }
;         if (!UNIT) wb = cmul(wb, wb); }
; }
; template <int R> __device__ __forceinline__ void dif_pass_rt(LAS f32x2* X, int sl, const f32x2 wb_in, int tid) {
;     float wbx = wb_in.x, wby = wb_in.y; asm volatile("" : "+v"(wbx), "+v"(wby)); const f32x2 wb = {wbx, wby};
;     const int r = tid & ((1 << sl) - 1), base = ((tid >> sl) << (sl + R)) + r;
;     LAS f32x2* Xb = X + PADI(base); f32x2 v[1 << R];
; #pragma unroll
;     for (int k = 0; k < (1 << R); ++k) v[k] = Xb[(k << sl) + ((k << sl) >> 4)];
;     dif_regs<R, false>(v, wb);
; #pragma unroll
;     for (int k = 0; k < (1 << R); ++k) Xb[(k << sl) + ((k << sl) >> 4)] = v[k];
; }
; template <int R> __device__ __forceinline__ void dit_pass_rt(LAS f32x2* X, int sl, const f32x2 wb_in, int tid) {
;     float wbx = wb_in.x, wby = wb_in.y; asm volatile("" : "+v"(wbx), "+v"(wby)); const f32x2 wbig = {wbx, wby};
;     const int r = tid & ((1 << sl) - 1), base = ((tid >> sl) << (sl + R)) + r;
;     LAS f32x2* Xb = X + PADI(base); f32x2 v[1 << R];
; #pragma unroll
;     for (int k = 0; k < (1 << R); ++k) v[k] = Xb[(k << sl) + ((k << sl) >> 4)];
;     dit_regs<R, false>(v, wbig);
; #pragma unroll
;     for (int k = 0; k < (1 << R); ++k) Xb[(k << sl) + ((k << sl) >> 4)] = v[k];
; }
; template <int NPT> __device__ __forceinline__ void fwd2_to_lds(LAS f32x2* Xe, LAS f32x2* Xo, const f32x2* tw, int tid, f32x2* ve, f32x2* vo) {
;     constexpr int R = NPT == 16 ? 4 : 3;
;     asm volatile("" : "+v"(tid)); __syncthreads();
;     { LAS f32x2* Pe = Xe + PADI(tid); LAS f32x2* Po = Xo + PADI(tid);
; #pragma unroll
.LBB0_639:
	s_cmp_eq_u32 s2, 1
	s_cselect_b32 s3, 6, 3
	s_cmp_lg_u32 s2, 0
	s_cselect_b32 s25, s3, 9
	s_sub_i32 s3, 11, s25
	v_lshlrev_b32_e32 v16, s3, v44
	v_and_b32_e32 v16, 0x7ff, v16
	v_lshlrev_b32_e32 v176, 3, v16
	v_lshl_add_u64 v[16:17], s[50:51], 0, v[176:177]
	global_load_dwordx2 v[16:17], v[16:17], off
	v_bfe_u32 v18, v44, 0, s25
	v_ashrrev_i32_e32 v19, s25, v44
	s_add_i32 s3, s25, 3
	v_lshl_add_u32 v18, v19, s3, v18
	s_lshl_b32 s3, 1, s25
	s_ashr_i32 s6, s3, 4
	s_lshl_b32 s3, s3, 3
	s_lshl_b32 s6, s6, 3
	s_add_i32 s3, s6, s3
	s_lshl_b32 s6, 2, s25
	s_ashr_i32 s7, s6, 4
	s_lshl_b32 s6, s6, 3
	s_lshl_b32 s7, s7, 3
	s_add_i32 s6, s7, s6
	s_lshl_b32 s7, 3, s25
	s_ashr_i32 s10, s7, 4
	s_lshl_b32 s7, s7, 3
	s_lshl_b32 s10, s10, 3
	s_add_i32 s7, s10, s7
	s_lshl_b32 s10, 4, s25
	s_ashr_i32 s11, s10, 4
	s_lshl_b32 s10, s10, 3
	s_lshl_b32 s11, s11, 3
	s_add_i32 s10, s11, s10
	s_lshl_b32 s11, 5, s25
	s_ashr_i32 s24, s11, 4
	s_lshl_b32 s11, s11, 3
	s_lshl_b32 s24, s24, 3
	s_add_i32 s11, s24, s11
	s_lshl_b32 s24, 6, s25
	s_ashr_i32 s26, s24, 4
	s_lshl_b32 s24, s24, 3
	s_lshl_b32 s26, s26, 3
	s_lshl_b32 s25, 7, s25
	v_ashrrev_i32_e32 v19, 4, v18
	s_add_i32 s24, s26, s24
	s_ashr_i32 s26, s25, 4
	v_lshlrev_b32_e32 v38, 3, v19
	v_lshlrev_b32_e32 v39, 3, v18
	s_lshl_b32 s25, s25, 3
	s_lshl_b32 s26, s26, 3
	v_add3_u32 v40, 0, v38, v39
	s_add_i32 s25, s26, s25
	v_add_u32_e32 v41, s3, v40
	v_add_u32_e32 v42, s6, v40
	v_add_u32_e32 v43, s7, v40
	v_add_u32_e32 v45, s10, v40
	v_add_u32_e32 v46, s11, v40
	v_add_u32_e32 v47, s24, v40
	v_add_u32_e32 v48, s25, v40
	v_mov_b32_e32 v49, 0x3f3504f3
	v_mov_b32_e32 v50, 0x3f6c835e
	v_mov_b32_e32 v51, 0x3ec3ef15
	s_add_i32 s55, 0, 0x11000
	s_add_i32 s2, s2, 1
	s_cmp_lg_u32 s2, 3
	s_waitcnt vmcnt(0) lgkmcnt(0)
	v_mov_b32_e32 v36, v17
	v_mov_b32_e32 v37, v16
	ds_read_b64 v[24:25], v40
	ds_read_b64 v[22:23], v41
	ds_read_b64 v[20:21], v42
	ds_read_b64 v[18:19], v43
	ds_read_b64 v[34:35], v45
	ds_read_b64 v[30:31], v46
	ds_read_b64 v[28:29], v47
	ds_read_b64 v[26:27], v48
	s_waitcnt lgkmcnt(3)
	v_add_f32_e32 v52, v25, v35
	v_sub_f32_e32 v25, v25, v35
	s_waitcnt lgkmcnt(2)
	v_add_f32_e32 v35, v23, v31
	v_sub_f32_e32 v23, v23, v31
	v_add_f32_e32 v51, v24, v34
	v_sub_f32_e32 v24, v24, v34
	v_xor_b32_e32 v50, 0x80000000, v49
	v_mul_f32_e32 v34, v24, v37
	v_mul_f32_e32 v24, v24, v36
	v_mul_f32_e32 v31, v37, v50
	v_fma_f32 v34, -v25, v36, v34
	v_fma_f32 v24, v25, v37, v24
	v_add_f32_e32 v25, v22, v30
	v_sub_f32_e32 v22, v22, v30
	v_mul_f32_e32 v30, v37, v49
	v_fma_f32 v49, v36, v49, v31
	v_fma_f32 v30, -v36, v50, v30
	v_mul_f32_e32 v53, v22, v30
	v_mul_f32_e32 v22, v22, v49
	v_fma_f32 v53, -v23, v49, v53
	v_fma_f32 v22, v23, v30, v22
	s_waitcnt lgkmcnt(1)
	v_add_f32_e32 v23, v20, v28
	v_add_f32_e32 v30, v21, v29
	v_sub_f32_e32 v20, v20, v28
	v_sub_f32_e32 v21, v21, v29
	v_mul_f32_e32 v28, v37, v177
	v_mul_f32_e32 v29, v37, v197
	v_fma_f32 v28, -v36, v197, v28
	v_fma_f32 v29, v36, v177, v29
	v_mul_f32_e32 v49, v20, v28
	v_mul_f32_e32 v20, v20, v29
	v_fma_f32 v49, -v21, v29, v49
	v_fma_f32 v20, v21, v28, v20
	s_waitcnt lgkmcnt(0)
	v_add_f32_e32 v21, v18, v26
	v_sub_f32_e32 v18, v18, v26
	v_add_f32_e32 v28, v19, v27
	v_sub_f32_e32 v19, v19, v27
	v_fma_f32 v26, -v36, v50, v31
	v_fma_f32 v27, v36, v50, v31
	v_add_f32_e32 v31, v52, v30
	v_sub_f32_e32 v30, v52, v30
	v_add_f32_e32 v52, v24, v20
	v_sub_f32_e32 v20, v24, v20
	v_mul_f32_e32 v29, v18, v26
	v_mul_f32_e32 v18, v18, v27
	v_fma_f32 v29, -v19, v27, v29
	v_fma_f32 v18, v19, v26, v18
	v_mul_f32_e32 v19, v37, v37
	v_mul_f32_e32 v26, v37, v36
	v_add_f32_e32 v27, v51, v23
	v_sub_f32_e32 v23, v51, v23
	v_add_f32_e32 v51, v34, v49
	v_add_f32_e32 v55, v22, v18
	v_fma_f32 v19, -v36, v36, v19
	v_fma_f32 v26, v36, v37, v26
	v_add_f32_e32 v37, v35, v28
	v_sub_f32_e32 v18, v22, v18
	v_add_f32_e32 v54, v53, v29
	v_mul_f32_e32 v36, v23, v19
	v_mul_f32_e32 v23, v23, v26
	v_sub_f32_e32 v22, v31, v37
	v_fma_f32 v36, -v30, v26, v36
	v_fma_f32 v30, v30, v19, v23
	v_add_f32_e32 v23, v25, v21
	v_sub_f32_e32 v21, v25, v21
	v_sub_f32_e32 v25, v35, v28
	v_mul_f32_e32 v28, v19, v177
	v_mul_f32_e32 v35, v19, v197
	v_fma_f32 v28, -v26, v197, v28
	v_fma_f32 v35, v26, v177, v35
	v_mul_f32_e32 v50, v21, v28
	v_mul_f32_e32 v21, v21, v35
	v_fma_f32 v50, -v25, v35, v50
	v_fma_f32 v25, v25, v28, v21
	v_sub_f32_e32 v21, v34, v49
	v_mul_f32_e32 v24, v21, v19
	v_mul_f32_e32 v21, v21, v26
	v_fma_f32 v34, -v20, v26, v24
	v_fma_f32 v49, v20, v19, v21
	v_sub_f32_e32 v20, v53, v29
	v_sub_f32_e32 v29, v51, v54
	v_mul_f32_e32 v21, v20, v28
	v_mul_f32_e32 v20, v20, v35
	v_fma_f32 v53, -v18, v35, v21
	v_fma_f32 v35, v18, v28, v20
	v_mul_f32_e32 v18, v19, v19
	v_sub_f32_e32 v21, v27, v23
	v_fma_f32 v56, -v26, v26, v18
	v_mul_f32_e32 v18, v19, v26
	v_fma_f32 v57, v26, v19, v18
	v_mul_f32_e32 v20, v21, v56
	v_add_f32_e32 v18, v27, v23
	v_add_f32_e32 v23, v30, v25
	v_sub_f32_e32 v26, v36, v50
	v_sub_f32_e32 v25, v30, v25
	v_mul_f32_e32 v21, v21, v57
	v_fma_f32 v20, -v22, v57, v20
	v_sub_f32_e32 v30, v52, v55
	v_mul_f32_e32 v28, v29, v56
	v_mul_f32_e32 v29, v29, v57
	v_add_f32_e32 v19, v31, v37
	v_fma_f32 v21, v22, v56, v21
	v_add_f32_e32 v22, v36, v50
	v_sub_f32_e32 v36, v34, v53
	v_fma_f32 v28, -v30, v57, v28
	v_fma_f32 v29, v30, v56, v29
	v_add_f32_e32 v30, v34, v53
	v_add_f32_e32 v31, v49, v35
	v_sub_f32_e32 v35, v49, v35
	v_mul_f32_e32 v34, v36, v56
	v_mul_f32_e32 v36, v36, v57
	v_mul_f32_e32 v24, v26, v56
	v_mul_f32_e32 v26, v26, v57
	v_add_f32_e32 v27, v52, v55
	v_fma_f32 v34, -v35, v57, v34
	v_fma_f32 v35, v35, v56, v36
	v_add3_u32 v36, s55, v38, v39
	v_fma_f32 v24, -v25, v57, v24
	v_fma_f32 v25, v25, v56, v26
	v_add_f32_e32 v26, v51, v54
	ds_write_b64 v40, v[18:19]
	ds_write_b64 v41, v[20:21]
	ds_write_b64 v42, v[22:23]
	ds_write_b64 v43, v[24:25]
	ds_write_b64 v45, v[26:27]
	ds_write_b64 v46, v[28:29]
	ds_write_b64 v47, v[30:31]
	ds_write_b64 v48, v[34:35]
	v_add_u32_e32 v37, s3, v36
	v_add_u32_e32 v38, s6, v36
	v_add_u32_e32 v39, s7, v36
	v_add_u32_e32 v40, s10, v36
	v_add_u32_e32 v41, s11, v36
	v_add_u32_e32 v42, s24, v36
	v_add_u32_e32 v43, s25, v36
	v_mov_b32_e32 v45, 0x3f3504f3
	v_mov_b32_e32 v46, 0x3f6c835e
	v_mov_b32_e32 v47, 0x3ec3ef15
	ds_read_b64 v[28:29], v36
	ds_read_b64 v[26:27], v37
	ds_read_b64 v[22:23], v38
	ds_read_b64 v[18:19], v39
	ds_read_b64 v[34:35], v40
	ds_read_b64 v[30:31], v41
	ds_read_b64 v[24:25], v42
	ds_read_b64 v[20:21], v43
	s_waitcnt lgkmcnt(3)
; #define LAS __attribute__((address_space(3)))
; __device__ __forceinline__ f32x2 cadd(f32x2 a, f32x2 b) { return (f32x2){fadd_(a.x, b.x), fadd_(a.y, b.y)}; }
; __device__ __forceinline__ f32x2 csub(f32x2 a, f32x2 b) { return (f32x2){fsub_(a.x, b.x), fsub_(a.y, b.y)}; }
; __device__ __forceinline__ f32x2 cscale(f32x2 a, float s) { return (f32x2){fmul_(a.x, s), fmul_(a.y, s)}; }
; template <int R, bool UNIT> __device__ __forceinline__ void dif_regs(f32x2* v, f32x2 wb) {
;     float k1 = 0.92387953251128674f, k2 = 0.70710678118654752f, k3 = 0.38268343236508977f; asm volatile("" : "+v"(k1), "+v"(k2), "+v"(k3));
; #pragma unroll
;     for (int t = 0; t < R; ++t) { constexpr int dummy = 0; (void)dummy; const int half = 1 << (R - 1 - t);
; #pragma unroll
;         for (int k = 0; k < (1 << R); ++k) if (!(k & half)) { const int kk = k & (half - 1), m = kk * (8 / half);
;             const f32x2 a = v[k], b = v[k + half]; v[k] = cadd(a, b); const f32x2 d = csub(a, b);
;             if (UNIT) { v[k + half] = (m == 0) ? d : (m == 4) ? (f32x2){d.y, -d.x} : cmul(d, CW16(m)); }
;             else { const f32x2 tw = (m == 0) ? wb : cmul(wb, CW16(m)); v[k + half] = cmul(d, tw); } }
;         if (!UNIT) wb = cmul(wb, wb); }
; }
; template <int NPT> __device__ __forceinline__ void fwd2_to_lds(LAS f32x2* Xe, LAS f32x2* Xo, const f32x2* tw, int tid, f32x2* ve, f32x2* vo) {
;     ...
;     for (int ps = 0; ps < 3; ++ps) { int sl = pass_sl<NPT>(ps); asm volatile("" : "+s"(sl));
;         const f32x2 wb = tw[(tid & ((1 << sl) - 1)) << (14 - R - sl)];
;         dif_pass_rt<R>(Xe, sl, wb, tid); dif_pass_rt<R>(Xo, sl, wb, tid); __syncthreads(); }
; }
; template <int NPT> __device__ __forceinline__ void mid_spectrum(const LAS f32x2* X, int tid, f32x2* K, float sc) {
;     if (NPT == 16) {
; #pragma unroll
;         for (int u = 0; u < 8; ++u) { const LAS f32x2* Xb = X + PADI(2 * tid) + 1088 * u; const f32x2 a = Xb[0], b = Xb[1]; K[2 * u] = cscale(cadd(a, b), sc); K[2 * u + 1] = cscale(csub(a, b), sc); } }
;     else { f32x2 w[8]; const LAS f32x2* Xb = X + PADI(8 * tid);
; #pragma unroll
;         for (int k = 0; k < 8; ++k) w[k] = Xb[k];
;         dif_regs<3, true>(w, (f32x2){1.f, 0.f});
; #pragma unroll
;         for (int k = 0; k < 8; ++k) K[k] = cscale(w[k], sc); }
	v_add_f32_e32 v48, v29, v35
	v_sub_f32_e32 v29, v29, v35
	s_waitcnt lgkmcnt(2)
	v_add_f32_e32 v35, v27, v31
	v_sub_f32_e32 v27, v27, v31
	v_add_f32_e32 v47, v28, v34
	v_sub_f32_e32 v28, v28, v34
	v_xor_b32_e32 v46, 0x80000000, v45
	v_mul_f32_e32 v34, v28, v16
	v_mul_f32_e32 v28, v28, v17
	v_mul_f32_e32 v31, v16, v46
	v_fma_f32 v34, -v29, v17, v34
	v_fma_f32 v28, v29, v16, v28
	v_add_f32_e32 v29, v26, v30
	v_sub_f32_e32 v26, v26, v30
	v_mul_f32_e32 v30, v16, v45
	v_fma_f32 v45, v17, v45, v31
	v_fma_f32 v30, -v17, v46, v30
	v_mul_f32_e32 v49, v26, v30
	v_mul_f32_e32 v26, v26, v45
	v_fma_f32 v49, -v27, v45, v49
	v_fma_f32 v26, v27, v30, v26
	s_waitcnt lgkmcnt(1)
	v_add_f32_e32 v27, v22, v24
	v_add_f32_e32 v30, v23, v25
	v_sub_f32_e32 v22, v22, v24
	v_sub_f32_e32 v23, v23, v25
	v_mul_f32_e32 v24, v16, v177
	v_mul_f32_e32 v25, v16, v197
	v_fma_f32 v24, -v17, v197, v24
	v_fma_f32 v25, v17, v177, v25
	v_mul_f32_e32 v45, v22, v24
	v_mul_f32_e32 v22, v22, v25
	v_fma_f32 v45, -v23, v25, v45
	v_fma_f32 v22, v23, v24, v22
	s_waitcnt lgkmcnt(0)
	v_add_f32_e32 v23, v18, v20
	v_sub_f32_e32 v18, v18, v20
	v_add_f32_e32 v24, v19, v21
	v_sub_f32_e32 v19, v19, v21
	v_fma_f32 v20, -v17, v46, v31
	v_fma_f32 v21, v17, v46, v31
	v_add_f32_e32 v31, v29, v23
	v_mul_f32_e32 v25, v18, v20
	v_mul_f32_e32 v18, v18, v21
	v_add_f32_e32 v46, v35, v24
	v_fma_f32 v25, -v19, v21, v25
	v_fma_f32 v18, v19, v20, v18
	v_mul_f32_e32 v19, v16, v16
	v_mul_f32_e32 v20, v16, v17
	v_add_f32_e32 v21, v48, v30
	v_fma_f32 v19, -v17, v17, v19
	v_fma_f32 v16, v17, v16, v20
	v_sub_f32_e32 v17, v47, v27
	v_add_f32_e32 v20, v47, v27
	v_sub_f32_e32 v27, v48, v30
	v_add_f32_e32 v48, v28, v22
	v_sub_f32_e32 v22, v28, v22
	v_add_f32_e32 v47, v34, v45
	v_mul_f32_e32 v30, v17, v19
	v_mul_f32_e32 v17, v17, v16
	v_add_f32_e32 v50, v26, v18
	v_sub_f32_e32 v18, v26, v18
	v_fma_f32 v30, -v27, v16, v30
	v_fma_f32 v27, v27, v19, v17
	v_sub_f32_e32 v17, v29, v23
	v_sub_f32_e32 v23, v35, v24
	v_mul_f32_e32 v24, v19, v177
	v_mul_f32_e32 v29, v19, v197
	v_fma_f32 v24, -v16, v197, v24
	v_fma_f32 v29, v16, v177, v29
	v_mul_f32_e32 v35, v17, v24
	v_mul_f32_e32 v17, v17, v29
	v_fma_f32 v35, -v23, v29, v35
	v_fma_f32 v23, v23, v24, v17
	v_sub_f32_e32 v17, v34, v45
	v_mul_f32_e32 v28, v17, v19
	v_mul_f32_e32 v17, v17, v16
	v_fma_f32 v45, v22, v19, v17
	v_sub_f32_e32 v17, v49, v25
	v_fma_f32 v34, -v22, v16, v28
	v_add_f32_e32 v28, v49, v25
	v_add_f32_e32 v25, v48, v50
	v_mul_f32_e32 v22, v17, v24
	v_mul_f32_e32 v17, v17, v29
	v_fma_f32 v51, v18, v24, v17
	v_mul_f32_e32 v17, v19, v19
	v_sub_f32_e32 v24, v30, v35
	v_fma_f32 v49, -v18, v29, v22
	v_fma_f32 v52, -v16, v16, v17
	v_mul_f32_e32 v17, v19, v16
	v_add_f32_e32 v29, v45, v51
	v_fma_f32 v53, v16, v19, v17
	v_sub_f32_e32 v19, v20, v31
	v_add_f32_e32 v16, v20, v31
	v_add_f32_e32 v17, v21, v46
	v_sub_f32_e32 v20, v21, v46
	v_add_f32_e32 v21, v27, v23
	v_sub_f32_e32 v23, v27, v23
	v_mul_f32_e32 v18, v19, v52
	v_mul_f32_e32 v19, v19, v53
	v_mul_f32_e32 v22, v24, v52
	v_mul_f32_e32 v24, v24, v53
	v_sub_f32_e32 v27, v47, v28
	v_sub_f32_e32 v31, v34, v49
	v_fma_f32 v18, -v20, v53, v18
	v_fma_f32 v19, v20, v52, v19
	v_add_f32_e32 v20, v30, v35
	v_fma_f32 v22, -v23, v53, v22
	v_fma_f32 v23, v23, v52, v24
	v_add_f32_e32 v24, v47, v28
	v_sub_f32_e32 v28, v48, v50
	v_mul_f32_e32 v26, v27, v52
	v_mul_f32_e32 v27, v27, v53
	v_mul_f32_e32 v30, v31, v52
	v_mul_f32_e32 v31, v31, v53
	v_fma_f32 v26, -v28, v53, v26
	v_fma_f32 v27, v28, v52, v27
	v_add_f32_e32 v28, v34, v49
	v_sub_f32_e32 v34, v45, v51
	v_fma_f32 v30, -v34, v53, v30
	v_fma_f32 v31, v34, v52, v31
	ds_write_b64 v36, v[16:17]
	ds_write_b64 v37, v[18:19]
	ds_write_b64 v38, v[20:21]
	ds_write_b64 v39, v[22:23]
	ds_write_b64 v40, v[24:25]
	ds_write_b64 v41, v[26:27]
	ds_write_b64 v42, v[28:29]
	ds_write_b64 v43, v[30:31]
	s_waitcnt lgkmcnt(0)
	s_barrier
	s_cbranch_scc1 .LBB0_639
	v_and_b32_e32 v33, -8, v33
	v_add_u32_e32 v16, 0, v33
	v_lshlrev_b32_e32 v34, 6, v32
	v_add_u32_e32 v56, v16, v34
	ds_read2_b64 v[16:19], v56 offset1:1
	ds_read2_b64 v[20:23], v56 offset0:2 offset1:3
	ds_read2_b64 v[24:27], v56 offset0:4 offset1:5
	ds_read2_b64 v[28:31], v56 offset0:6 offset1:7
	v_mov_b32_e32 v35, 0x3f3504f3
	v_mov_b32_e32 v36, 0x3f6c835e
	v_mov_b32_e32 v37, 0x3ec3ef15
	s_waitcnt lgkmcnt(1)
	v_add_f32_e32 v38, v17, v25
	v_sub_f32_e32 v17, v17, v25
	v_add_f32_e32 v25, v19, v27
	v_sub_f32_e32 v19, v19, v27
	s_waitcnt lgkmcnt(0)
; #define LAS __attribute__((address_space(3)))
; __device__ __forceinline__ f32x2 cadd(f32x2 a, f32x2 b) { return (f32x2){fadd_(a.x, b.x), fadd_(a.y, b.y)}; }
; __device__ __forceinline__ f32x2 csub(f32x2 a, f32x2 b) { return (f32x2){fsub_(a.x, b.x), fsub_(a.y, b.y)}; }
; __device__ __forceinline__ f32x2 cscale(f32x2 a, float s) { return (f32x2){fmul_(a.x, s), fmul_(a.y, s)}; }
; __device__ __forceinline__ f32x2 cmul(f32x2 a, f32x2 b) { return (f32x2){fnma_(a.y, b.y, fmul_(a.x, b.x)), ffma_(a.y, b.x, fmul_(a.x, b.y))}; }
; template <int R, bool UNIT> __device__ __forceinline__ void dif_regs(f32x2* v, f32x2 wb) {
;     float k1 = 0.92387953251128674f, k2 = 0.70710678118654752f, k3 = 0.38268343236508977f; asm volatile("" : "+v"(k1), "+v"(k2), "+v"(k3));
; #pragma unroll
;     for (int t = 0; t < R; ++t) { constexpr int dummy = 0; (void)dummy; const int half = 1 << (R - 1 - t);
; #pragma unroll
;         for (int k = 0; k < (1 << R); ++k) if (!(k & half)) { const int kk = k & (half - 1), m = kk * (8 / half);
;             const f32x2 a = v[k], b = v[k + half]; v[k] = cadd(a, b); const f32x2 d = csub(a, b);
;             if (UNIT) { v[k + half] = (m == 0) ? d : (m == 4) ? (f32x2){d.y, -d.x} : cmul(d, CW16(m)); }
;             else { const f32x2 tw = (m == 0) ? wb : cmul(wb, CW16(m)); v[k + half] = cmul(d, tw); } }
;         if (!UNIT) wb = cmul(wb, wb); }
; }
; template <int NPT> __device__ __forceinline__ void mid_spectrum(const LAS f32x2* X, int tid, f32x2* K, float sc) {
;     if (NPT == 16) {
; #pragma unroll
;         for (int u = 0; u < 8; ++u) { const LAS f32x2* Xb = X + PADI(2 * tid) + 1088 * u; const f32x2 a = Xb[0], b = Xb[1]; K[2 * u] = cscale(cadd(a, b), sc); K[2 * u + 1] = cscale(csub(a, b), sc); } }
;     else { f32x2 w[8]; const LAS f32x2* Xb = X + PADI(8 * tid);
; #pragma unroll
;         for (int k = 0; k < 8; ++k) w[k] = Xb[k];
;         dif_regs<3, true>(w, (f32x2){1.f, 0.f});
; #pragma unroll
;         for (int k = 0; k < 8; ++k) K[k] = cscale(w[k], sc); }
	v_add_f32_e32 v27, v21, v29
	v_add_f32_e32 v37, v16, v24
	v_sub_f32_e32 v16, v16, v24
	v_add_f32_e32 v24, v18, v26
	v_sub_f32_e32 v18, v18, v26
	v_xor_b32_e32 v36, 0x80000000, v35
	v_mul_f32_e32 v26, v18, v35
	v_mul_f32_e32 v18, v18, v36
	v_sub_f32_e32 v21, v21, v29
	v_add_f32_e32 v29, v23, v31
	v_sub_f32_e32 v23, v23, v31
	v_add_f32_e32 v31, v38, v27
	v_fma_f32 v26, -v19, v36, v26
	v_fma_f32 v18, v19, v35, v18
	v_add_f32_e32 v19, v20, v28
	v_sub_f32_e32 v20, v20, v28
	v_add_f32_e32 v28, v22, v30
	v_sub_f32_e32 v22, v22, v30
	v_sub_f32_e32 v27, v38, v27
	v_readlane_b32 s8, v254, 32
	v_xor_b32_e32 v20, 0x80000000, v20
	v_mul_f32_e32 v22, v22, v36
	v_add_f32_e32 v35, v24, v28
	v_sub_f32_e32 v24, v24, v28
	v_add_f32_e32 v28, v16, v21
	v_sub_f32_e32 v16, v16, v21
	v_readlane_b32 s9, v254, 33
	v_fma_f32 v30, -v23, v36, v22
	v_fma_f32 v22, v23, v36, v22
	v_add_f32_e32 v23, v37, v19
	v_sub_f32_e32 v19, v37, v19
	v_add_f32_e32 v36, v25, v29
	v_sub_f32_e32 v25, v25, v29
	v_add_f32_e32 v29, v17, v20
	v_sub_f32_e32 v17, v17, v20
	v_add_f32_e32 v20, v26, v30
	v_sub_f32_e32 v26, v26, v30
	v_add_f32_e32 v21, v18, v22
	v_sub_f32_e32 v18, v18, v22
	v_xor_b32_e32 v24, 0x80000000, v24
	v_xor_b32_e32 v22, 0x80000000, v26
	v_add_f32_e32 v26, v23, v35
	v_sub_f32_e32 v23, v23, v35
	v_add_f32_e32 v35, v19, v25
	v_sub_f32_e32 v19, v19, v25
	v_add_f32_e32 v25, v28, v20
	v_sub_f32_e32 v20, v28, v20
	v_add_f32_e32 v28, v16, v18
	v_sub_f32_e32 v16, v16, v18
	v_mov_b32_e32 v37, 0x39000000
	v_mul_f32_e32 v71, v16, v37
	v_add_u32_e32 v16, s55, v33
	v_add_f32_e32 v30, v31, v36
	v_sub_f32_e32 v31, v31, v36
	v_add_f32_e32 v36, v27, v24
	v_sub_f32_e32 v24, v27, v24
	v_add_f32_e32 v27, v29, v21
	v_sub_f32_e32 v21, v29, v21
	v_add_f32_e32 v29, v17, v22
	v_sub_f32_e32 v17, v17, v22
	v_add_u32_e32 v73, v16, v34
	v_mul_f32_e32 v57, v26, v37
	v_mul_f32_e32 v58, v30, v37
	v_mul_f32_e32 v59, v23, v37
	v_mul_f32_e32 v60, v31, v37
	v_mul_f32_e32 v63, v19, v37
	v_mul_f32_e32 v64, v24, v37
	v_mul_f32_e32 v65, v25, v37
	v_mul_f32_e32 v66, v27, v37
	v_mul_f32_e32 v67, v20, v37
	v_mul_f32_e32 v68, v21, v37
	v_mul_f32_e32 v69, v28, v37
	v_mul_f32_e32 v70, v29, v37
	v_mul_f32_e32 v72, v17, v37
	ds_read2_b64 v[16:19], v73 offset1:1
	ds_read2_b64 v[20:23], v73 offset0:2 offset1:3
	ds_read2_b64 v[24:27], v73 offset0:4 offset1:5
	ds_read2_b64 v[28:31], v73 offset0:6 offset1:7
	v_mul_f32_e32 v61, v35, v37
	v_mov_b32_e32 v33, 0x3f3504f3
	v_mov_b32_e32 v34, 0x3f6c835e
	v_mov_b32_e32 v35, 0x3ec3ef15
	v_mul_f32_e32 v62, v36, v37
	s_waitcnt lgkmcnt(1)
	v_add_f32_e32 v36, v17, v25
	v_sub_f32_e32 v17, v17, v25
	v_add_f32_e32 v25, v19, v27
	v_sub_f32_e32 v19, v19, v27
	v_add_f32_e32 v35, v16, v24
	v_sub_f32_e32 v16, v16, v24
	v_add_f32_e32 v24, v18, v26
	v_sub_f32_e32 v18, v18, v26
	v_xor_b32_e32 v34, 0x80000000, v33
	v_mul_f32_e32 v26, v18, v33
	v_mul_f32_e32 v18, v18, v34
	s_waitcnt lgkmcnt(0)
	v_add_f32_e32 v27, v21, v29
	v_sub_f32_e32 v21, v21, v29
	v_add_f32_e32 v29, v23, v31
	v_sub_f32_e32 v23, v23, v31
	v_fma_f32 v26, -v19, v34, v26
	v_fma_f32 v18, v19, v33, v18
	v_add_f32_e32 v19, v20, v28
	v_sub_f32_e32 v20, v20, v28
	v_add_f32_e32 v28, v22, v30
	v_sub_f32_e32 v22, v22, v30
	v_readlane_b32 s10, v254, 34
	v_xor_b32_e32 v20, 0x80000000, v20
	v_mul_f32_e32 v22, v22, v34
	v_add_f32_e32 v33, v24, v28
	v_sub_f32_e32 v24, v24, v28
	v_add_f32_e32 v28, v16, v21
	v_sub_f32_e32 v16, v16, v21
	v_readlane_b32 s11, v254, 35
	v_fma_f32 v30, -v23, v34, v22
	v_fma_f32 v22, v23, v34, v22
	v_add_f32_e32 v23, v35, v19
	v_sub_f32_e32 v19, v35, v19
	v_add_f32_e32 v34, v25, v29
	v_sub_f32_e32 v25, v25, v29
	v_add_f32_e32 v29, v17, v20
	v_sub_f32_e32 v17, v17, v20
	v_add_f32_e32 v20, v26, v30
	v_sub_f32_e32 v26, v26, v30
	v_add_f32_e32 v21, v18, v22
	v_sub_f32_e32 v18, v18, v22
	v_add_f32_e32 v31, v36, v27
	v_sub_f32_e32 v27, v36, v27
	v_xor_b32_e32 v24, 0x80000000, v24
	v_xor_b32_e32 v22, 0x80000000, v26
	v_add_f32_e32 v26, v23, v33
	v_sub_f32_e32 v23, v23, v33
	v_add_f32_e32 v33, v19, v25
	v_sub_f32_e32 v19, v19, v25
	v_add_f32_e32 v25, v28, v20
	v_sub_f32_e32 v20, v28, v20
	v_add_f32_e32 v28, v16, v18
	v_sub_f32_e32 v16, v16, v18
	v_mul_f32_e32 v78, v33, v37
	s_lshl_b64 s[2:3], s[8:9], 13
	v_mul_f32_e32 v88, v16, v37
	v_ashrrev_i32_e32 v16, 4, v32
	v_add_lshl_u32 v16, v16, v32, 3
	v_add_u32_e32 v90, 0, v16
	v_add_u32_e32 v91, s55, v16
	v_ashrrev_i32_e32 v33, 31, v32
	s_mov_b64 s[6:7], 0
	s_mov_b64 s[10:11], -1
	v_add_f32_e32 v30, v31, v34
	v_sub_f32_e32 v31, v31, v34
	v_add_f32_e32 v34, v27, v24
	v_sub_f32_e32 v24, v27, v24
	v_add_f32_e32 v27, v29, v21
	v_sub_f32_e32 v21, v29, v21
	v_add_f32_e32 v29, v17, v22
	v_sub_f32_e32 v17, v17, v22
	v_mul_f32_e32 v74, v26, v37
	v_mul_f32_e32 v75, v30, v37
	v_mul_f32_e32 v76, v23, v37
	v_mul_f32_e32 v77, v31, v37
	v_mul_f32_e32 v79, v34, v37
	v_mul_f32_e32 v80, v19, v37
	v_mul_f32_e32 v81, v24, v37
	v_mul_f32_e32 v82, v25, v37
	v_mul_f32_e32 v83, v27, v37
	v_mul_f32_e32 v84, v20, v37
	v_mul_f32_e32 v85, v21, v37
	v_mul_f32_e32 v86, v28, v37
	v_mul_f32_e32 v87, v29, v37
	v_mul_f32_e32 v89, v17, v37
	v_readlane_b32 s12, v254, 36
	v_readlane_b32 s13, v254, 37
	v_readlane_b32 s14, v254, 38
	v_readlane_b32 s15, v254, 39
	v_readlane_b32 s16, v254, 40
	v_readlane_b32 s17, v254, 41
	v_readlane_b32 s18, v254, 42
	v_readlane_b32 s19, v254, 43
	v_readlane_b32 s20, v254, 44
	v_readlane_b32 s21, v254, 45
	v_readlane_b32 s22, v254, 46
	v_readlane_b32 s23, v254, 47
; #define LAS __attribute__((address_space(3)))
; __device__ __forceinline__ float bf2f(unsigned h) { return __uint_as_float(h << 16); }
; __device__ __forceinline__ f32x2 cmul(f32x2 a, f32x2 b) { return (f32x2){fnma_(a.y, b.y, fmul_(a.x, b.x)), ffma_(a.y, b.x, fmul_(a.x, b.y))}; }
; template <int NPT> __device__ __forceinline__ void fwd2_to_lds(LAS f32x2* Xe, LAS f32x2* Xo, const f32x2* tw, int tid, f32x2* ve, f32x2* vo) {
;     constexpr int R = NPT == 16 ? 4 : 3;
;     asm volatile("" : "+v"(tid)); __syncthreads();
;     { LAS f32x2* Pe = Xe + PADI(tid); LAS f32x2* Po = Xo + PADI(tid);
; #pragma unroll
;       for (int k = 0; k < NPT; ++k) { Pe[544 * k] = ve[k]; Po[544 * k] = vo[k]; } }
;     __syncthreads();
; template <int NPT>
; __device__ __forceinline__ void hyena_unit(LAS unsigned char* lds, int ch, int rowbase, int nb, const float* H2, const float* w3, const float* bias, bf16_t* ST, const f32x2* T2, int tid_in) {
;     ...
;     for (int p = 0; p < nb / 2; ++p) {
;         bf16_t* s0 = ST + (size_t)(rowbase + 2 * p * N) * 512 + (size_t)ch * N; bf16_t* s1 = s0 + (size_t)N * 512;
;         f32x2 ve[NPT], vo[NPT];
; #pragma unroll
;         for (int i = 0; i < NPT; ++i) { const int j = tid + 512 * i; ve[i] = (f32x2){bf2f(s0[j]), bf2f(s1[j])}; vo[i] = cmul(ve[i], T2[j * (8192 / N)]); }
.LBB0_641:
	s_xor_b64 s[82:83], s[10:11], -1
	s_lshl_b64 s[6:7], s[6:7], 1
	s_add_u32 s6, s50, s6
	s_addc_u32 s7, s51, s7
	s_add_u32 s6, s6, s2
	s_addc_u32 s7, s7, s3
	v_lshl_add_u64 v[30:31], v[32:33], 1, s[6:7]
	s_mov_b64 s[6:7], 0x2d400000
	v_lshl_add_u64 v[16:17], v[30:31], 0, s[6:7]
	s_mov_b64 s[6:7], 0x2d800000
	v_lshl_add_u64 v[18:19], v[30:31], 0, s[6:7]
	s_mov_b32 s6, 0x2d400000
	v_add_co_u32_e32 v20, vcc, s6, v30
	s_mov_b32 s6, 0x2d401000
	s_nop 0
	v_addc_co_u32_e32 v21, vcc, 0, v31, vcc
	global_load_ushort v92, v[20:21], off
	global_load_ushort v48, v[16:17], off offset:1024
	global_load_ushort v49, v[18:19], off offset:1024
	global_load_ushort v50, v[16:17], off offset:2048
	global_load_ushort v51, v[18:19], off offset:2048
	v_add_co_u32_e32 v20, vcc, s6, v30
	s_mov_b32 s6, 0x2d801000
	s_nop 0
	v_addc_co_u32_e32 v21, vcc, 0, v31, vcc
	v_add_co_u32_e32 v22, vcc, s6, v30
	s_mov_b32 s6, 0x2d800000
	s_nop 0
	v_addc_co_u32_e32 v23, vcc, 0, v31, vcc
	global_load_ushort v52, v[22:23], off
	global_load_ushort v54, v[20:21], off
	global_load_ushort v55, v[22:23], off offset:1024
	global_load_ushort v93, v[20:21], off offset:1024
	v_add_co_u32_e32 v24, vcc, s6, v30
	global_load_dwordx2 v[28:29], v[2:3], off
	global_load_dwordx2 v[34:35], v[4:5], off
	global_load_dwordx2 v[36:37], v[8:9], off
	global_load_dwordx2 v[38:39], v[10:11], off
	v_addc_co_u32_e32 v25, vcc, 0, v31, vcc
	global_load_ushort v95, v[24:25], off
	global_load_dwordx2 v[40:41], v[6:7], off
	global_load_dwordx2 v[42:43], v[0:1], off
	global_load_ushort v100, v[18:19], off offset:3072
	global_load_ushort v102, v[16:17], off offset:3072
	global_load_ushort v106, v[22:23], off offset:2048
	global_load_ushort v107, v[20:21], off offset:2048
	global_load_dwordx2 v[44:45], v[12:13], off
	global_load_ushort v108, v[22:23], off offset:3072
	global_load_ushort v109, v[20:21], off offset:3072
	global_load_dwordx2 v[46:47], v[14:15], off
	s_mov_b64 s[10:11], 0x2d401000
	v_lshl_add_u64 v[24:25], v[30:31], 0, s[10:11]
	s_mov_b64 s[10:11], 0x2d801000
	v_lshl_add_u64 v[26:27], v[30:31], 0, s[10:11]
	s_mov_b64 s[10:11], 0x2d401400
	v_lshl_add_u64 v[20:21], v[30:31], 0, s[10:11]
	s_mov_b64 s[10:11], 0x2d801400
	v_lshl_add_u64 v[22:23], v[30:31], 0, s[10:11]
	s_mov_b64 s[10:11], 0x2d401800
	s_mov_b32 s6, 0
	s_waitcnt vmcnt(0) lgkmcnt(0)
	v_lshlrev_b32_e32 v94, 16, v92
	v_lshlrev_b32_e32 v48, 16, v48
	v_lshlrev_b32_e32 v49, 16, v49
	v_mul_f32_e32 v92, v48, v28
	v_lshlrev_b32_e32 v53, 16, v52
	v_lshlrev_b32_e32 v52, 16, v54
	v_lshlrev_b32_e32 v54, 16, v93
	v_mul_f32_e32 v93, v48, v29
	v_mul_f32_e32 v103, v52, v36
	v_mul_f32_e32 v104, v52, v37
	v_mul_f32_e32 v105, v54, v38
	v_lshlrev_b32_e32 v101, 16, v100
	v_fma_f32 v97, v49, v28, v93
	v_lshlrev_b32_e32 v100, 16, v102
	v_mul_f32_e32 v28, v100, v40
	v_lshlrev_b32_e32 v55, 16, v55
	v_mul_f32_e32 v110, v54, v39
	v_lshlrev_b32_e32 v95, 16, v95
	v_mul_f32_e32 v111, v94, v42
	v_mul_f32_e32 v112, v94, v43
	v_fma_f32 v96, -v49, v29, v92
	v_fma_f32 v102, -v53, v37, v103
	v_fma_f32 v103, v53, v36, v104
	v_fma_f32 v104, -v55, v39, v105
	v_fma_f32 v105, v55, v38, v110
	v_fma_f32 v38, -v95, v43, v111
	v_fma_f32 v39, v95, v42, v112
	v_mul_f32_e32 v29, v100, v41
	v_fma_f32 v42, -v101, v41, v28
	v_lshlrev_b32_e32 v50, 16, v50
	v_fma_f32 v43, v101, v40, v29
	v_lshlrev_b32_e32 v40, 16, v107
	v_mul_f32_e32 v28, v40, v44
	v_mul_f32_e32 v98, v50, v34
	v_mul_f32_e32 v99, v50, v35
	v_lshlrev_b32_e32 v41, 16, v106
	v_fma_f32 v106, -v41, v45, v28
	v_mul_f32_e32 v28, v40, v45
	v_lshlrev_b32_e32 v51, 16, v51
	v_fma_f32 v107, v41, v44, v28
	v_lshlrev_b32_e32 v44, 16, v109
	v_mul_f32_e32 v92, v44, v46
	v_fma_f32 v98, -v51, v35, v98
	v_fma_f32 v99, v51, v34, v99
	v_lshl_add_u64 v[34:35], v[30:31], 0, s[10:11]
	s_mov_b64 s[10:11], 0x2d801800
	v_lshlrev_b32_e32 v45, 16, v108
	v_fma_f32 v108, -v45, v47, v92
	v_mov_b32_e32 v92, v32
	v_lshl_add_u64 v[36:37], v[30:31], 0, s[10:11]
	s_mov_b64 s[10:11], 0x2d401c00
	v_mul_f32_e32 v47, v44, v47
	v_lshl_add_u64 v[28:29], v[30:31], 0, s[10:11]
	v_fma_f32 v109, v45, v46, v47
	v_ashrrev_i32_e32 v46, 4, v92
	s_mov_b64 s[10:11], 0x2d801c00
	v_add_u32_e32 v46, v46, v92
	v_lshl_add_u64 v[30:31], v[30:31], 0, s[10:11]
	v_lshl_add_u32 v46, v46, 3, 0
	s_barrier
	v_add_u32_e32 v47, 0x11000, v46
	ds_write_b64 v46, v[94:95]
	ds_write_b64 v47, v[38:39]
	ds_write_b64 v46, v[48:49] offset:4352
	ds_write_b64 v47, v[96:97] offset:4352
	ds_write_b64 v46, v[50:51] offset:8704
	ds_write_b64 v47, v[98:99] offset:8704
	ds_write_b64 v46, v[100:101] offset:13056
	ds_write_b64 v47, v[42:43] offset:13056
	ds_write_b64 v46, v[52:53] offset:17408
	ds_write_b64 v47, v[102:103] offset:17408
	ds_write_b64 v46, v[54:55] offset:21760
	ds_write_b64 v47, v[104:105] offset:21760
	ds_write_b64 v46, v[40:41] offset:26112
	ds_write_b64 v47, v[106:107] offset:26112
	ds_write_b64 v46, v[44:45] offset:30464
	ds_write_b64 v47, v[108:109] offset:30464
	s_waitcnt lgkmcnt(0)
	s_barrier
; template <int R, bool UNIT> __device__ __forceinline__ void dif_regs(f32x2* v, f32x2 wb) {
;     float k1 = 0.92387953251128674f, k2 = 0.70710678118654752f, k3 = 0.38268343236508977f; asm volatile("" : "+v"(k1), "+v"(k2), "+v"(k3));
; #pragma unroll
;     for (int t = 0; t < R; ++t) { constexpr int dummy = 0; (void)dummy; const int half = 1 << (R - 1 - t);
; #pragma unroll
;         for (int k = 0; k < (1 << R); ++k) if (!(k & half)) { const int kk = k & (half - 1), m = kk * (8 / half);
;             const f32x2 a = v[k], b = v[k + half]; v[k] = cadd(a, b); const f32x2 d = csub(a, b);
;             if (UNIT) { v[k + half] = (m == 0) ? d : (m == 4) ? (f32x2){d.y, -d.x} : cmul(d, CW16(m)); }
;             else { const f32x2 tw = (m == 0) ? wb : cmul(wb, CW16(m)); v[k + half] = cmul(d, tw); } }
;         if (!UNIT) wb = cmul(wb, wb); }
; }
; template <int R> __device__ __forceinline__ void dif_pass_rt(LAS f32x2* X, int sl, const f32x2 wb_in, int tid) {
;     float wbx = wb_in.x, wby = wb_in.y; asm volatile("" : "+v"(wbx), "+v"(wby)); const f32x2 wb = {wbx, wby};
;     const int r = tid & ((1 << sl) - 1), base = ((tid >> sl) << (sl + R)) + r;
;     LAS f32x2* Xb = X + PADI(base); f32x2 v[1 << R];
; #pragma unroll
;     for (int k = 0; k < (1 << R); ++k) v[k] = Xb[(k << sl) + ((k << sl) >> 4)];
;     dif_regs<R, false>(v, wb);
; #pragma unroll
;     for (int k = 0; k < (1 << R); ++k) Xb[(k << sl) + ((k << sl) >> 4)] = v[k];
; }
; template <int R> __device__ __forceinline__ void dit_pass_rt(LAS f32x2* X, int sl, const f32x2 wb_in, int tid) {
;     float wbx = wb_in.x, wby = wb_in.y; asm volatile("" : "+v"(wbx), "+v"(wby)); const f32x2 wbig = {wbx, wby};
;     const int r = tid & ((1 << sl) - 1), base = ((tid >> sl) << (sl + R)) + r;
;     LAS f32x2* Xb = X + PADI(base); f32x2 v[1 << R];
; #pragma unroll
;     for (int k = 0; k < (1 << R); ++k) v[k] = Xb[(k << sl) + ((k << sl) >> 4)];
;     dit_regs<R, false>(v, wbig);
; #pragma unroll
;     for (int k = 0; k < (1 << R); ++k) Xb[(k << sl) + ((k << sl) >> 4)] = v[k];
; }
; template <int NPT> __device__ __forceinline__ void fwd2_to_lds(LAS f32x2* Xe, LAS f32x2* Xo, const f32x2* tw, int tid, f32x2* ve, f32x2* vo) {
;     constexpr int R = NPT == 16 ? 4 : 3;
;     asm volatile("" : "+v"(tid)); __syncthreads();
;     { LAS f32x2* Pe = Xe + PADI(tid); LAS f32x2* Po = Xo + PADI(tid);
; #pragma unroll
.LBB0_642:
	s_cmp_eq_u32 s6, 1
	s_cselect_b32 s7, 6, 3
	s_cmp_lg_u32 s6, 0
	s_cselect_b32 s27, s7, 9
	s_sub_i32 s7, 11, s27
	v_lshlrev_b32_e32 v38, s7, v92
	v_and_b32_e32 v38, 0x7ff, v38
	v_lshlrev_b32_e32 v176, 3, v38
	v_lshl_add_u64 v[38:39], s[50:51], 0, v[176:177]
	global_load_dwordx2 v[38:39], v[38:39], off
	v_bfe_u32 v40, v92, 0, s27
	v_ashrrev_i32_e32 v41, s27, v92
	s_add_i32 s7, s27, 3
	v_lshl_add_u32 v40, v41, s7, v40
	s_lshl_b32 s7, 1, s27
	s_ashr_i32 s10, s7, 4
	s_lshl_b32 s7, s7, 3
	s_lshl_b32 s10, s10, 3
	s_add_i32 s7, s10, s7
	s_lshl_b32 s10, 2, s27
	s_ashr_i32 s11, s10, 4
	s_lshl_b32 s10, s10, 3
	s_lshl_b32 s11, s11, 3
	s_add_i32 s10, s11, s10
	s_lshl_b32 s11, 3, s27
	s_ashr_i32 s24, s11, 4
	s_lshl_b32 s11, s11, 3
	s_lshl_b32 s24, s24, 3
	s_add_i32 s11, s24, s11
	s_lshl_b32 s24, 4, s27
	s_ashr_i32 s25, s24, 4
	s_lshl_b32 s24, s24, 3
	s_lshl_b32 s25, s25, 3
	s_add_i32 s24, s25, s24
	s_lshl_b32 s25, 5, s27
	s_ashr_i32 s26, s25, 4
	s_lshl_b32 s25, s25, 3
	s_lshl_b32 s26, s26, 3
	s_add_i32 s25, s26, s25
	s_lshl_b32 s26, 6, s27
	s_ashr_i32 s30, s26, 4
	s_lshl_b32 s26, s26, 3
	s_lshl_b32 s30, s30, 3
	s_lshl_b32 s27, 7, s27
	v_ashrrev_i32_e32 v41, 4, v40
	s_add_i32 s26, s30, s26
	s_ashr_i32 s30, s27, 4
	v_lshlrev_b32_e32 v95, 3, v41
	v_lshlrev_b32_e32 v96, 3, v40
	s_lshl_b32 s27, s27, 3
	s_lshl_b32 s30, s30, 3
	v_add3_u32 v97, 0, v95, v96
	s_add_i32 s27, s30, s27
	v_add_u32_e32 v98, s7, v97
	v_add_u32_e32 v99, s10, v97
	v_add_u32_e32 v100, s11, v97
	v_add_u32_e32 v101, s24, v97
	v_add_u32_e32 v102, s25, v97
	v_add_u32_e32 v103, s26, v97
	v_add_u32_e32 v104, s27, v97
	v_mov_b32_e32 v105, 0x3f3504f3
	v_mov_b32_e32 v106, 0x3f6c835e
	v_mov_b32_e32 v107, 0x3ec3ef15
	s_add_i32 s6, s6, 1
	s_cmp_lg_u32 s6, 3
	s_waitcnt vmcnt(0) lgkmcnt(0)
	v_mov_b32_e32 v93, v39
	v_mov_b32_e32 v94, v38
	ds_read_b64 v[46:47], v97
	ds_read_b64 v[44:45], v98
	ds_read_b64 v[42:43], v99
	ds_read_b64 v[40:41], v100
	ds_read_b64 v[54:55], v101
	ds_read_b64 v[52:53], v102
	ds_read_b64 v[50:51], v103
	ds_read_b64 v[48:49], v104
	s_waitcnt lgkmcnt(3)
	v_add_f32_e32 v108, v47, v55
	v_sub_f32_e32 v47, v47, v55
	s_waitcnt lgkmcnt(2)
	v_add_f32_e32 v55, v45, v53
	v_sub_f32_e32 v45, v45, v53
	v_add_f32_e32 v107, v46, v54
	v_sub_f32_e32 v46, v46, v54
	v_xor_b32_e32 v106, 0x80000000, v105
	v_mul_f32_e32 v54, v46, v94
	v_mul_f32_e32 v46, v46, v93
	v_mul_f32_e32 v53, v94, v106
	v_fma_f32 v54, -v47, v93, v54
	v_fma_f32 v46, v47, v94, v46
	v_add_f32_e32 v47, v44, v52
	v_sub_f32_e32 v44, v44, v52
	v_mul_f32_e32 v52, v94, v105
	v_fma_f32 v105, v93, v105, v53
	v_fma_f32 v52, -v93, v106, v52
	v_mul_f32_e32 v109, v44, v52
	v_mul_f32_e32 v44, v44, v105
	v_fma_f32 v109, -v45, v105, v109
	v_fma_f32 v44, v45, v52, v44
	s_waitcnt lgkmcnt(1)
	v_add_f32_e32 v45, v42, v50
	v_add_f32_e32 v52, v43, v51
	v_sub_f32_e32 v42, v42, v50
	v_sub_f32_e32 v43, v43, v51
	v_mul_f32_e32 v50, v94, v177
	v_mul_f32_e32 v51, v94, v197
	v_fma_f32 v50, -v93, v197, v50
	v_fma_f32 v51, v93, v177, v51
	v_mul_f32_e32 v105, v42, v50
	v_mul_f32_e32 v42, v42, v51
	v_fma_f32 v105, -v43, v51, v105
	v_fma_f32 v42, v43, v50, v42
	s_waitcnt lgkmcnt(0)
	v_add_f32_e32 v43, v40, v48
	v_sub_f32_e32 v40, v40, v48
	v_add_f32_e32 v50, v41, v49
	v_sub_f32_e32 v41, v41, v49
	v_fma_f32 v48, -v93, v106, v53
	v_fma_f32 v49, v93, v106, v53
	v_add_f32_e32 v53, v108, v52
	v_sub_f32_e32 v52, v108, v52
	v_add_f32_e32 v108, v46, v42
	v_sub_f32_e32 v42, v46, v42
	v_mul_f32_e32 v51, v40, v48
	v_mul_f32_e32 v40, v40, v49
	v_fma_f32 v51, -v41, v49, v51
	v_fma_f32 v40, v41, v48, v40
	v_mul_f32_e32 v41, v94, v94
	v_mul_f32_e32 v48, v94, v93
	v_add_f32_e32 v49, v107, v45
	v_sub_f32_e32 v45, v107, v45
	v_add_f32_e32 v107, v54, v105
	v_add_f32_e32 v111, v44, v40
	v_fma_f32 v41, -v93, v93, v41
	v_fma_f32 v48, v93, v94, v48
	v_add_f32_e32 v94, v55, v50
	v_sub_f32_e32 v40, v44, v40
	v_add_f32_e32 v110, v109, v51
	v_mul_f32_e32 v93, v45, v41
	v_mul_f32_e32 v45, v45, v48
	v_sub_f32_e32 v44, v53, v94
	v_fma_f32 v93, -v52, v48, v93
	v_fma_f32 v52, v52, v41, v45
	v_add_f32_e32 v45, v47, v43
	v_sub_f32_e32 v43, v47, v43
	v_sub_f32_e32 v47, v55, v50
	v_mul_f32_e32 v50, v41, v177
	v_mul_f32_e32 v55, v41, v197
	v_fma_f32 v50, -v48, v197, v50
	v_fma_f32 v55, v48, v177, v55
	v_mul_f32_e32 v106, v43, v50
	v_mul_f32_e32 v43, v43, v55
	v_fma_f32 v106, -v47, v55, v106
	v_fma_f32 v47, v47, v50, v43
	v_sub_f32_e32 v43, v54, v105
	v_mul_f32_e32 v46, v43, v41
	v_mul_f32_e32 v43, v43, v48
	v_fma_f32 v54, -v42, v48, v46
	v_fma_f32 v105, v42, v41, v43
	v_sub_f32_e32 v42, v109, v51
	v_sub_f32_e32 v51, v107, v110
	v_mul_f32_e32 v43, v42, v50
	v_mul_f32_e32 v42, v42, v55
	v_fma_f32 v109, -v40, v55, v43
	v_fma_f32 v55, v40, v50, v42
	v_mul_f32_e32 v40, v41, v41
	v_sub_f32_e32 v43, v49, v45
	v_fma_f32 v112, -v48, v48, v40
	v_mul_f32_e32 v40, v41, v48
	v_fma_f32 v113, v48, v41, v40
	v_mul_f32_e32 v42, v43, v112
	v_add_f32_e32 v40, v49, v45
	v_add_f32_e32 v45, v52, v47
	v_sub_f32_e32 v48, v93, v106
	v_sub_f32_e32 v47, v52, v47
	v_mul_f32_e32 v43, v43, v113
	v_fma_f32 v42, -v44, v113, v42
	v_sub_f32_e32 v52, v108, v111
	v_mul_f32_e32 v50, v51, v112
	v_mul_f32_e32 v51, v51, v113
	v_add_f32_e32 v41, v53, v94
	v_fma_f32 v43, v44, v112, v43
	v_add_f32_e32 v44, v93, v106
	v_sub_f32_e32 v93, v54, v109
	v_fma_f32 v50, -v52, v113, v50
	v_fma_f32 v51, v52, v112, v51
	v_add_f32_e32 v52, v54, v109
	v_add_f32_e32 v53, v105, v55
	v_sub_f32_e32 v55, v105, v55
	v_mul_f32_e32 v54, v93, v112
	v_mul_f32_e32 v93, v93, v113
	v_mul_f32_e32 v46, v48, v112
	v_mul_f32_e32 v48, v48, v113
	v_add_f32_e32 v49, v108, v111
	v_fma_f32 v54, -v55, v113, v54
	v_fma_f32 v55, v55, v112, v93
	v_add3_u32 v93, s55, v95, v96
	v_fma_f32 v46, -v47, v113, v46
	v_fma_f32 v47, v47, v112, v48
	v_add_f32_e32 v48, v107, v110
	ds_write_b64 v97, v[40:41]
	ds_write_b64 v98, v[42:43]
	ds_write_b64 v99, v[44:45]
	ds_write_b64 v100, v[46:47]
	ds_write_b64 v101, v[48:49]
	ds_write_b64 v102, v[50:51]
	ds_write_b64 v103, v[52:53]
	ds_write_b64 v104, v[54:55]
	v_add_u32_e32 v94, s7, v93
	v_add_u32_e32 v95, s10, v93
	v_add_u32_e32 v96, s11, v93
	v_add_u32_e32 v97, s24, v93
	v_add_u32_e32 v98, s25, v93
	v_add_u32_e32 v99, s26, v93
	v_add_u32_e32 v100, s27, v93
	v_mov_b32_e32 v101, 0x3f3504f3
	v_mov_b32_e32 v102, 0x3f6c835e
	v_mov_b32_e32 v103, 0x3ec3ef15
	ds_read_b64 v[50:51], v93
	ds_read_b64 v[48:49], v94
	ds_read_b64 v[44:45], v95
	ds_read_b64 v[40:41], v96
	ds_read_b64 v[54:55], v97
	ds_read_b64 v[52:53], v98
	ds_read_b64 v[46:47], v99
	ds_read_b64 v[42:43], v100
	s_waitcnt lgkmcnt(3)
; template <int R, bool UNIT> __device__ __forceinline__ void dif_regs(f32x2* v, f32x2 wb) {
;     float k1 = 0.92387953251128674f, k2 = 0.70710678118654752f, k3 = 0.38268343236508977f; asm volatile("" : "+v"(k1), "+v"(k2), "+v"(k3));
; #pragma unroll
;     for (int t = 0; t < R; ++t) { constexpr int dummy = 0; (void)dummy; const int half = 1 << (R - 1 - t);
; #pragma unroll
;         for (int k = 0; k < (1 << R); ++k) if (!(k & half)) { const int kk = k & (half - 1), m = kk * (8 / half);
;             const f32x2 a = v[k], b = v[k + half]; v[k] = cadd(a, b); const f32x2 d = csub(a, b);
;             if (UNIT) { v[k + half] = (m == 0) ? d : (m == 4) ? (f32x2){d.y, -d.x} : cmul(d, CW16(m)); }
;             else { const f32x2 tw = (m == 0) ? wb : cmul(wb, CW16(m)); v[k + half] = cmul(d, tw); } }
;         if (!UNIT) wb = cmul(wb, wb); }
; }
; template <int NPT> __device__ __forceinline__ void fwd2_to_lds(LAS f32x2* Xe, LAS f32x2* Xo, const f32x2* tw, int tid, f32x2* ve, f32x2* vo) {
;     ...
;     for (int ps = 0; ps < 3; ++ps) { int sl = pass_sl<NPT>(ps); asm volatile("" : "+s"(sl));
;         const f32x2 wb = tw[(tid & ((1 << sl) - 1)) << (14 - R - sl)];
;         dif_pass_rt<R>(Xe, sl, wb, tid); dif_pass_rt<R>(Xo, sl, wb, tid); __syncthreads(); }
; }
; template <int NPT> __device__ __forceinline__ void mid_spectrum(const LAS f32x2* X, int tid, f32x2* K, float sc) {
;     if (NPT == 16) {
; #pragma unroll
;         for (int u = 0; u < 8; ++u) { const LAS f32x2* Xb = X + PADI(2 * tid) + 1088 * u; const f32x2 a = Xb[0], b = Xb[1]; K[2 * u] = cscale(cadd(a, b), sc); K[2 * u + 1] = cscale(csub(a, b), sc); } }
;     else { f32x2 w[8]; const LAS f32x2* Xb = X + PADI(8 * tid);
; #pragma unroll
;         for (int k = 0; k < 8; ++k) w[k] = Xb[k];
;         dif_regs<3, true>(w, (f32x2){1.f, 0.f});
; #pragma unroll
;         for (int k = 0; k < 8; ++k) K[k] = cscale(w[k], sc); }
; }
; template <int NPT> __device__ __forceinline__ void mid_mul(LAS f32x2* X, int tid, const f32x2* K) {
;     if (NPT == 16) {
; #pragma unroll
;         for (int u = 0; u < 8; ++u) { LAS f32x2* Xb = X + PADI(2 * tid) + 1088 * u; const f32x2 a = Xb[0], b = Xb[1];
;             const f32x2 s = cmul(cadd(a, b), K[2 * u]), d = cmul(csub(a, b), K[2 * u + 1]); Xb[0] = cadd(s, d); Xb[1] = csub(s, d); } }
;     else { f32x2 w[8]; LAS f32x2* Xb = X + PADI(8 * tid);
; #pragma unroll
	v_add_f32_e32 v104, v51, v55
	v_sub_f32_e32 v51, v51, v55
	s_waitcnt lgkmcnt(2)
	v_add_f32_e32 v55, v49, v53
	v_sub_f32_e32 v49, v49, v53
	v_add_f32_e32 v103, v50, v54
	v_sub_f32_e32 v50, v50, v54
	v_xor_b32_e32 v102, 0x80000000, v101
	v_mul_f32_e32 v54, v50, v38
	v_mul_f32_e32 v50, v50, v39
	v_mul_f32_e32 v53, v38, v102
	v_fma_f32 v54, -v51, v39, v54
	v_fma_f32 v50, v51, v38, v50
	v_add_f32_e32 v51, v48, v52
	v_sub_f32_e32 v48, v48, v52
	v_mul_f32_e32 v52, v38, v101
	v_fma_f32 v101, v39, v101, v53
	v_fma_f32 v52, -v39, v102, v52
	v_mul_f32_e32 v105, v48, v52
	v_mul_f32_e32 v48, v48, v101
	v_fma_f32 v105, -v49, v101, v105
	v_fma_f32 v48, v49, v52, v48
	s_waitcnt lgkmcnt(1)
	v_add_f32_e32 v49, v44, v46
	v_add_f32_e32 v52, v45, v47
	v_sub_f32_e32 v44, v44, v46
	v_sub_f32_e32 v45, v45, v47
	v_mul_f32_e32 v46, v38, v177
	v_mul_f32_e32 v47, v38, v197
	v_fma_f32 v46, -v39, v197, v46
	v_fma_f32 v47, v39, v177, v47
	v_mul_f32_e32 v101, v44, v46
	v_mul_f32_e32 v44, v44, v47
	v_fma_f32 v101, -v45, v47, v101
	v_fma_f32 v44, v45, v46, v44
	s_waitcnt lgkmcnt(0)
	v_add_f32_e32 v45, v40, v42
	v_sub_f32_e32 v40, v40, v42
	v_add_f32_e32 v46, v41, v43
	v_sub_f32_e32 v41, v41, v43
	v_fma_f32 v42, -v39, v102, v53
	v_fma_f32 v43, v39, v102, v53
	v_add_f32_e32 v53, v51, v45
	v_mul_f32_e32 v47, v40, v42
	v_mul_f32_e32 v40, v40, v43
	v_add_f32_e32 v102, v55, v46
	v_fma_f32 v47, -v41, v43, v47
	v_fma_f32 v40, v41, v42, v40
	v_mul_f32_e32 v41, v38, v38
	v_mul_f32_e32 v42, v38, v39
	v_add_f32_e32 v43, v104, v52
	v_fma_f32 v41, -v39, v39, v41
	v_fma_f32 v38, v39, v38, v42
	v_sub_f32_e32 v39, v103, v49
	v_add_f32_e32 v42, v103, v49
	v_sub_f32_e32 v49, v104, v52
	v_add_f32_e32 v104, v50, v44
	v_sub_f32_e32 v44, v50, v44
	v_add_f32_e32 v103, v54, v101
	v_mul_f32_e32 v52, v39, v41
	v_mul_f32_e32 v39, v39, v38
	v_add_f32_e32 v106, v48, v40
	v_sub_f32_e32 v40, v48, v40
	v_fma_f32 v52, -v49, v38, v52
	v_fma_f32 v49, v49, v41, v39
	v_sub_f32_e32 v39, v51, v45
	v_sub_f32_e32 v45, v55, v46
	v_mul_f32_e32 v46, v41, v177
	v_mul_f32_e32 v51, v41, v197
	v_fma_f32 v46, -v38, v197, v46
	v_fma_f32 v51, v38, v177, v51
	v_mul_f32_e32 v55, v39, v46
	v_mul_f32_e32 v39, v39, v51
	v_fma_f32 v55, -v45, v51, v55
	v_fma_f32 v45, v45, v46, v39
	v_sub_f32_e32 v39, v54, v101
	v_mul_f32_e32 v50, v39, v41
	v_mul_f32_e32 v39, v39, v38
	v_fma_f32 v101, v44, v41, v39
	v_sub_f32_e32 v39, v105, v47
	v_fma_f32 v54, -v44, v38, v50
	v_add_f32_e32 v50, v105, v47
	v_add_f32_e32 v47, v104, v106
	v_mul_f32_e32 v44, v39, v46
	v_mul_f32_e32 v39, v39, v51
	v_fma_f32 v107, v40, v46, v39
	v_mul_f32_e32 v39, v41, v41
	v_sub_f32_e32 v46, v52, v55
	v_fma_f32 v105, -v40, v51, v44
	v_fma_f32 v108, -v38, v38, v39
	v_mul_f32_e32 v39, v41, v38
	v_add_f32_e32 v51, v101, v107
	v_fma_f32 v109, v38, v41, v39
	v_sub_f32_e32 v41, v42, v53
	v_add_f32_e32 v38, v42, v53
	v_add_f32_e32 v39, v43, v102
	v_sub_f32_e32 v42, v43, v102
	v_add_f32_e32 v43, v49, v45
	v_sub_f32_e32 v45, v49, v45
	v_mul_f32_e32 v40, v41, v108
	v_mul_f32_e32 v41, v41, v109
	v_mul_f32_e32 v44, v46, v108
	v_mul_f32_e32 v46, v46, v109
	v_sub_f32_e32 v49, v103, v50
	v_sub_f32_e32 v53, v54, v105
	v_fma_f32 v40, -v42, v109, v40
	v_fma_f32 v41, v42, v108, v41
	v_add_f32_e32 v42, v52, v55
	v_fma_f32 v44, -v45, v109, v44
	v_fma_f32 v45, v45, v108, v46
	v_add_f32_e32 v46, v103, v50
	v_sub_f32_e32 v50, v104, v106
	v_mul_f32_e32 v48, v49, v108
	v_mul_f32_e32 v49, v49, v109
	v_mul_f32_e32 v52, v53, v108
	v_mul_f32_e32 v53, v53, v109
	v_fma_f32 v48, -v50, v109, v48
	v_fma_f32 v49, v50, v108, v49
	v_add_f32_e32 v50, v54, v105
	v_sub_f32_e32 v54, v101, v107
	v_fma_f32 v52, -v54, v109, v52
	v_fma_f32 v53, v54, v108, v53
	ds_write_b64 v93, v[38:39]
	ds_write_b64 v94, v[40:41]
	ds_write_b64 v95, v[42:43]
	ds_write_b64 v96, v[44:45]
	ds_write_b64 v97, v[46:47]
	ds_write_b64 v98, v[48:49]
	ds_write_b64 v99, v[50:51]
	ds_write_b64 v100, v[52:53]
	s_waitcnt lgkmcnt(0)
	s_barrier
	s_cbranch_scc1 .LBB0_642
	ds_read2_b64 v[38:41], v56 offset1:1
	ds_read2_b64 v[42:45], v56 offset0:2 offset1:3
	ds_read2_b64 v[46:49], v56 offset0:4 offset1:5
	ds_read2_b64 v[50:53], v56 offset0:6 offset1:7
	v_mov_b32_e32 v54, 0x3f3504f3
	v_mov_b32_e32 v55, 0x3f6c835e
	v_mov_b32_e32 v92, 0x3ec3ef15
	s_waitcnt lgkmcnt(1)
	v_add_f32_e32 v93, v39, v47
	v_sub_f32_e32 v39, v39, v47
	v_add_f32_e32 v47, v41, v49
	v_sub_f32_e32 v41, v41, v49
	s_waitcnt lgkmcnt(0)
; template <int R, bool UNIT> __device__ __forceinline__ void dif_regs(f32x2* v, f32x2 wb) {
;     float k1 = 0.92387953251128674f, k2 = 0.70710678118654752f, k3 = 0.38268343236508977f; asm volatile("" : "+v"(k1), "+v"(k2), "+v"(k3));
; #pragma unroll
;     for (int t = 0; t < R; ++t) { constexpr int dummy = 0; (void)dummy; const int half = 1 << (R - 1 - t);
; #pragma unroll
;         for (int k = 0; k < (1 << R); ++k) if (!(k & half)) { const int kk = k & (half - 1), m = kk * (8 / half);
;             const f32x2 a = v[k], b = v[k + half]; v[k] = cadd(a, b); const f32x2 d = csub(a, b);
;             if (UNIT) { v[k + half] = (m == 0) ? d : (m == 4) ? (f32x2){d.y, -d.x} : cmul(d, CW16(m)); }
;             else { const f32x2 tw = (m == 0) ? wb : cmul(wb, CW16(m)); v[k + half] = cmul(d, tw); } }
;         if (!UNIT) wb = cmul(wb, wb); }
; }
; template <int R, bool UNIT> __device__ __forceinline__ void dit_regs(f32x2* v, f32x2 wbig) {
;     float k1 = 0.92387953251128674f, k2 = 0.70710678118654752f, k3 = 0.38268343236508977f; asm volatile("" : "+v"(k1), "+v"(k2), "+v"(k3));
;     f32x2 wbs[R]; wbs[R - 1] = wbig;
; #pragma unroll
;     for (int t = R - 2; t >= 0; --t) wbs[t] = cmul(wbs[t + 1], wbs[t + 1]);
; #pragma unroll
;     for (int t = 0; t < R; ++t) { const int half = 1 << t;
; #pragma unroll
;         for (int k = 0; k < (1 << R); ++k) if (!(k & half)) { const int kk = k & (half - 1), m = kk * (8 / half);
;             const f32x2 a = v[k]; f32x2 b = v[k + half];
;             if (UNIT) { if (m == 4) b = (f32x2){-b.y, b.x}; else if (m != 0) b = cmulc(b, CW16(m)); }
;             else { const f32x2 tw = (m == 0) ? wbs[t] : cmul(wbs[t], CW16(m)); b = cmulc(b, tw); }
;             v[k] = cadd(a, b); v[k + half] = csub(a, b); } }
; }
; template <int NPT> __device__ __forceinline__ void mid_mul(LAS f32x2* X, int tid, const f32x2* K) {
;     if (NPT == 16) {
; #pragma unroll
;         for (int u = 0; u < 8; ++u) { LAS f32x2* Xb = X + PADI(2 * tid) + 1088 * u; const f32x2 a = Xb[0], b = Xb[1];
;             const f32x2 s = cmul(cadd(a, b), K[2 * u]), d = cmul(csub(a, b), K[2 * u + 1]); Xb[0] = cadd(s, d); Xb[1] = csub(s, d); } }
;     else { f32x2 w[8]; LAS f32x2* Xb = X + PADI(8 * tid);
; #pragma unroll
;         for (int k = 0; k < 8; ++k) w[k] = Xb[k];
;         dif_regs<3, true>(w, (f32x2){1.f, 0.f});
; #pragma unroll
	v_add_f32_e32 v49, v43, v51
	v_add_f32_e32 v92, v38, v46
	v_sub_f32_e32 v38, v38, v46
	v_add_f32_e32 v46, v40, v48
	v_sub_f32_e32 v40, v40, v48
	v_xor_b32_e32 v55, 0x80000000, v54
	v_mul_f32_e32 v48, v40, v54
	v_mul_f32_e32 v40, v40, v55
	v_sub_f32_e32 v43, v43, v51
	v_add_f32_e32 v51, v45, v53
	v_sub_f32_e32 v45, v45, v53
	v_add_f32_e32 v53, v93, v49
	v_fma_f32 v48, -v41, v55, v48
	v_fma_f32 v40, v41, v54, v40
	v_add_f32_e32 v41, v42, v50
	v_sub_f32_e32 v42, v42, v50
	v_add_f32_e32 v50, v44, v52
	v_sub_f32_e32 v44, v44, v52
	v_sub_f32_e32 v49, v93, v49
	s_mov_b32 s6, -1
	v_xor_b32_e32 v42, 0x80000000, v42
	v_mul_f32_e32 v44, v44, v55
	v_add_f32_e32 v54, v46, v50
	v_sub_f32_e32 v46, v46, v50
	v_add_f32_e32 v50, v38, v43
	v_sub_f32_e32 v38, v38, v43
	v_fma_f32 v52, -v45, v55, v44
	v_fma_f32 v44, v45, v55, v44
	v_add_f32_e32 v45, v92, v41
	v_add_f32_e32 v55, v47, v51
	v_sub_f32_e32 v47, v47, v51
	v_add_f32_e32 v51, v39, v42
	v_sub_f32_e32 v39, v39, v42
	v_add_f32_e32 v42, v48, v52
	v_sub_f32_e32 v48, v48, v52
	v_sub_f32_e32 v41, v92, v41
	v_xor_b32_e32 v46, 0x80000000, v46
	v_add_f32_e32 v43, v40, v44
	v_sub_f32_e32 v40, v40, v44
	v_xor_b32_e32 v44, 0x80000000, v48
	v_add_f32_e32 v48, v45, v54
	v_sub_f32_e32 v45, v45, v54
	v_add_f32_e32 v52, v53, v55
	v_sub_f32_e32 v53, v53, v55
	v_add_f32_e32 v54, v41, v47
	v_add_f32_e32 v55, v49, v46
	v_sub_f32_e32 v41, v41, v47
	v_sub_f32_e32 v46, v49, v46
	v_add_f32_e32 v47, v50, v42
	v_add_f32_e32 v49, v51, v43
	v_sub_f32_e32 v42, v50, v42
	v_sub_f32_e32 v43, v51, v43
	v_add_f32_e32 v50, v38, v40
	v_add_f32_e32 v51, v39, v44
	v_sub_f32_e32 v38, v38, v40
	v_sub_f32_e32 v39, v39, v44
	v_mul_f32_e32 v40, v48, v57
	v_mul_f32_e32 v44, v48, v58
	v_mul_f32_e32 v48, v45, v59
	v_mul_f32_e32 v45, v45, v60
	v_mov_b32_e32 v92, 0x3ec3ef15
	v_fma_f32 v40, -v52, v58, v40
	v_fma_f32 v44, v52, v57, v44
	v_fma_f32 v48, -v53, v60, v48
	v_fma_f32 v45, v53, v59, v45
	v_mul_f32_e32 v52, v54, v61
	v_mul_f32_e32 v53, v54, v62
	v_mul_f32_e32 v54, v41, v63
	v_mul_f32_e32 v41, v41, v64
	v_fma_f32 v54, -v46, v64, v54
	v_fma_f32 v41, v46, v63, v41
	v_mul_f32_e32 v46, v47, v65
	v_mul_f32_e32 v47, v47, v66
	v_fma_f32 v52, -v55, v62, v52
	v_fma_f32 v53, v55, v61, v53
	v_mov_b32_e32 v55, 0x3f3504f3
	v_fma_f32 v46, -v49, v66, v46
	v_fma_f32 v47, v49, v65, v47
	v_mul_f32_e32 v49, v42, v67
	v_mul_f32_e32 v42, v42, v68
	v_add_f32_e32 v93, v44, v45
	v_sub_f32_e32 v44, v44, v45
	v_add_f32_e32 v45, v52, v54
	v_sub_f32_e32 v52, v52, v54
	v_fma_f32 v49, -v43, v68, v49
	v_fma_f32 v42, v43, v67, v42
	v_mul_f32_e32 v43, v50, v69
	v_mul_f32_e32 v50, v50, v70
	v_fma_f32 v43, -v51, v70, v43
	v_fma_f32 v50, v51, v69, v50
	v_mul_f32_e32 v51, v38, v71
	v_mul_f32_e32 v38, v38, v72
	v_add_f32_e32 v54, v47, v42
	v_sub_f32_e32 v42, v47, v42
	v_sub_f32_e32 v96, v44, v52
	v_fma_f32 v51, -v39, v72, v51
	v_fma_f32 v38, v39, v71, v38
	v_mov_b32_e32 v39, 0x3f6c835e
	v_add_f32_e32 v47, v43, v51
	v_sub_f32_e32 v43, v43, v51
	v_add_f32_e32 v39, v40, v48
	v_sub_f32_e32 v40, v40, v48
	v_add_f32_e32 v48, v53, v41
	v_sub_f32_e32 v41, v53, v41
	v_add_f32_e32 v53, v46, v49
	v_sub_f32_e32 v46, v46, v49
	v_add_f32_e32 v49, v50, v38
	v_sub_f32_e32 v38, v50, v38
	v_add_f32_e32 v50, v39, v45
	v_add_f32_e32 v51, v93, v48
	v_sub_f32_e32 v94, v39, v45
	v_sub_f32_e32 v93, v93, v48
	v_xor_b32_e32 v39, 0x80000000, v41
	v_add_f32_e32 v45, v40, v39
	v_add_f32_e32 v48, v44, v52
	v_sub_f32_e32 v95, v40, v39
	v_add_f32_e32 v40, v53, v47
	v_add_f32_e32 v41, v54, v49
	v_sub_f32_e32 v52, v53, v47
	v_sub_f32_e32 v47, v54, v49
	v_xor_b32_e32 v38, 0x80000000, v38
	v_add_f32_e32 v44, v46, v38
	v_add_f32_e32 v49, v42, v43
	v_sub_f32_e32 v54, v42, v43
	v_xor_b32_e32 v92, 0x80000000, v55
	v_mul_f32_e32 v42, v44, v55
	v_sub_f32_e32 v53, v46, v38
	v_add_f32_e32 v38, v50, v40
	v_sub_f32_e32 v40, v50, v40
	v_add_f32_e32 v39, v51, v41
	v_sub_f32_e32 v41, v51, v41
	v_fma_f32 v46, v49, v92, v42
	v_mul_f32_e32 v42, v49, v55
	v_mul_f32_e32 v50, v53, v92
	v_mov_b32_e32 v55, 0x3f6c835e
	v_fma_f32 v49, -v44, v92, v42
	v_add_f32_e32 v42, v45, v46
	v_sub_f32_e32 v44, v45, v46
	v_add_f32_e32 v43, v48, v49
	v_sub_f32_e32 v45, v48, v49
	v_xor_b32_e32 v48, 0x80000000, v47
	v_add_f32_e32 v47, v93, v52
	v_sub_f32_e32 v49, v93, v52
	v_fma_f32 v52, v54, v92, v50
	v_mul_f32_e32 v50, v54, v92
	v_add_f32_e32 v46, v94, v48
	v_sub_f32_e32 v48, v94, v48
	v_mov_b32_e32 v54, 0x3f3504f3
	v_fma_f32 v53, -v53, v92, v50
	v_add_f32_e32 v50, v95, v52
	v_sub_f32_e32 v52, v95, v52
	v_mov_b32_e32 v92, 0x3ec3ef15
	v_add_f32_e32 v51, v96, v53
	v_sub_f32_e32 v53, v96, v53
	ds_write2_b64 v56, v[38:39], v[42:43] offset1:1
	ds_write2_b64 v56, v[46:47], v[50:51] offset0:2 offset1:3
	ds_write2_b64 v56, v[40:41], v[44:45] offset0:4 offset1:5
	ds_write2_b64 v56, v[48:49], v[52:53] offset0:6 offset1:7
	ds_read2_b64 v[38:41], v73 offset1:1
	ds_read2_b64 v[42:45], v73 offset0:2 offset1:3
	ds_read2_b64 v[46:49], v73 offset0:4 offset1:5
	ds_read2_b64 v[50:53], v73 offset0:6 offset1:7
	s_waitcnt lgkmcnt(1)
	v_add_f32_e32 v93, v39, v47
	v_add_f32_e32 v92, v38, v46
	v_sub_f32_e32 v38, v38, v46
	v_add_f32_e32 v46, v40, v48
	v_sub_f32_e32 v40, v40, v48
	v_xor_b32_e32 v55, 0x80000000, v54
	v_sub_f32_e32 v39, v39, v47
	v_add_f32_e32 v47, v41, v49
	v_sub_f32_e32 v41, v41, v49
	v_mul_f32_e32 v48, v40, v54
	v_mul_f32_e32 v40, v40, v55
	s_waitcnt lgkmcnt(0)
; template <int R, bool UNIT> __device__ __forceinline__ void dif_regs(f32x2* v, f32x2 wb) {
;     float k1 = 0.92387953251128674f, k2 = 0.70710678118654752f, k3 = 0.38268343236508977f; asm volatile("" : "+v"(k1), "+v"(k2), "+v"(k3));
; #pragma unroll
;     for (int t = 0; t < R; ++t) { constexpr int dummy = 0; (void)dummy; const int half = 1 << (R - 1 - t);
; #pragma unroll
;         for (int k = 0; k < (1 << R); ++k) if (!(k & half)) { const int kk = k & (half - 1), m = kk * (8 / half);
;             const f32x2 a = v[k], b = v[k + half]; v[k] = cadd(a, b); const f32x2 d = csub(a, b);
;             if (UNIT) { v[k + half] = (m == 0) ? d : (m == 4) ? (f32x2){d.y, -d.x} : cmul(d, CW16(m)); }
;             else { const f32x2 tw = (m == 0) ? wb : cmul(wb, CW16(m)); v[k + half] = cmul(d, tw); } }
;         if (!UNIT) wb = cmul(wb, wb); }
; }
; template <int R, bool UNIT> __device__ __forceinline__ void dit_regs(f32x2* v, f32x2 wbig) {
;     float k1 = 0.92387953251128674f, k2 = 0.70710678118654752f, k3 = 0.38268343236508977f; asm volatile("" : "+v"(k1), "+v"(k2), "+v"(k3));
;     f32x2 wbs[R]; wbs[R - 1] = wbig;
; #pragma unroll
;     for (int t = R - 2; t >= 0; --t) wbs[t] = cmul(wbs[t + 1], wbs[t + 1]);
; #pragma unroll
;     for (int t = 0; t < R; ++t) { const int half = 1 << t;
; #pragma unroll
;         for (int k = 0; k < (1 << R); ++k) if (!(k & half)) { const int kk = k & (half - 1), m = kk * (8 / half);
;             const f32x2 a = v[k]; f32x2 b = v[k + half];
;             if (UNIT) { if (m == 4) b = (f32x2){-b.y, b.x}; else if (m != 0) b = cmulc(b, CW16(m)); }
;             else { const f32x2 tw = (m == 0) ? wbs[t] : cmul(wbs[t], CW16(m)); b = cmulc(b, tw); }
;             v[k] = cadd(a, b); v[k + half] = csub(a, b); } }
; }
; template <int NPT> __device__ __forceinline__ void mid_mul(LAS f32x2* X, int tid, const f32x2* K) {
;     if (NPT == 16) {
; #pragma unroll
;         for (int u = 0; u < 8; ++u) { LAS f32x2* Xb = X + PADI(2 * tid) + 1088 * u; const f32x2 a = Xb[0], b = Xb[1];
;             const f32x2 s = cmul(cadd(a, b), K[2 * u]), d = cmul(csub(a, b), K[2 * u + 1]); Xb[0] = cadd(s, d); Xb[1] = csub(s, d); } }
;     else { f32x2 w[8]; LAS f32x2* Xb = X + PADI(8 * tid);
; #pragma unroll
;         for (int k = 0; k < 8; ++k) w[k] = Xb[k];
;         dif_regs<3, true>(w, (f32x2){1.f, 0.f});
; #pragma unroll
	v_add_f32_e32 v49, v43, v51
	v_sub_f32_e32 v43, v43, v51
	v_add_f32_e32 v51, v45, v53
	v_sub_f32_e32 v45, v45, v53
	v_fma_f32 v48, -v41, v55, v48
	v_fma_f32 v40, v41, v54, v40
	v_add_f32_e32 v41, v42, v50
	v_sub_f32_e32 v42, v42, v50
	v_add_f32_e32 v50, v44, v52
	v_sub_f32_e32 v44, v44, v52
	v_add_f32_e32 v53, v93, v49
	v_sub_f32_e32 v49, v93, v49
	v_xor_b32_e32 v42, 0x80000000, v42
	v_mul_f32_e32 v44, v44, v55
	v_add_f32_e32 v54, v46, v50
	v_sub_f32_e32 v46, v46, v50
	v_add_f32_e32 v50, v38, v43
	v_sub_f32_e32 v38, v38, v43
	v_fma_f32 v52, -v45, v55, v44
	v_fma_f32 v44, v45, v55, v44
	v_add_f32_e32 v45, v92, v41
	v_add_f32_e32 v55, v47, v51
	v_sub_f32_e32 v47, v47, v51
	v_add_f32_e32 v51, v39, v42
	v_sub_f32_e32 v39, v39, v42
	v_add_f32_e32 v42, v48, v52
	v_sub_f32_e32 v48, v48, v52
	v_sub_f32_e32 v41, v92, v41
	v_xor_b32_e32 v46, 0x80000000, v46
	v_add_f32_e32 v43, v40, v44
	v_sub_f32_e32 v40, v40, v44
	v_xor_b32_e32 v44, 0x80000000, v48
	v_add_f32_e32 v48, v45, v54
	v_sub_f32_e32 v45, v45, v54
	v_add_f32_e32 v52, v53, v55
	v_sub_f32_e32 v53, v53, v55
	v_add_f32_e32 v54, v41, v47
	v_add_f32_e32 v55, v49, v46
	v_sub_f32_e32 v41, v41, v47
	v_sub_f32_e32 v46, v49, v46
	v_add_f32_e32 v47, v50, v42
	v_add_f32_e32 v49, v51, v43
	v_sub_f32_e32 v42, v50, v42
	v_sub_f32_e32 v43, v51, v43
	v_add_f32_e32 v50, v38, v40
	v_add_f32_e32 v51, v39, v44
	v_sub_f32_e32 v38, v38, v40
	v_sub_f32_e32 v39, v39, v44
	v_mul_f32_e32 v40, v48, v74
	v_mul_f32_e32 v44, v48, v75
	v_mul_f32_e32 v48, v45, v76
	v_mul_f32_e32 v45, v45, v77
	v_mov_b32_e32 v92, 0x3ec3ef15
	v_fma_f32 v40, -v52, v75, v40
	v_fma_f32 v44, v52, v74, v44
	v_fma_f32 v48, -v53, v77, v48
	v_fma_f32 v45, v53, v76, v45
	v_mul_f32_e32 v52, v54, v78
	v_mul_f32_e32 v53, v54, v79
	v_mul_f32_e32 v54, v41, v80
	v_mul_f32_e32 v41, v41, v81
	v_fma_f32 v54, -v46, v81, v54
	v_fma_f32 v41, v46, v80, v41
	v_mul_f32_e32 v46, v47, v82
	v_mul_f32_e32 v47, v47, v83
	v_fma_f32 v52, -v55, v79, v52
	v_fma_f32 v53, v55, v78, v53
	v_mov_b32_e32 v55, 0x3f3504f3
	v_fma_f32 v46, -v49, v83, v46
	v_fma_f32 v47, v49, v82, v47
	v_mul_f32_e32 v49, v42, v84
	v_mul_f32_e32 v42, v42, v85
	v_add_f32_e32 v93, v44, v45
	v_sub_f32_e32 v44, v44, v45
	v_add_f32_e32 v45, v52, v54
	v_sub_f32_e32 v52, v52, v54
	v_fma_f32 v49, -v43, v85, v49
	v_fma_f32 v42, v43, v84, v42
	v_mul_f32_e32 v43, v50, v86
	v_mul_f32_e32 v50, v50, v87
	v_fma_f32 v43, -v51, v87, v43
	v_fma_f32 v50, v51, v86, v50
	v_mul_f32_e32 v51, v38, v88
	v_mul_f32_e32 v38, v38, v89
	v_add_f32_e32 v54, v47, v42
	v_sub_f32_e32 v42, v47, v42
	v_sub_f32_e32 v96, v44, v52
	v_fma_f32 v51, -v39, v89, v51
	v_fma_f32 v38, v39, v88, v38
	v_mov_b32_e32 v39, 0x3f6c835e
	v_add_f32_e32 v47, v43, v51
	v_sub_f32_e32 v43, v43, v51
	v_add_f32_e32 v39, v40, v48
	v_sub_f32_e32 v40, v40, v48
	v_add_f32_e32 v48, v53, v41
	v_sub_f32_e32 v41, v53, v41
	v_add_f32_e32 v53, v46, v49
	v_sub_f32_e32 v46, v46, v49
	v_add_f32_e32 v49, v50, v38
	v_sub_f32_e32 v38, v50, v38
	v_add_f32_e32 v50, v39, v45
	v_add_f32_e32 v51, v93, v48
	v_sub_f32_e32 v94, v39, v45
	v_sub_f32_e32 v93, v93, v48
	v_xor_b32_e32 v39, 0x80000000, v41
	v_add_f32_e32 v45, v40, v39
	v_add_f32_e32 v48, v44, v52
	v_sub_f32_e32 v95, v40, v39
	v_add_f32_e32 v40, v53, v47
	v_add_f32_e32 v41, v54, v49
	v_sub_f32_e32 v52, v53, v47
	v_sub_f32_e32 v47, v54, v49
	v_xor_b32_e32 v38, 0x80000000, v38
	v_add_f32_e32 v44, v46, v38
	v_add_f32_e32 v49, v42, v43
	v_sub_f32_e32 v54, v42, v43
	v_xor_b32_e32 v92, 0x80000000, v55
	v_mul_f32_e32 v42, v44, v55
	v_sub_f32_e32 v53, v46, v38
	v_add_f32_e32 v38, v50, v40
	v_sub_f32_e32 v40, v50, v40
	v_add_f32_e32 v39, v51, v41
	v_sub_f32_e32 v41, v51, v41
	v_fma_f32 v46, v49, v92, v42
	v_mul_f32_e32 v42, v49, v55
	v_mul_f32_e32 v50, v53, v92
	v_fma_f32 v49, -v44, v92, v42
	v_add_f32_e32 v42, v45, v46
	v_sub_f32_e32 v44, v45, v46
	v_add_f32_e32 v43, v48, v49
	v_sub_f32_e32 v45, v48, v49
	v_xor_b32_e32 v48, 0x80000000, v47
	v_add_f32_e32 v47, v93, v52
	v_sub_f32_e32 v49, v93, v52
	v_fma_f32 v52, v54, v92, v50
	v_mul_f32_e32 v50, v54, v92
	v_add_f32_e32 v46, v94, v48
	v_sub_f32_e32 v48, v94, v48
	v_fma_f32 v53, -v53, v92, v50
	v_add_f32_e32 v50, v95, v52
	v_sub_f32_e32 v52, v95, v52
	v_add_f32_e32 v51, v96, v53
	v_sub_f32_e32 v53, v96, v53
	ds_write2_b64 v73, v[38:39], v[42:43] offset1:1
	ds_write2_b64 v73, v[46:47], v[50:51] offset0:2 offset1:3
	ds_write2_b64 v73, v[40:41], v[44:45] offset0:4 offset1:5
	ds_write2_b64 v73, v[48:49], v[52:53] offset0:6 offset1:7
	s_waitcnt lgkmcnt(0)
	s_barrier
; #define LAS __attribute__((address_space(3)))
; template <int R, bool UNIT> __device__ __forceinline__ void dit_regs(f32x2* v, f32x2 wbig) {
;     float k1 = 0.92387953251128674f, k2 = 0.70710678118654752f, k3 = 0.38268343236508977f; asm volatile("" : "+v"(k1), "+v"(k2), "+v"(k3));
;     f32x2 wbs[R]; wbs[R - 1] = wbig;
; #pragma unroll
;     for (int t = R - 2; t >= 0; --t) wbs[t] = cmul(wbs[t + 1], wbs[t + 1]);
; #pragma unroll
;     for (int t = 0; t < R; ++t) { const int half = 1 << t;
; #pragma unroll
;         for (int k = 0; k < (1 << R); ++k) if (!(k & half)) { const int kk = k & (half - 1), m = kk * (8 / half);
;             const f32x2 a = v[k]; f32x2 b = v[k + half];
;             if (UNIT) { if (m == 4) b = (f32x2){-b.y, b.x}; else if (m != 0) b = cmulc(b, CW16(m)); }
;             else { const f32x2 tw = (m == 0) ? wbs[t] : cmul(wbs[t], CW16(m)); b = cmulc(b, tw); }
;             v[k] = cadd(a, b); v[k + half] = csub(a, b); } }
; }
; template <int R> __device__ __forceinline__ void dif_pass_rt(LAS f32x2* X, int sl, const f32x2 wb_in, int tid) {
;     float wbx = wb_in.x, wby = wb_in.y; asm volatile("" : "+v"(wbx), "+v"(wby)); const f32x2 wb = {wbx, wby};
;     const int r = tid & ((1 << sl) - 1), base = ((tid >> sl) << (sl + R)) + r;
;     LAS f32x2* Xb = X + PADI(base); f32x2 v[1 << R];
; #pragma unroll
;     for (int k = 0; k < (1 << R); ++k) v[k] = Xb[(k << sl) + ((k << sl) >> 4)];
;     dif_regs<R, false>(v, wb);
; #pragma unroll
;     for (int k = 0; k < (1 << R); ++k) Xb[(k << sl) + ((k << sl) >> 4)] = v[k];
; }
; template <int R> __device__ __forceinline__ void dit_pass_rt(LAS f32x2* X, int sl, const f32x2 wb_in, int tid) {
;     float wbx = wb_in.x, wby = wb_in.y; asm volatile("" : "+v"(wbx), "+v"(wby)); const f32x2 wbig = {wbx, wby};
;     const int r = tid & ((1 << sl) - 1), base = ((tid >> sl) << (sl + R)) + r;
;     LAS f32x2* Xb = X + PADI(base); f32x2 v[1 << R];
; #pragma unroll
;     for (int k = 0; k < (1 << R); ++k) v[k] = Xb[(k << sl) + ((k << sl) >> 4)];
;     dit_regs<R, false>(v, wbig);
; #pragma unroll
;     for (int k = 0; k < (1 << R); ++k) Xb[(k << sl) + ((k << sl) >> 4)] = v[k];
; }
; template <int NPT> __device__ __forceinline__ void conv2(LAS f32x2* Xe, LAS f32x2* Xo, const f32x2* tw, int tid, f32x2* ve, f32x2* vo, const f32x2* KE, const f32x2* KO) {
;     ...
;     constexpr int R = NPT == 16 ? 4 : 3;
; #pragma nounroll
.LBB0_644:
	s_cmp_eq_u32 s6, 0
	s_cselect_b32 s7, 6, 3
	s_cmp_lg_u32 s6, 1
	s_cselect_b32 s27, s7, 9
	s_sub_i32 s7, 11, s27
	v_lshlrev_b32_e32 v38, s7, v32
	v_and_b32_e32 v38, 0x7ff, v38
	v_lshlrev_b32_e32 v176, 3, v38
	v_lshl_add_u64 v[38:39], s[50:51], 0, v[176:177]
	global_load_dwordx2 v[38:39], v[38:39], off
	v_bfe_u32 v40, v32, 0, s27
	v_ashrrev_i32_e32 v41, s27, v32
	s_add_i32 s7, s27, 3
	v_lshl_add_u32 v40, v41, s7, v40
	s_lshl_b32 s7, 1, s27
	s_ashr_i32 s10, s7, 4
	s_lshl_b32 s7, s7, 3
	s_lshl_b32 s10, s10, 3
	s_add_i32 s7, s10, s7
	s_lshl_b32 s10, 2, s27
	s_ashr_i32 s11, s10, 4
	s_lshl_b32 s10, s10, 3
	s_lshl_b32 s11, s11, 3
	s_add_i32 s10, s11, s10
	s_lshl_b32 s11, 3, s27
	s_ashr_i32 s24, s11, 4
	s_lshl_b32 s11, s11, 3
	s_lshl_b32 s24, s24, 3
	s_add_i32 s11, s24, s11
	s_lshl_b32 s24, 4, s27
	s_ashr_i32 s25, s24, 4
	s_lshl_b32 s24, s24, 3
	s_lshl_b32 s25, s25, 3
	s_add_i32 s24, s25, s24
	s_lshl_b32 s25, 5, s27
	s_ashr_i32 s26, s25, 4
	s_lshl_b32 s25, s25, 3
	s_lshl_b32 s26, s26, 3
	s_add_i32 s25, s26, s25
	s_lshl_b32 s26, 6, s27
	s_ashr_i32 s30, s26, 4
	s_lshl_b32 s26, s26, 3
	s_lshl_b32 s30, s30, 3
	s_lshl_b32 s27, 7, s27
	v_ashrrev_i32_e32 v41, 4, v40
	s_add_i32 s26, s30, s26
	s_ashr_i32 s30, s27, 4
	v_lshlrev_b32_e32 v94, 3, v41
	v_lshlrev_b32_e32 v95, 3, v40
	s_lshl_b32 s27, s27, 3
	s_lshl_b32 s30, s30, 3
	v_add3_u32 v96, 0, v94, v95
	s_add_i32 s27, s30, s27
	v_add_u32_e32 v97, s7, v96
	v_add_u32_e32 v98, s10, v96
	v_add_u32_e32 v99, s11, v96
	v_add_u32_e32 v100, s24, v96
	v_add_u32_e32 v101, s25, v96
	v_add_u32_e32 v102, s26, v96
	v_add_u32_e32 v103, s27, v96
	v_mov_b32_e32 v104, 0x3f3504f3
	v_mov_b32_e32 v105, 0x3f6c835e
	v_mov_b32_e32 v106, 0x3ec3ef15
	s_add_i32 s6, s6, 1
	s_cmp_lg_u32 s6, 2
	s_waitcnt vmcnt(0) lgkmcnt(0)
	v_mov_b32_e32 v92, v39
	v_mov_b32_e32 v93, v38
	ds_read_b64 v[40:41], v96
	ds_read_b64 v[44:45], v97
	ds_read_b64 v[42:43], v98
	ds_read_b64 v[48:49], v99
	ds_read_b64 v[46:47], v100
	ds_read_b64 v[52:53], v101
	ds_read_b64 v[50:51], v102
	ds_read_b64 v[54:55], v103
	s_nop 0
	v_mul_f32_e32 v105, v93, v93
	v_mul_f32_e32 v106, v93, v92
	v_xor_b32_e32 v109, 0x80000000, v104
	v_fma_f32 v105, -v92, v92, v105
	v_fma_f32 v106, v92, v93, v106
	v_mul_f32_e32 v107, v105, v105
	v_mul_f32_e32 v108, v105, v106
	v_fma_f32 v107, -v106, v106, v107
	v_fma_f32 v108, v106, v105, v108
	s_waitcnt lgkmcnt(6)
	v_mul_f32_e32 v110, v44, v107
	v_fma_f32 v110, v45, v108, v110
	v_mul_f32_e32 v45, v45, v107
	v_fma_f32 v44, -v44, v108, v45
	v_add_f32_e32 v45, v40, v110
	v_sub_f32_e32 v40, v40, v110
	v_add_f32_e32 v111, v41, v44
	v_sub_f32_e32 v41, v41, v44
	s_waitcnt lgkmcnt(4)
	v_mul_f32_e32 v44, v48, v107
	v_fma_f32 v44, v49, v108, v44
	v_mul_f32_e32 v49, v49, v107
	v_fma_f32 v48, -v48, v108, v49
	v_add_f32_e32 v49, v42, v44
	v_sub_f32_e32 v42, v42, v44
	s_waitcnt lgkmcnt(2)
	v_mul_f32_e32 v44, v52, v107
	v_add_f32_e32 v110, v43, v48
	v_sub_f32_e32 v43, v43, v48
	v_fma_f32 v44, v53, v108, v44
	v_mul_f32_e32 v48, v53, v107
	v_fma_f32 v48, -v52, v108, v48
	v_add_f32_e32 v52, v46, v44
	v_sub_f32_e32 v44, v46, v44
	v_add_f32_e32 v53, v47, v48
	v_sub_f32_e32 v46, v47, v48
	s_waitcnt lgkmcnt(0)
	v_mul_f32_e32 v47, v54, v107
	v_mul_f32_e32 v48, v55, v107
	v_fma_f32 v47, v55, v108, v47
	v_fma_f32 v48, -v54, v108, v48
	v_add_f32_e32 v54, v50, v47
	v_sub_f32_e32 v47, v50, v47
	v_mul_f32_e32 v50, v49, v105
	v_add_f32_e32 v55, v51, v48
	v_sub_f32_e32 v48, v51, v48
	v_mul_f32_e32 v51, v110, v105
	v_fma_f32 v50, v110, v106, v50
	v_fma_f32 v49, -v49, v106, v51
	v_add_f32_e32 v51, v45, v50
	v_sub_f32_e32 v50, v45, v50
	v_mul_f32_e32 v45, v105, v177
	v_add_f32_e32 v107, v111, v49
	v_sub_f32_e32 v108, v111, v49
	v_mul_f32_e32 v49, v105, v197
	v_fma_f32 v45, -v106, v197, v45
	v_fma_f32 v49, v106, v177, v49
	v_mul_f32_e32 v110, v42, v45
	v_fma_f32 v110, v43, v49, v110
	v_mul_f32_e32 v43, v43, v45
	v_add_f32_e32 v111, v40, v110
	v_sub_f32_e32 v110, v40, v110
	v_mul_f32_e32 v40, v54, v105
	v_fma_f32 v42, -v42, v49, v43
	v_fma_f32 v40, v55, v106, v40
	v_add_f32_e32 v112, v41, v42
	v_sub_f32_e32 v113, v41, v42
	v_mul_f32_e32 v41, v55, v105
	v_mul_f32_e32 v105, v93, v109
	v_add_f32_e32 v42, v52, v40
	v_sub_f32_e32 v52, v52, v40
	v_mul_f32_e32 v40, v47, v45
	v_fma_f32 v41, -v54, v106, v41
	v_fma_f32 v40, v48, v49, v40
	v_add_f32_e32 v43, v53, v41
	v_sub_f32_e32 v53, v53, v41
	v_mul_f32_e32 v41, v48, v45
	v_add_f32_e32 v45, v44, v40
	v_sub_f32_e32 v54, v44, v40
	v_mul_f32_e32 v40, v42, v93
	v_fma_f32 v41, -v47, v49, v41
	v_mul_f32_e32 v49, v93, v197
	v_fma_f32 v44, v43, v92, v40
	v_mul_f32_e32 v40, v43, v93
	v_add_f32_e32 v47, v46, v41
	v_sub_f32_e32 v55, v46, v41
	v_fma_f32 v46, v92, v104, v105
	v_fma_f32 v49, v92, v177, v49
	v_fma_f32 v43, -v42, v92, v40
	v_add_f32_e32 v40, v51, v44
	v_sub_f32_e32 v42, v51, v44
	v_mul_f32_e32 v44, v93, v104
	v_fma_f32 v44, -v92, v109, v44
	v_add_f32_e32 v41, v107, v43
	v_sub_f32_e32 v43, v107, v43
	v_mul_f32_e32 v48, v45, v44
	v_mul_f32_e32 v44, v47, v44
	v_fma_f32 v48, v47, v46, v48
	v_fma_f32 v47, -v45, v46, v44
	v_add_f32_e32 v44, v111, v48
	v_sub_f32_e32 v46, v111, v48
	v_mul_f32_e32 v48, v93, v177
	v_add_f32_e32 v45, v112, v47
	v_sub_f32_e32 v47, v112, v47
	v_fma_f32 v48, -v92, v197, v48
	v_mul_f32_e32 v51, v52, v48
	v_mul_f32_e32 v48, v53, v48
	v_fma_f32 v51, v53, v49, v51
	v_fma_f32 v52, -v52, v49, v48
	v_fma_f32 v53, v92, v109, v105
	v_add_f32_e32 v48, v50, v51
	v_add_f32_e32 v49, v108, v52
	v_sub_f32_e32 v50, v50, v51
	v_sub_f32_e32 v51, v108, v52
	v_fma_f32 v52, -v92, v109, v105
	v_mul_f32_e32 v92, v54, v52
	v_mul_f32_e32 v52, v55, v52
	v_fma_f32 v92, v55, v53, v92
	v_fma_f32 v55, -v54, v53, v52
	v_add_f32_e32 v52, v110, v92
	v_sub_f32_e32 v54, v110, v92
	v_add3_u32 v92, s55, v94, v95
	v_add_f32_e32 v53, v113, v55
	v_sub_f32_e32 v55, v113, v55
	ds_write_b64 v96, v[40:41]
	ds_write_b64 v97, v[44:45]
	ds_write_b64 v98, v[48:49]
	ds_write_b64 v99, v[52:53]
	ds_write_b64 v100, v[42:43]
	ds_write_b64 v101, v[46:47]
	ds_write_b64 v102, v[50:51]
	ds_write_b64 v103, v[54:55]
	v_add_u32_e32 v93, s7, v92
	v_add_u32_e32 v94, s10, v92
	v_add_u32_e32 v95, s11, v92
	v_add_u32_e32 v96, s24, v92
	v_add_u32_e32 v97, s25, v92
	v_add_u32_e32 v98, s26, v92
	v_add_u32_e32 v99, s27, v92
	v_mov_b32_e32 v100, 0x3f3504f3
	v_mov_b32_e32 v101, 0x3f6c835e
	v_mov_b32_e32 v102, 0x3ec3ef15
	ds_read_b64 v[50:51], v92
	ds_read_b64 v[54:55], v93
	ds_read_b64 v[46:47], v94
	ds_read_b64 v[52:53], v95
	ds_read_b64 v[42:43], v96
	ds_read_b64 v[48:49], v97
	ds_read_b64 v[40:41], v98
	ds_read_b64 v[44:45], v99
	s_nop 0
	v_mul_f32_e32 v101, v38, v38
	v_mul_f32_e32 v102, v38, v39
	v_xor_b32_e32 v105, 0x80000000, v100
	v_fma_f32 v101, -v39, v39, v101
	v_fma_f32 v102, v39, v38, v102
	v_mul_f32_e32 v103, v101, v101
	v_mul_f32_e32 v104, v101, v102
	v_fma_f32 v103, -v102, v102, v103
	v_fma_f32 v104, v102, v101, v104
	s_waitcnt lgkmcnt(6)
; #define LAS __attribute__((address_space(3)))
; template <int R, bool UNIT> __device__ __forceinline__ void dit_regs(f32x2* v, f32x2 wbig) {
;     float k1 = 0.92387953251128674f, k2 = 0.70710678118654752f, k3 = 0.38268343236508977f; asm volatile("" : "+v"(k1), "+v"(k2), "+v"(k3));
;     f32x2 wbs[R]; wbs[R - 1] = wbig;
; #pragma unroll
;     for (int t = R - 2; t >= 0; --t) wbs[t] = cmul(wbs[t + 1], wbs[t + 1]);
; #pragma unroll
;     for (int t = 0; t < R; ++t) { const int half = 1 << t;
; #pragma unroll
;         for (int k = 0; k < (1 << R); ++k) if (!(k & half)) { const int kk = k & (half - 1), m = kk * (8 / half);
;             const f32x2 a = v[k]; f32x2 b = v[k + half];
;             if (UNIT) { if (m == 4) b = (f32x2){-b.y, b.x}; else if (m != 0) b = cmulc(b, CW16(m)); }
;             else { const f32x2 tw = (m == 0) ? wbs[t] : cmul(wbs[t], CW16(m)); b = cmulc(b, tw); }
;             v[k] = cadd(a, b); v[k + half] = csub(a, b); } }
; }
; template <int R> __device__ __forceinline__ void dif_pass_rt(LAS f32x2* X, int sl, const f32x2 wb_in, int tid) {
;     float wbx = wb_in.x, wby = wb_in.y; asm volatile("" : "+v"(wbx), "+v"(wby)); const f32x2 wb = {wbx, wby};
;     const int r = tid & ((1 << sl) - 1), base = ((tid >> sl) << (sl + R)) + r;
;     LAS f32x2* Xb = X + PADI(base); f32x2 v[1 << R];
; #pragma unroll
;     for (int k = 0; k < (1 << R); ++k) v[k] = Xb[(k << sl) + ((k << sl) >> 4)];
;     dif_regs<R, false>(v, wb);
; #pragma unroll
;     for (int k = 0; k < (1 << R); ++k) Xb[(k << sl) + ((k << sl) >> 4)] = v[k];
; }
; template <int R> __device__ __forceinline__ void dit_pass_rt(LAS f32x2* X, int sl, const f32x2 wb_in, int tid) {
;     float wbx = wb_in.x, wby = wb_in.y; asm volatile("" : "+v"(wbx), "+v"(wby)); const f32x2 wbig = {wbx, wby};
;     const int r = tid & ((1 << sl) - 1), base = ((tid >> sl) << (sl + R)) + r;
;     LAS f32x2* Xb = X + PADI(base); f32x2 v[1 << R];
; #pragma unroll
;     for (int k = 0; k < (1 << R); ++k) v[k] = Xb[(k << sl) + ((k << sl) >> 4)];
;     dit_regs<R, false>(v, wbig);
; #pragma unroll
;     for (int k = 0; k < (1 << R); ++k) Xb[(k << sl) + ((k << sl) >> 4)] = v[k];
; }
; template <int NPT> __device__ __forceinline__ void conv2(LAS f32x2* Xe, LAS f32x2* Xo, const f32x2* tw, int tid, f32x2* ve, f32x2* vo, const f32x2* KE, const f32x2* KO) {
;     ...
;     constexpr int R = NPT == 16 ? 4 : 3;
; #pragma nounroll
	v_mul_f32_e32 v106, v54, v103
	v_fma_f32 v106, v55, v104, v106
	v_mul_f32_e32 v55, v55, v103
	v_fma_f32 v54, -v54, v104, v55
	v_add_f32_e32 v55, v50, v106
	v_sub_f32_e32 v50, v50, v106
	v_add_f32_e32 v107, v51, v54
	v_sub_f32_e32 v51, v51, v54
	s_waitcnt lgkmcnt(4)
	v_mul_f32_e32 v54, v52, v103
	v_fma_f32 v54, v53, v104, v54
	v_mul_f32_e32 v53, v53, v103
	v_fma_f32 v52, -v52, v104, v53
	v_add_f32_e32 v53, v46, v54
	v_sub_f32_e32 v46, v46, v54
	v_add_f32_e32 v106, v47, v52
	v_sub_f32_e32 v47, v47, v52
	s_waitcnt lgkmcnt(2)
	v_mul_f32_e32 v52, v48, v103
	v_fma_f32 v52, v49, v104, v52
	v_mul_f32_e32 v49, v49, v103
	v_fma_f32 v48, -v48, v104, v49
	v_add_f32_e32 v49, v42, v52
	v_sub_f32_e32 v42, v42, v52
	v_add_f32_e32 v54, v43, v48
	v_sub_f32_e32 v43, v43, v48
	s_waitcnt lgkmcnt(0)
	v_mul_f32_e32 v48, v44, v103
	v_fma_f32 v48, v45, v104, v48
	v_mul_f32_e32 v45, v45, v103
	v_fma_f32 v44, -v44, v104, v45
	v_add_f32_e32 v45, v40, v48
	v_sub_f32_e32 v40, v40, v48
	v_mul_f32_e32 v48, v106, v101
	v_add_f32_e32 v52, v41, v44
	v_sub_f32_e32 v41, v41, v44
	v_mul_f32_e32 v44, v53, v101
	v_fma_f32 v48, -v53, v102, v48
	v_fma_f32 v44, v106, v102, v44
	v_add_f32_e32 v103, v107, v48
	v_sub_f32_e32 v104, v107, v48
	v_mul_f32_e32 v48, v101, v197
	v_add_f32_e32 v53, v55, v44
	v_sub_f32_e32 v55, v55, v44
	v_mul_f32_e32 v44, v101, v177
	v_fma_f32 v48, v102, v177, v48
	v_fma_f32 v44, -v102, v197, v44
	v_mul_f32_e32 v106, v46, v44
	v_fma_f32 v106, v47, v48, v106
	v_mul_f32_e32 v47, v47, v44
	v_fma_f32 v46, -v46, v48, v47
	v_add_f32_e32 v47, v50, v106
	v_sub_f32_e32 v106, v50, v106
	v_mul_f32_e32 v50, v52, v101
	v_add_f32_e32 v107, v51, v46
	v_sub_f32_e32 v108, v51, v46
	v_mul_f32_e32 v46, v45, v101
	v_fma_f32 v45, -v45, v102, v50
	v_fma_f32 v46, v52, v102, v46
	v_add_f32_e32 v51, v54, v45
	v_sub_f32_e32 v52, v54, v45
	v_mul_f32_e32 v45, v40, v44
	v_fma_f32 v45, v41, v48, v45
	v_mul_f32_e32 v41, v41, v44
	v_add_f32_e32 v50, v49, v46
	v_sub_f32_e32 v49, v49, v46
	v_fma_f32 v40, -v40, v48, v41
	v_add_f32_e32 v44, v42, v45
	v_sub_f32_e32 v54, v42, v45
	v_mul_f32_e32 v45, v38, v100
	v_add_f32_e32 v46, v43, v40
	v_sub_f32_e32 v101, v43, v40
	v_mul_f32_e32 v40, v50, v38
	v_fma_f32 v45, -v39, v105, v45
	v_fma_f32 v42, v51, v39, v40
	v_mul_f32_e32 v40, v51, v38
	v_fma_f32 v43, -v50, v39, v40
	v_add_f32_e32 v40, v53, v42
	v_sub_f32_e32 v42, v53, v42
	v_mul_f32_e32 v53, v38, v105
	v_mul_f32_e32 v50, v44, v45
	v_mul_f32_e32 v45, v46, v45
	v_add_f32_e32 v41, v103, v43
	v_sub_f32_e32 v43, v103, v43
	v_fma_f32 v48, v39, v100, v53
	v_fma_f32 v50, v46, v48, v50
	v_fma_f32 v48, -v44, v48, v45
	v_add_f32_e32 v44, v47, v50
	v_add_f32_e32 v45, v107, v48
	v_sub_f32_e32 v46, v47, v50
	v_sub_f32_e32 v47, v107, v48
	v_mul_f32_e32 v48, v38, v177
	v_mul_f32_e32 v38, v38, v197
	v_fma_f32 v48, -v39, v197, v48
	v_fma_f32 v38, v39, v177, v38
	v_mul_f32_e32 v50, v49, v48
	v_mul_f32_e32 v48, v52, v48
	v_fma_f32 v50, v52, v38, v50
	v_fma_f32 v38, -v49, v38, v48
	v_add_f32_e32 v49, v104, v38
	v_sub_f32_e32 v51, v104, v38
	v_fma_f32 v38, -v39, v105, v53
	v_fma_f32 v39, v39, v105, v53
	v_add_f32_e32 v48, v55, v50
	v_sub_f32_e32 v50, v55, v50
	v_mul_f32_e32 v52, v54, v38
	v_mul_f32_e32 v38, v101, v38
	v_fma_f32 v52, v101, v39, v52
	v_fma_f32 v53, -v54, v39, v38
	v_add_f32_e32 v38, v106, v52
	v_add_f32_e32 v39, v108, v53
	v_sub_f32_e32 v52, v106, v52
	v_sub_f32_e32 v53, v108, v53
	ds_write_b64 v92, v[40:41]
	ds_write_b64 v93, v[44:45]
	ds_write_b64 v94, v[48:49]
	ds_write_b64 v95, v[38:39]
	ds_write_b64 v96, v[42:43]
	ds_write_b64 v97, v[46:47]
	ds_write_b64 v98, v[50:51]
	ds_write_b64 v99, v[52:53]
	s_waitcnt lgkmcnt(0)
	s_barrier
	s_cbranch_scc1 .LBB0_644
; #define LAS __attribute__((address_space(3)))
; __device__ __forceinline__ unsigned f2bf(float f) { unsigned u = __float_as_uint(f); return (u + 0x7fffu + ((u >> 16) & 1u)) >> 16; }
; __device__ __forceinline__ f32x2 cadd(f32x2 a, f32x2 b) { return (f32x2){fadd_(a.x, b.x), fadd_(a.y, b.y)}; }
; __device__ __forceinline__ f32x2 cmulc(f32x2 a, f32x2 b) { return (f32x2){ffma_(a.y, b.y, fmul_(a.x, b.x)), fnma_(a.x, b.y, fmul_(a.y, b.x))}; }
; template <int NPT> __device__ __forceinline__ void conv2(LAS f32x2* Xe, LAS f32x2* Xo, const f32x2* tw, int tid, f32x2* ve, f32x2* vo, const f32x2* KE, const f32x2* KO) {
;     ...
;     { const LAS f32x2* Pe = Xe + PADI(tid); const LAS f32x2* Po = Xo + PADI(tid);
; #pragma unroll
;       for (int k = 0; k < NPT; ++k) { ve[k] = Pe[544 * k]; vo[k] = Po[544 * k]; } }
; template <int NPT>
; __device__ __forceinline__ void hyena_unit(LAS unsigned char* lds, int ch, int rowbase, int nb, const float* H2, const float* w3, const float* bias, bf16_t* ST, const f32x2* T2, int tid_in) {
;     ...
; #pragma unroll
;         for (int i = 0; i < NPT; ++i) { const int j = tid + 512 * i; const f32x2 y = cadd(ve[i], cmulc(vo[i], T2[j * (8192 / N)]));
;             s0[j] = (bf16_t)f2bf(y.x); s1[j] = (bf16_t)f2bf(y.y); }
;     }
;     __syncthreads();
	global_load_dwordx2 v[38:39], v[0:1], off
	ds_read_b64 v[40:41], v90
	ds_read_b64 v[42:43], v90 offset:4352
	ds_read_b64 v[44:45], v90 offset:8704
	ds_read_b64 v[46:47], v90 offset:13056
	ds_read_b64 v[48:49], v91
	ds_read_b64 v[50:51], v91 offset:4352
	ds_read_b64 v[52:53], v91 offset:8704
	ds_read_b64 v[54:55], v91 offset:13056
	ds_read_b64 v[92:93], v90 offset:17408
	ds_read_b64 v[94:95], v90 offset:21760
	ds_read_b64 v[96:97], v90 offset:26112
	ds_read_b64 v[98:99], v90 offset:30464
	ds_read_b64 v[100:101], v91 offset:17408
	ds_read_b64 v[102:103], v91 offset:21760
	ds_read_b64 v[104:105], v91 offset:26112
	ds_read_b64 v[106:107], v91 offset:30464
	s_waitcnt vmcnt(0) lgkmcnt(0)
	v_mul_f32_e32 v108, v48, v38
	v_mul_f32_e32 v38, v49, v38
	s_mov_b64 s[6:7], 0x400000
	v_fma_f32 v49, v49, v39, v108
	v_fma_f32 v38, -v48, v39, v38
	s_andn2_b64 vcc, exec, s[82:83]
	v_add_f32_e32 v39, v40, v49
	v_add_f32_e32 v38, v41, v38
	s_mov_b64 s[10:11], 0
	v_bfe_u32 v40, v39, 16, 1
	v_bfe_u32 v41, v38, 16, 1
	v_add3_u32 v39, v39, v40, s97
	v_add3_u32 v38, v38, v41, s97
	global_store_short_d16_hi v[16:17], v39, off
	global_store_short_d16_hi v[18:19], v38, off
	global_load_dwordx2 v[38:39], v[2:3], off
	s_waitcnt vmcnt(0) lgkmcnt(0)
	v_mul_f32_e32 v40, v50, v38
	v_mul_f32_e32 v38, v51, v38
	v_fma_f32 v40, v51, v39, v40
	v_fma_f32 v38, -v50, v39, v38
	v_add_f32_e32 v39, v42, v40
	v_add_f32_e32 v38, v43, v38
	s_nop 0
	v_bfe_u32 v40, v39, 16, 1
	v_bfe_u32 v41, v38, 16, 1
	v_add3_u32 v39, v39, v40, s97
	v_add3_u32 v38, v38, v41, s97
	global_store_short_d16_hi v[16:17], v39, off offset:1024
	global_store_short_d16_hi v[18:19], v38, off offset:1024
	global_load_dwordx2 v[38:39], v[4:5], off
	s_waitcnt vmcnt(0) lgkmcnt(0)
	v_mul_f32_e32 v40, v52, v38
	v_mul_f32_e32 v38, v53, v38
	v_fma_f32 v40, v53, v39, v40
	v_fma_f32 v38, -v52, v39, v38
	v_add_f32_e32 v39, v44, v40
	v_add_f32_e32 v38, v45, v38
	s_nop 0
	v_bfe_u32 v40, v39, 16, 1
	v_bfe_u32 v41, v38, 16, 1
	v_add3_u32 v39, v39, v40, s97
	v_add3_u32 v38, v38, v41, s97
	global_store_short_d16_hi v[16:17], v39, off offset:2048
	global_store_short_d16_hi v[18:19], v38, off offset:2048
	global_load_dwordx2 v[38:39], v[6:7], off
	s_waitcnt vmcnt(0) lgkmcnt(0)
	v_mul_f32_e32 v40, v54, v38
	v_mul_f32_e32 v38, v55, v38
	v_fma_f32 v40, v55, v39, v40
	v_fma_f32 v38, -v54, v39, v38
	v_add_f32_e32 v39, v46, v40
	v_add_f32_e32 v38, v47, v38
	s_nop 0
	v_bfe_u32 v40, v39, 16, 1
	v_bfe_u32 v41, v38, 16, 1
	v_add3_u32 v39, v39, v40, s97
	v_add3_u32 v38, v38, v41, s97
	global_store_short_d16_hi v[16:17], v39, off offset:3072
	global_store_short_d16_hi v[18:19], v38, off offset:3072
	global_load_dwordx2 v[16:17], v[8:9], off
	s_waitcnt vmcnt(0) lgkmcnt(0)
	v_mul_f32_e32 v18, v100, v16
	v_mul_f32_e32 v16, v101, v16
	v_fma_f32 v18, v101, v17, v18
	v_fma_f32 v16, -v100, v17, v16
	v_add_f32_e32 v17, v92, v18
	v_add_f32_e32 v16, v93, v16
	s_nop 0
	v_bfe_u32 v18, v17, 16, 1
	v_bfe_u32 v19, v16, 16, 1
	v_add3_u32 v17, v17, v18, s97
	v_add3_u32 v16, v16, v19, s97
	global_store_short_d16_hi v[24:25], v17, off
	global_store_short_d16_hi v[26:27], v16, off
	global_load_dwordx2 v[16:17], v[10:11], off
	s_waitcnt vmcnt(0) lgkmcnt(0)
	v_mul_f32_e32 v18, v102, v16
	v_mul_f32_e32 v16, v103, v16
	v_fma_f32 v18, v103, v17, v18
	v_fma_f32 v16, -v102, v17, v16
	v_add_f32_e32 v17, v94, v18
	v_add_f32_e32 v16, v95, v16
	s_nop 0
	v_bfe_u32 v18, v17, 16, 1
	v_bfe_u32 v19, v16, 16, 1
	v_add3_u32 v17, v17, v18, s97
	v_add3_u32 v16, v16, v19, s97
	global_store_short_d16_hi v[20:21], v17, off
	global_store_short_d16_hi v[22:23], v16, off
	global_load_dwordx2 v[16:17], v[12:13], off
	s_waitcnt vmcnt(0) lgkmcnt(0)
	v_mul_f32_e32 v18, v104, v16
	v_mul_f32_e32 v16, v105, v16
	v_fma_f32 v18, v105, v17, v18
	v_fma_f32 v16, -v104, v17, v16
	v_add_f32_e32 v17, v96, v18
	v_add_f32_e32 v16, v97, v16
	s_nop 0
	v_bfe_u32 v18, v17, 16, 1
	v_bfe_u32 v19, v16, 16, 1
	v_add3_u32 v17, v17, v18, s97
	v_add3_u32 v16, v16, v19, s97
	global_store_short_d16_hi v[34:35], v17, off
	global_store_short_d16_hi v[36:37], v16, off
	global_load_dwordx2 v[16:17], v[14:15], off
	s_waitcnt vmcnt(0) lgkmcnt(0)
	v_mul_f32_e32 v18, v106, v16
	v_mul_f32_e32 v16, v107, v16
	v_fma_f32 v18, v107, v17, v18
	v_fma_f32 v16, -v106, v17, v16
	v_add_f32_e32 v17, v98, v18
	v_add_f32_e32 v16, v99, v16
	s_nop 0
	v_bfe_u32 v18, v17, 16, 1
	v_bfe_u32 v19, v16, 16, 1
	v_add3_u32 v17, v17, v18, s97
	v_add3_u32 v16, v16, v19, s97
	global_store_short_d16_hi v[28:29], v17, off
	global_store_short_d16_hi v[30:31], v16, off
	s_cbranch_vccnz .LBB0_641
	s_mov_b64 s[84:85], 0x40000
	s_waitcnt lgkmcnt(0)
	s_barrier
	s_branch .LBB0_609

; __device__ __forceinline__ float shfl_xor_l(float v, int o, int lane) { return __int_as_float(__builtin_amdgcn_ds_bpermute((lane ^ o) << 2, __float_as_int(v))); }
; __device__ __forceinline__ float ffma_(float a, float b, float c) { float r; asm("v_fma_f32 %0, %1, %2, %3" : "=v"(r) : "v"(a), "v"(b), "v"(c)); return r; }
; template <int NPT>
; __device__ __forceinline__ void hyena_unit(LAS unsigned char* lds, int ch, int rowbase, int nb, const float* H2, const float* w3, const float* bias, bf16_t* ST, const f32x2* T2, int tid_in) {
;     ...
; #pragma unroll 2
;       for (int it = 0; it < N / 128; ++it) { const int t = wv * (N / 8) + it * 16 + rr; const f32x4* hp = (const f32x4*)(H2 + (size_t)t * 64) + qs; float af = 0.f, ab = 0.f;
; #pragma unroll
;           for (int s4 = 0; s4 < 4; ++s4) { const f32x4 h = hp[4 * s4];
;               af = ffma_(h.x, wf[s4 * 4], af); af = ffma_(h.y, wf[s4 * 4 + 1], af); af = ffma_(h.z, wf[s4 * 4 + 2], af); af = ffma_(h.w, wf[s4 * 4 + 3], af);
;               ab = ffma_(h.x, wb[s4 * 4], ab); ab = ffma_(h.y, wb[s4 * 4 + 1], ab); ab = ffma_(h.z, wb[s4 * 4 + 2], ab); ab = ffma_(h.w, wb[s4 * 4 + 3], ab); }
;           af += shfl_xor_l(af, 1, lane); ab += shfl_xor_l(ab, 1, lane); af += shfl_xor_l(af, 2, lane); ab += shfl_xor_l(ab, 2, lane);
;           if (qs == 0) { const float win = __builtin_amdgcn_exp2f((float)t * tsc); FW[t] = af * win + (t == 0 ? bs : 0.f); BW[t] = ab * win; } } }
.LBB0_651:
	v_ashrrev_i32_e32 v37, 31, v36
	v_lshlrev_b64 v[38:39], 8, v[36:37]
	v_lshl_add_u64 v[38:39], v[34:35], 0, v[38:39]
	s_waitcnt lgkmcnt(0)
	global_load_dwordx4 v[46:49], v[38:39], off
	s_waitcnt vmcnt(0) lgkmcnt(0)
	v_fma_f32 v37, v46, v0, v177
	v_fma_f32 v45, v46, v8, v177
	v_fma_f32 v37, v47, v1, v37
	v_fma_f32 v45, v47, v9, v45
	v_fma_f32 v37, v48, v2, v37
	v_fma_f32 v45, v48, v10, v45
	v_fma_f32 v37, v49, v3, v37
	v_fma_f32 v45, v49, v11, v45
	global_load_dwordx4 v[46:49], v[38:39], off offset:64
	s_waitcnt vmcnt(0) lgkmcnt(0)
	v_fma_f32 v37, v46, v4, v37
	v_fma_f32 v45, v46, v12, v45
	v_fma_f32 v37, v47, v5, v37
	v_fma_f32 v45, v47, v13, v45
	v_fma_f32 v37, v48, v6, v37
	v_fma_f32 v45, v48, v14, v45
	v_fma_f32 v37, v49, v7, v37
	v_fma_f32 v45, v49, v15, v45
	global_load_dwordx4 v[46:49], v[38:39], off offset:128
	s_waitcnt vmcnt(0) lgkmcnt(0)
	v_fma_f32 v37, v46, v16, v37
	v_fma_f32 v45, v46, v24, v45
	v_fma_f32 v37, v47, v17, v37
	v_fma_f32 v45, v47, v25, v45
	v_fma_f32 v37, v48, v18, v37
	v_fma_f32 v45, v48, v26, v45
	v_fma_f32 v37, v49, v19, v37
	v_fma_f32 v45, v49, v27, v45
	global_load_dwordx4 v[46:49], v[38:39], off offset:192
	s_waitcnt vmcnt(0) lgkmcnt(0)
	v_fma_f32 v37, v46, v20, v37
	v_fma_f32 v38, v46, v28, v45
	v_fma_f32 v37, v47, v21, v37
	v_fma_f32 v38, v47, v29, v38
	v_fma_f32 v37, v48, v22, v37
	v_fma_f32 v38, v48, v30, v38
	v_fma_f32 v37, v49, v23, v37
	v_fma_f32 v39, v49, v31, v38
	ds_bpermute_b32 v38, v41, v37
	s_waitcnt lgkmcnt(0)
	v_add_f32_e32 v38, v37, v38
	ds_bpermute_b32 v37, v41, v39
	ds_bpermute_b32 v45, v42, v38
	s_waitcnt lgkmcnt(1)
	v_add_f32_e32 v39, v39, v37
	ds_bpermute_b32 v46, v42, v39
	v_add_u32_e32 v37, s10, v44
	s_and_saveexec_b64 s[6:7], vcc
	s_cbranch_execz .LBB0_653
	s_waitcnt lgkmcnt(1)
	v_add_f32_e32 v38, v38, v45
	v_cvt_f32_i32_e32 v45, v36
	v_cmp_eq_u32_e64 s[2:3], 0, v36
	s_waitcnt lgkmcnt(0)
	v_add_f32_e32 v39, v39, v46
	v_mul_f32_e32 v45, v40, v45
	v_exp_f32_e32 v45, v45
	v_cndmask_b32_e64 v46, 0, v33, s[2:3]
	v_fmac_f32_e32 v46, v45, v38
	v_mul_f32_e32 v38, v45, v39
	ds_write2st64_b32 v37, v46, v38 offset1:128
.LBB0_653:
	s_or_b64 exec, exec, s[6:7]
	v_add_u32_e32 v38, 16, v36
	v_ashrrev_i32_e32 v39, 31, v38
	s_waitcnt lgkmcnt(0)
	v_lshlrev_b64 v[46:47], 8, v[38:39]
	v_lshl_add_u64 v[50:51], v[34:35], 0, v[46:47]
	global_load_dwordx4 v[46:49], v[50:51], off
	s_waitcnt vmcnt(0) lgkmcnt(0)
	v_fma_f32 v39, v46, v0, v177
	v_fma_f32 v45, v46, v8, v177
	v_fma_f32 v39, v47, v1, v39
	v_fma_f32 v45, v47, v9, v45
	v_fma_f32 v39, v48, v2, v39
	v_fma_f32 v45, v48, v10, v45
	v_fma_f32 v39, v49, v3, v39
	v_fma_f32 v45, v49, v11, v45
	global_load_dwordx4 v[46:49], v[50:51], off offset:64
	s_waitcnt vmcnt(0) lgkmcnt(0)
	v_fma_f32 v39, v46, v4, v39
	v_fma_f32 v45, v46, v12, v45
	v_fma_f32 v39, v47, v5, v39
	v_fma_f32 v45, v47, v13, v45
	v_fma_f32 v39, v48, v6, v39
	v_fma_f32 v45, v48, v14, v45
	v_fma_f32 v39, v49, v7, v39
	v_fma_f32 v45, v49, v15, v45
	global_load_dwordx4 v[46:49], v[50:51], off offset:128
	s_waitcnt vmcnt(0) lgkmcnt(0)
	v_fma_f32 v39, v46, v16, v39
	v_fma_f32 v45, v46, v24, v45
	v_fma_f32 v39, v47, v17, v39
	v_fma_f32 v45, v47, v25, v45
	v_fma_f32 v39, v48, v18, v39
	v_fma_f32 v45, v48, v26, v45
	v_fma_f32 v39, v49, v19, v39
	v_fma_f32 v45, v49, v27, v45
	global_load_dwordx4 v[46:49], v[50:51], off offset:192
	s_waitcnt vmcnt(0) lgkmcnt(0)
	v_fma_f32 v39, v46, v20, v39
	v_fma_f32 v45, v46, v28, v45
	v_fma_f32 v39, v47, v21, v39
	v_fma_f32 v45, v47, v29, v45
	v_fma_f32 v39, v48, v22, v39
	v_fma_f32 v45, v48, v30, v45
	v_fma_f32 v39, v49, v23, v39
	ds_bpermute_b32 v46, v41, v39
	v_fma_f32 v45, v49, v31, v45
	s_waitcnt lgkmcnt(0)
	v_add_f32_e32 v39, v39, v46
	ds_bpermute_b32 v46, v41, v45
	s_waitcnt lgkmcnt(0)
	v_add_f32_e32 v45, v45, v46
	ds_bpermute_b32 v46, v42, v39
	ds_bpermute_b32 v47, v42, v45
	s_and_saveexec_b64 s[2:3], vcc
	s_cbranch_execz .LBB0_650
	v_cvt_f32_i32_e32 v38, v38
	s_waitcnt lgkmcnt(0)
	v_add_f32_e32 v45, v45, v47
	v_add_f32_e32 v39, v39, v46
	v_add_u32_e32 v37, 64, v37
	v_mul_f32_e32 v38, v40, v38
	v_exp_f32_e32 v38, v38
	s_nop 0
	v_fma_f32 v39, v38, v39, 0
	v_mul_f32_e32 v38, v38, v45
	ds_write2st64_b32 v37, v39, v38 offset1:128
	s_branch .LBB0_650

; template <int R, bool UNIT> __device__ __forceinline__ void dif_regs(f32x2* v, f32x2 wb) {
;     float k1 = 0.92387953251128674f, k2 = 0.70710678118654752f, k3 = 0.38268343236508977f; asm volatile("" : "+v"(k1), "+v"(k2), "+v"(k3));
; #pragma unroll
;     for (int t = 0; t < R; ++t) { constexpr int dummy = 0; (void)dummy; const int half = 1 << (R - 1 - t);
; #pragma unroll
;         for (int k = 0; k < (1 << R); ++k) if (!(k & half)) { const int kk = k & (half - 1), m = kk * (8 / half);
;             const f32x2 a = v[k], b = v[k + half]; v[k] = cadd(a, b); const f32x2 d = csub(a, b);
;             if (UNIT) { v[k + half] = (m == 0) ? d : (m == 4) ? (f32x2){d.y, -d.x} : cmul(d, CW16(m)); }
;             else { const f32x2 tw = (m == 0) ? wb : cmul(wb, CW16(m)); v[k + half] = cmul(d, tw); } }
;         if (!UNIT) wb = cmul(wb, wb); }
; }
; template <int R> __device__ __forceinline__ void dif_pass_rt(LAS f32x2* X, int sl, const f32x2 wb_in, int tid) {
;     float wbx = wb_in.x, wby = wb_in.y; asm volatile("" : "+v"(wbx), "+v"(wby)); const f32x2 wb = {wbx, wby};
;     const int r = tid & ((1 << sl) - 1), base = ((tid >> sl) << (sl + R)) + r;
;     LAS f32x2* Xb = X + PADI(base); f32x2 v[1 << R];
; #pragma unroll
;     for (int k = 0; k < (1 << R); ++k) v[k] = Xb[(k << sl) + ((k << sl) >> 4)];
;     dif_regs<R, false>(v, wb);
; #pragma unroll
;     for (int k = 0; k < (1 << R); ++k) Xb[(k << sl) + ((k << sl) >> 4)] = v[k];
; }
; template <int R> __device__ __forceinline__ void dit_pass_rt(LAS f32x2* X, int sl, const f32x2 wb_in, int tid) {
;     float wbx = wb_in.x, wby = wb_in.y; asm volatile("" : "+v"(wbx), "+v"(wby)); const f32x2 wbig = {wbx, wby};
;     const int r = tid & ((1 << sl) - 1), base = ((tid >> sl) << (sl + R)) + r;
;     LAS f32x2* Xb = X + PADI(base); f32x2 v[1 << R];
; #pragma unroll
;     for (int k = 0; k < (1 << R); ++k) v[k] = Xb[(k << sl) + ((k << sl) >> 4)];
;     dit_regs<R, false>(v, wbig);
; #pragma unroll
;     for (int k = 0; k < (1 << R); ++k) Xb[(k << sl) + ((k << sl) >> 4)] = v[k];
; }
; template <int NPT> __device__ __forceinline__ void fwd2_to_lds(LAS f32x2* Xe, LAS f32x2* Xo, const f32x2* tw, int tid, f32x2* ve, f32x2* vo) {
;     constexpr int R = NPT == 16 ? 4 : 3;
;     asm volatile("" : "+v"(tid)); __syncthreads();
;     { LAS f32x2* Pe = Xe + PADI(tid); LAS f32x2* Po = Xo + PADI(tid);
; #pragma unroll
.LBB0_688:
	s_cmp_eq_u32 s3, 1
	s_cselect_b32 s2, 5, 1
	s_cmp_lg_u32 s3, 0
	s_cselect_b32 s2, s2, 9
	s_sub_i32 s6, 10, s2
	v_lshlrev_b32_e32 v34, s6, v92
	v_and_b32_e32 v34, 0x3ff, v34
	v_lshlrev_b32_e32 v176, 3, v34
	v_lshl_add_u64 v[34:35], s[50:51], 0, v[176:177]
	global_load_dwordx2 v[34:35], v[34:35], off
	v_bfe_u32 v36, v92, 0, s2
	v_ashrrev_i32_e32 v37, s2, v92
	s_add_i32 s6, s2, 4
	v_lshl_add_u32 v36, v37, s6, v36
	s_lshl_b32 s6, 1, s2
	s_ashr_i32 s7, s6, 4
	s_lshl_b32 s6, s6, 3
	s_lshl_b32 s7, s7, 3
	s_add_i32 s6, s7, s6
	s_lshl_b32 s7, 2, s2
	s_ashr_i32 s10, s7, 4
	s_lshl_b32 s7, s7, 3
	s_lshl_b32 s10, s10, 3
	s_add_i32 s7, s10, s7
	s_lshl_b32 s10, 3, s2
	s_ashr_i32 s11, s10, 4
	s_lshl_b32 s10, s10, 3
	s_lshl_b32 s11, s11, 3
	s_add_i32 s10, s11, s10
	s_lshl_b32 s11, 4, s2
	s_ashr_i32 s24, s11, 4
	s_lshl_b32 s11, s11, 3
	s_lshl_b32 s24, s24, 3
	s_add_i32 s11, s24, s11
	s_lshl_b32 s24, 5, s2
	s_ashr_i32 s25, s24, 4
	s_lshl_b32 s24, s24, 3
	s_lshl_b32 s25, s25, 3
	s_add_i32 s24, s25, s24
	s_lshl_b32 s25, 6, s2
	s_ashr_i32 s26, s25, 4
	s_lshl_b32 s25, s25, 3
	s_lshl_b32 s26, s26, 3
	s_add_i32 s25, s26, s25
	s_lshl_b32 s26, 7, s2
	s_ashr_i32 s27, s26, 4
	s_lshl_b32 s26, s26, 3
	s_lshl_b32 s27, s27, 3
	s_add_i32 s26, s27, s26
	s_lshl_b32 s27, 8, s2
	s_ashr_i32 s30, s27, 4
	s_lshl_b32 s27, s27, 3
	s_lshl_b32 s30, s30, 3
	s_add_i32 s27, s30, s27
	s_lshl_b32 s30, 9, s2
	s_ashr_i32 s38, s30, 4
	s_lshl_b32 s30, s30, 3
	s_lshl_b32 s38, s38, 3
	s_add_i32 s30, s38, s30
	s_lshl_b32 s38, 10, s2
	s_ashr_i32 s39, s38, 4
	s_lshl_b32 s38, s38, 3
	s_lshl_b32 s39, s39, 3
	s_add_i32 s38, s39, s38
	s_lshl_b32 s39, 11, s2
	s_ashr_i32 s55, s39, 4
	s_lshl_b32 s39, s39, 3
	s_lshl_b32 s55, s55, 3
	s_add_i32 s39, s55, s39
	s_lshl_b32 s55, 12, s2
	s_ashr_i32 s64, s55, 4
	s_lshl_b32 s55, s55, 3
	s_lshl_b32 s64, s64, 3
	s_add_i32 s55, s64, s55
	s_lshl_b32 s64, 13, s2
	s_ashr_i32 s65, s64, 4
	s_lshl_b32 s64, s64, 3
	s_lshl_b32 s65, s65, 3
	s_add_i32 s64, s65, s64
	s_lshl_b32 s65, 14, s2
	v_ashrrev_i32_e32 v37, 4, v36
	s_ashr_i32 s80, s65, 4
	v_lshlrev_b32_e32 v68, 3, v37
	v_lshlrev_b32_e32 v69, 3, v36
	s_lshl_b32 s65, s65, 3
	s_lshl_b32 s80, s80, 3
	s_lshl_b32 s2, 15, s2
	v_add3_u32 v70, 0, v68, v69
	s_add_i32 s65, s80, s65
	s_waitcnt vmcnt(0) lgkmcnt(0)
	v_mov_b32_e32 v86, v35
	v_mov_b32_e32 v87, v34
	s_ashr_i32 s80, s2, 4
	ds_read_b64 v[50:51], v70
	v_add_u32_e32 v71, s6, v70
	v_add_u32_e32 v72, s7, v70
	v_add_u32_e32 v73, s10, v70
	v_add_u32_e32 v78, s27, v70
	v_add_u32_e32 v79, s30, v70
	v_add_u32_e32 v80, s38, v70
	v_add_u32_e32 v81, s39, v70
	s_lshl_b32 s2, s2, 3
	s_lshl_b32 s80, s80, 3
	ds_read_b64 v[48:49], v71
	ds_read_b64 v[46:47], v72
	ds_read_b64 v[44:45], v73
	ds_read_b64 v[66:67], v78
	ds_read_b64 v[64:65], v79
	ds_read_b64 v[62:63], v80
	ds_read_b64 v[60:61], v81
	s_add_i32 s80, s80, s2
	s_waitcnt lgkmcnt(3)
	v_add_f32_e32 v95, v50, v66
	v_sub_f32_e32 v50, v50, v66
	v_add_u32_e32 v74, s11, v70
	v_add_u32_e32 v75, s24, v70
	v_add_u32_e32 v76, s25, v70
	v_add_u32_e32 v77, s26, v70
	v_add_u32_e32 v82, s55, v70
	v_add_u32_e32 v83, s64, v70
	v_add_u32_e32 v84, s65, v70
	v_add_u32_e32 v85, s80, v70
	v_mov_b32_e32 v88, 0x3f3504f3
	v_mov_b32_e32 v89, 0x3f6c835e
	v_mov_b32_e32 v90, 0x3ec3ef15
	v_add_f32_e32 v96, v51, v67
	v_sub_f32_e32 v51, v51, v67
	v_mul_f32_e32 v66, v50, v87
	v_mul_f32_e32 v50, v50, v86
	ds_read_b64 v[42:43], v74
	ds_read_b64 v[40:41], v75
	ds_read_b64 v[38:39], v76
	ds_read_b64 v[36:37], v77
	ds_read_b64 v[58:59], v82
	ds_read_b64 v[56:57], v83
	ds_read_b64 v[54:55], v84
	ds_read_b64 v[52:53], v85
	v_fma_f32 v66, -v51, v86, v66
	v_fma_f32 v50, v51, v87, v50
	s_waitcnt lgkmcnt(10)
	v_add_f32_e32 v51, v48, v64
	v_sub_f32_e32 v48, v48, v64
	v_add_f32_e32 v67, v49, v65
	v_mul_f32_e32 v64, v87, v89
	v_xor_b32_e32 v91, 0x80000000, v90
	v_xor_b32_e32 v93, 0x80000000, v89
	v_sub_f32_e32 v49, v49, v65
	v_fma_f32 v64, -v86, v91, v64
	v_mul_f32_e32 v65, v87, v91
	v_xor_b32_e32 v94, 0x80000000, v88
	v_fma_f32 v89, v86, v89, v65
	v_mul_f32_e32 v97, v48, v64
	s_add_i32 s2, 0, 0x11000
	v_mul_f32_e32 v48, v48, v89
	v_fma_f32 v97, -v49, v89, v97
	v_add3_u32 v68, s2, v68, v69
	v_fma_f32 v48, v49, v64, v48
	s_waitcnt lgkmcnt(9)
	v_add_f32_e32 v49, v46, v62
	v_sub_f32_e32 v46, v46, v62
	v_mul_f32_e32 v62, v87, v88
	v_add_f32_e32 v64, v47, v63
	v_sub_f32_e32 v47, v47, v63
	v_mul_f32_e32 v63, v87, v94
	v_add_u32_e32 v69, s6, v68
	v_fma_f32 v62, -v86, v94, v62
	v_fma_f32 v89, v86, v88, v63
	s_add_i32 s3, s3, 1
	v_mul_f32_e32 v98, v46, v62
	v_mul_f32_e32 v46, v46, v89
	s_cmp_lg_u32 s3, 3
	v_fma_f32 v98, -v47, v89, v98
	v_fma_f32 v46, v47, v62, v46
	s_waitcnt lgkmcnt(8)
	v_add_f32_e32 v47, v44, v60
	v_sub_f32_e32 v44, v44, v60
	v_mul_f32_e32 v60, v87, v90
	v_add_f32_e32 v62, v45, v61
	v_sub_f32_e32 v45, v45, v61
	v_mul_f32_e32 v61, v87, v93
	v_fma_f32 v60, -v86, v93, v60
	v_fma_f32 v89, v86, v90, v61
	v_mul_f32_e32 v90, v44, v60
	v_mul_f32_e32 v44, v44, v89
	v_fma_f32 v90, -v45, v89, v90
	v_fma_f32 v44, v45, v60, v44
	s_waitcnt lgkmcnt(3)
	v_add_f32_e32 v45, v42, v58
	v_add_f32_e32 v60, v43, v59
	v_sub_f32_e32 v42, v42, v58
	v_sub_f32_e32 v43, v43, v59
	v_mul_f32_e32 v58, v87, v177
	v_mul_f32_e32 v59, v87, v197
	v_fma_f32 v58, -v86, v197, v58
	v_fma_f32 v59, v86, v177, v59
	v_mul_f32_e32 v89, v42, v58
	v_mul_f32_e32 v42, v42, v59
	v_fma_f32 v89, -v43, v59, v89
	v_fma_f32 v42, v43, v58, v42
	s_waitcnt lgkmcnt(2)
	v_add_f32_e32 v43, v40, v56
	v_sub_f32_e32 v40, v40, v56
	v_add_f32_e32 v58, v41, v57
	v_sub_f32_e32 v41, v41, v57
	v_fma_f32 v56, -v86, v93, v65
	v_fma_f32 v57, v86, v91, v61
	v_mul_f32_e32 v59, v40, v56
	v_mul_f32_e32 v40, v40, v57
	v_fma_f32 v59, -v41, v57, v59
	v_fma_f32 v40, v41, v56, v40
	s_waitcnt lgkmcnt(1)
; template <int R, bool UNIT> __device__ __forceinline__ void dif_regs(f32x2* v, f32x2 wb) {
;     float k1 = 0.92387953251128674f, k2 = 0.70710678118654752f, k3 = 0.38268343236508977f; asm volatile("" : "+v"(k1), "+v"(k2), "+v"(k3));
; #pragma unroll
;     for (int t = 0; t < R; ++t) { constexpr int dummy = 0; (void)dummy; const int half = 1 << (R - 1 - t);
; #pragma unroll
;         for (int k = 0; k < (1 << R); ++k) if (!(k & half)) { const int kk = k & (half - 1), m = kk * (8 / half);
;             const f32x2 a = v[k], b = v[k + half]; v[k] = cadd(a, b); const f32x2 d = csub(a, b);
;             if (UNIT) { v[k + half] = (m == 0) ? d : (m == 4) ? (f32x2){d.y, -d.x} : cmul(d, CW16(m)); }
;             else { const f32x2 tw = (m == 0) ? wb : cmul(wb, CW16(m)); v[k + half] = cmul(d, tw); } }
;         if (!UNIT) wb = cmul(wb, wb); }
; }
; template <int R> __device__ __forceinline__ void dif_pass_rt(LAS f32x2* X, int sl, const f32x2 wb_in, int tid) {
;     float wbx = wb_in.x, wby = wb_in.y; asm volatile("" : "+v"(wbx), "+v"(wby)); const f32x2 wb = {wbx, wby};
;     const int r = tid & ((1 << sl) - 1), base = ((tid >> sl) << (sl + R)) + r;
;     LAS f32x2* Xb = X + PADI(base); f32x2 v[1 << R];
; #pragma unroll
;     for (int k = 0; k < (1 << R); ++k) v[k] = Xb[(k << sl) + ((k << sl) >> 4)];
;     dif_regs<R, false>(v, wb);
; #pragma unroll
;     for (int k = 0; k < (1 << R); ++k) Xb[(k << sl) + ((k << sl) >> 4)] = v[k];
; }
; template <int R> __device__ __forceinline__ void dit_pass_rt(LAS f32x2* X, int sl, const f32x2 wb_in, int tid) {
;     float wbx = wb_in.x, wby = wb_in.y; asm volatile("" : "+v"(wbx), "+v"(wby)); const f32x2 wbig = {wbx, wby};
;     const int r = tid & ((1 << sl) - 1), base = ((tid >> sl) << (sl + R)) + r;
;     LAS f32x2* Xb = X + PADI(base); f32x2 v[1 << R];
; #pragma unroll
;     for (int k = 0; k < (1 << R); ++k) v[k] = Xb[(k << sl) + ((k << sl) >> 4)];
;     dit_regs<R, false>(v, wbig);
; #pragma unroll
;     for (int k = 0; k < (1 << R); ++k) Xb[(k << sl) + ((k << sl) >> 4)] = v[k];
; }
; template <int NPT> __device__ __forceinline__ void fwd2_to_lds(LAS f32x2* Xe, LAS f32x2* Xo, const f32x2* tw, int tid, f32x2* ve, f32x2* vo) {
;     constexpr int R = NPT == 16 ? 4 : 3;
;     asm volatile("" : "+v"(tid)); __syncthreads();
;     { LAS f32x2* Pe = Xe + PADI(tid); LAS f32x2* Po = Xo + PADI(tid);
; #pragma unroll
	v_add_f32_e32 v41, v38, v54
	v_sub_f32_e32 v38, v38, v54
	v_add_f32_e32 v56, v39, v55
	v_sub_f32_e32 v39, v39, v55
	v_fma_f32 v54, -v86, v94, v63
	v_fma_f32 v55, v86, v94, v63
	v_mul_f32_e32 v57, v38, v54
	v_mul_f32_e32 v38, v38, v55
	v_fma_f32 v57, -v39, v55, v57
	v_fma_f32 v38, v39, v54, v38
	s_waitcnt lgkmcnt(0)
	v_add_f32_e32 v39, v36, v52
	v_sub_f32_e32 v36, v36, v52
	v_add_f32_e32 v54, v37, v53
	v_sub_f32_e32 v37, v37, v53
	v_fma_f32 v52, -v86, v91, v61
	v_fma_f32 v53, v86, v93, v65
	v_add_f32_e32 v61, v96, v60
	v_sub_f32_e32 v60, v96, v60
	v_add_f32_e32 v65, v67, v58
	v_add_f32_e32 v93, v62, v54
	v_mul_f32_e32 v55, v36, v52
	v_mul_f32_e32 v36, v36, v53
	v_fma_f32 v55, -v37, v53, v55
	v_fma_f32 v36, v37, v52, v36
	v_mul_f32_e32 v37, v87, v87
	v_mul_f32_e32 v52, v87, v86
	v_add_f32_e32 v53, v95, v45
	v_sub_f32_e32 v45, v95, v45
	v_fma_f32 v37, -v86, v86, v37
	v_fma_f32 v52, v86, v87, v52
	v_mul_f32_e32 v63, v45, v37
	v_mul_f32_e32 v45, v45, v52
	v_fma_f32 v63, -v60, v52, v63
	v_fma_f32 v45, v60, v37, v45
	v_add_f32_e32 v60, v51, v43
	v_sub_f32_e32 v43, v51, v43
	v_sub_f32_e32 v51, v67, v58
	v_mul_f32_e32 v58, v37, v88
	v_mul_f32_e32 v67, v37, v94
	v_fma_f32 v58, -v52, v94, v58
	v_fma_f32 v86, v52, v88, v67
	v_add_f32_e32 v88, v64, v56
	v_mul_f32_e32 v87, v43, v58
	v_mul_f32_e32 v43, v43, v86
	v_fma_f32 v87, -v51, v86, v87
	v_fma_f32 v43, v51, v58, v43
	v_add_f32_e32 v51, v49, v41
	v_sub_f32_e32 v41, v49, v41
	v_sub_f32_e32 v49, v64, v56
	v_mul_f32_e32 v56, v37, v177
	v_mul_f32_e32 v64, v37, v197
	v_fma_f32 v56, -v52, v197, v56
	v_fma_f32 v64, v52, v177, v64
	v_mul_f32_e32 v91, v41, v56
	v_mul_f32_e32 v41, v41, v64
	v_fma_f32 v91, -v49, v64, v91
	v_fma_f32 v41, v49, v56, v41
	v_add_f32_e32 v49, v47, v39
	v_sub_f32_e32 v39, v47, v39
	v_sub_f32_e32 v47, v62, v54
	v_fma_f32 v54, -v52, v94, v67
	v_fma_f32 v62, v52, v94, v67
	v_add_f32_e32 v94, v50, v42
	v_sub_f32_e32 v42, v50, v42
	v_mul_f32_e32 v67, v39, v54
	v_mul_f32_e32 v39, v39, v62
	v_fma_f32 v67, -v47, v62, v67
	v_fma_f32 v39, v47, v54, v39
	v_add_f32_e32 v47, v66, v89
	v_sub_f32_e32 v66, v66, v89
	v_add_f32_e32 v89, v48, v40
	v_sub_f32_e32 v40, v48, v40
	v_mul_f32_e32 v50, v66, v37
	v_mul_f32_e32 v66, v66, v52
	v_fma_f32 v50, -v42, v52, v50
	v_fma_f32 v42, v42, v37, v66
	v_add_f32_e32 v66, v97, v59
	v_sub_f32_e32 v59, v97, v59
	v_mul_f32_e32 v48, v59, v58
	v_mul_f32_e32 v59, v59, v86
	v_fma_f32 v48, -v40, v86, v48
	v_fma_f32 v40, v40, v58, v59
	v_add_f32_e32 v58, v98, v57
	v_sub_f32_e32 v57, v98, v57
	v_add_f32_e32 v59, v46, v38
	v_sub_f32_e32 v38, v46, v38
	v_mul_f32_e32 v46, v57, v56
	v_mul_f32_e32 v57, v57, v64
	v_add_f32_e32 v96, v94, v59
	v_add_f32_e32 v95, v47, v58
	v_fma_f32 v46, -v38, v64, v46
	v_fma_f32 v38, v38, v56, v57
	v_add_f32_e32 v56, v90, v55
	v_add_f32_e32 v57, v44, v36
	v_sub_f32_e32 v55, v90, v55
	v_sub_f32_e32 v36, v44, v36
	v_add_f32_e32 v98, v50, v46
	v_add_f32_e32 v99, v42, v38
	v_sub_f32_e32 v38, v42, v38
	v_add_f32_e32 v97, v89, v57
	v_mul_f32_e32 v44, v55, v54
	v_mul_f32_e32 v55, v55, v62
	v_fma_f32 v44, -v36, v62, v44
	v_fma_f32 v36, v36, v54, v55
	v_mul_f32_e32 v54, v37, v37
	v_mul_f32_e32 v55, v37, v52
	v_add_f32_e32 v62, v65, v93
	v_fma_f32 v54, -v52, v52, v54
	v_fma_f32 v37, v52, v37, v55
	v_add_f32_e32 v52, v53, v51
	v_sub_f32_e32 v51, v53, v51
	v_add_f32_e32 v55, v61, v88
	v_sub_f32_e32 v53, v61, v88
	v_mul_f32_e32 v64, v54, v177
	v_add_f32_e32 v88, v45, v41
	v_sub_f32_e32 v41, v45, v41
	v_mul_f32_e32 v61, v51, v54
	v_mul_f32_e32 v51, v51, v37
	v_add_f32_e32 v103, v40, v36
	v_fma_f32 v64, -v37, v197, v64
	v_sub_f32_e32 v36, v40, v36
	v_add_f32_e32 v102, v48, v44
	v_fma_f32 v61, -v53, v37, v61
	v_fma_f32 v51, v53, v54, v51
	v_add_f32_e32 v53, v60, v49
	v_sub_f32_e32 v49, v60, v49
	v_sub_f32_e32 v60, v65, v93
	v_mul_f32_e32 v65, v54, v197
	v_add_f32_e32 v93, v43, v39
	v_sub_f32_e32 v39, v43, v39
	v_sub_f32_e32 v40, v55, v62
	v_mul_f32_e32 v86, v49, v64
	v_fma_f32 v65, v37, v177, v65
	v_mul_f32_e32 v49, v49, v65
	v_fma_f32 v86, -v60, v65, v86
	v_fma_f32 v49, v60, v64, v49
	v_add_f32_e32 v60, v63, v91
	v_sub_f32_e32 v63, v63, v91
	v_add_f32_e32 v91, v87, v67
	v_mul_f32_e32 v45, v63, v54
	v_fma_f32 v90, -v41, v37, v45
	v_mul_f32_e32 v45, v63, v37
	v_fma_f32 v63, v41, v54, v45
	v_sub_f32_e32 v41, v87, v67
	v_add_f32_e32 v45, v88, v93
	v_mul_f32_e32 v43, v41, v64
	v_mul_f32_e32 v41, v41, v65
	v_fma_f32 v67, -v39, v65, v43
	v_fma_f32 v87, v39, v64, v41
	v_sub_f32_e32 v39, v47, v58
	v_sub_f32_e32 v41, v94, v59
	v_add_f32_e32 v94, v66, v56
	v_sub_f32_e32 v47, v60, v91
	v_mul_f32_e32 v43, v39, v54
	v_mul_f32_e32 v39, v39, v37
	v_fma_f32 v59, v41, v54, v39
	v_sub_f32_e32 v39, v66, v56
	v_fma_f32 v58, -v41, v37, v43
	v_sub_f32_e32 v41, v89, v57
	v_sub_f32_e32 v56, v96, v97
	v_mul_f32_e32 v43, v39, v64
	v_mul_f32_e32 v39, v39, v65
	v_fma_f32 v89, v41, v64, v39
	v_sub_f32_e32 v39, v50, v46
	v_fma_f32 v66, -v41, v65, v43
	v_sub_f32_e32 v43, v61, v86
	v_mul_f32_e32 v41, v39, v54
	v_mul_f32_e32 v39, v39, v37
	v_add_f32_e32 v57, v59, v89
	v_sub_f32_e32 v59, v59, v89
	v_fma_f32 v100, -v38, v37, v41
	v_fma_f32 v101, v38, v54, v39
	v_sub_f32_e32 v38, v48, v44
	v_sub_f32_e32 v44, v51, v49
	v_sub_f32_e32 v48, v88, v93
	v_add_f32_e32 v41, v51, v49
	v_add_f32_e32 v49, v63, v87
	v_sub_f32_e32 v51, v90, v67
	v_mul_f32_e32 v39, v38, v64
	v_mul_f32_e32 v38, v38, v65
	v_fma_f32 v104, -v36, v65, v39
	v_fma_f32 v105, v36, v64, v38
	v_mul_f32_e32 v36, v54, v54
	v_sub_f32_e32 v39, v52, v53
	v_sub_f32_e32 v64, v99, v103
	v_fma_f32 v106, -v37, v37, v36
	v_mul_f32_e32 v36, v54, v37
	v_add_f32_e32 v65, v101, v105
	v_fma_f32 v107, v37, v54, v36
	v_add_f32_e32 v37, v55, v62
; template <int R, bool UNIT> __device__ __forceinline__ void dif_regs(f32x2* v, f32x2 wb) {
;     float k1 = 0.92387953251128674f, k2 = 0.70710678118654752f, k3 = 0.38268343236508977f; asm volatile("" : "+v"(k1), "+v"(k2), "+v"(k3));
; #pragma unroll
;     for (int t = 0; t < R; ++t) { constexpr int dummy = 0; (void)dummy; const int half = 1 << (R - 1 - t);
; #pragma unroll
;         for (int k = 0; k < (1 << R); ++k) if (!(k & half)) { const int kk = k & (half - 1), m = kk * (8 / half);
;             const f32x2 a = v[k], b = v[k + half]; v[k] = cadd(a, b); const f32x2 d = csub(a, b);
;             if (UNIT) { v[k + half] = (m == 0) ? d : (m == 4) ? (f32x2){d.y, -d.x} : cmul(d, CW16(m)); }
;             else { const f32x2 tw = (m == 0) ? wb : cmul(wb, CW16(m)); v[k + half] = cmul(d, tw); } }
;         if (!UNIT) wb = cmul(wb, wb); }
; }
; template <int R> __device__ __forceinline__ void dif_pass_rt(LAS f32x2* X, int sl, const f32x2 wb_in, int tid) {
;     float wbx = wb_in.x, wby = wb_in.y; asm volatile("" : "+v"(wbx), "+v"(wby)); const f32x2 wb = {wbx, wby};
;     const int r = tid & ((1 << sl) - 1), base = ((tid >> sl) << (sl + R)) + r;
;     LAS f32x2* Xb = X + PADI(base); f32x2 v[1 << R];
; #pragma unroll
;     for (int k = 0; k < (1 << R); ++k) v[k] = Xb[(k << sl) + ((k << sl) >> 4)];
;     dif_regs<R, false>(v, wb);
; #pragma unroll
;     for (int k = 0; k < (1 << R); ++k) Xb[(k << sl) + ((k << sl) >> 4)] = v[k];
; }
; template <int R> __device__ __forceinline__ void dit_pass_rt(LAS f32x2* X, int sl, const f32x2 wb_in, int tid) {
;     float wbx = wb_in.x, wby = wb_in.y; asm volatile("" : "+v"(wbx), "+v"(wby)); const f32x2 wbig = {wbx, wby};
;     const int r = tid & ((1 << sl) - 1), base = ((tid >> sl) << (sl + R)) + r;
;     LAS f32x2* Xb = X + PADI(base); f32x2 v[1 << R];
; #pragma unroll
;     for (int k = 0; k < (1 << R); ++k) v[k] = Xb[(k << sl) + ((k << sl) >> 4)];
;     dit_regs<R, false>(v, wbig);
; #pragma unroll
;     for (int k = 0; k < (1 << R); ++k) Xb[(k << sl) + ((k << sl) >> 4)] = v[k];
; }
; template <int NPT> __device__ __forceinline__ void fwd2_to_lds(LAS f32x2* Xe, LAS f32x2* Xo, const f32x2* tw, int tid, f32x2* ve, f32x2* vo) {
;     constexpr int R = NPT == 16 ? 4 : 3;
;     asm volatile("" : "+v"(tid)); __syncthreads();
;     { LAS f32x2* Pe = Xe + PADI(tid); LAS f32x2* Po = Xo + PADI(tid);
; #pragma unroll
	v_mul_f32_e32 v42, v43, v106
	v_sub_f32_e32 v55, v95, v94
	v_mul_f32_e32 v46, v47, v106
	v_add_f32_e32 v36, v52, v53
	v_mul_f32_e32 v43, v43, v107
	v_mul_f32_e32 v47, v47, v107
	v_fma_f32 v42, -v44, v107, v42
	v_mul_f32_e32 v54, v55, v106
	v_mul_f32_e32 v55, v55, v107
	v_mul_f32_e32 v38, v39, v106
	v_fma_f32 v43, v44, v106, v43
	v_add_f32_e32 v44, v60, v91
	v_sub_f32_e32 v60, v58, v66
	v_mul_f32_e32 v39, v39, v107
	v_fma_f32 v46, -v48, v107, v46
	v_fma_f32 v47, v48, v106, v47
	v_add_f32_e32 v48, v90, v67
	v_sub_f32_e32 v52, v63, v87
	v_fma_f32 v54, -v56, v107, v54
	v_fma_f32 v55, v56, v106, v55
	v_add_f32_e32 v56, v58, v66
	v_mul_f32_e32 v58, v60, v106
	v_mul_f32_e32 v60, v60, v107
	v_sub_f32_e32 v63, v98, v102
	v_sub_f32_e32 v67, v100, v104
	v_fma_f32 v38, -v40, v107, v38
	v_fma_f32 v39, v40, v106, v39
	v_add_f32_e32 v40, v61, v86
	v_mul_f32_e32 v50, v51, v106
	v_mul_f32_e32 v51, v51, v107
	v_fma_f32 v58, -v59, v107, v58
	v_fma_f32 v59, v59, v106, v60
	v_add_f32_e32 v60, v98, v102
	v_add_f32_e32 v61, v99, v103
	v_mul_f32_e32 v62, v63, v106
	v_mul_f32_e32 v63, v63, v107
	v_mul_f32_e32 v66, v67, v106
	v_mul_f32_e32 v67, v67, v107
	v_fma_f32 v50, -v52, v107, v50
	v_fma_f32 v51, v52, v106, v51
	v_add_f32_e32 v52, v95, v94
	v_add_f32_e32 v53, v96, v97
	v_fma_f32 v62, -v64, v107, v62
	v_fma_f32 v63, v64, v106, v63
	v_add_f32_e32 v64, v100, v104
	v_sub_f32_e32 v86, v101, v105
	v_fma_f32 v66, -v86, v107, v66
	v_fma_f32 v67, v86, v106, v67
	ds_write_b64 v70, v[36:37]
	ds_write_b64 v71, v[38:39]
	ds_write_b64 v72, v[40:41]
	ds_write_b64 v73, v[42:43]
	ds_write_b64 v74, v[44:45]
	ds_write_b64 v75, v[46:47]
	ds_write_b64 v76, v[48:49]
	ds_write_b64 v77, v[50:51]
	ds_write_b64 v78, v[52:53]
	ds_write_b64 v79, v[54:55]
	ds_write_b64 v80, v[56:57]
	ds_write_b64 v81, v[58:59]
	ds_write_b64 v82, v[60:61]
	ds_write_b64 v83, v[62:63]
	ds_write_b64 v84, v[64:65]
	ds_write_b64 v85, v[66:67]
	ds_read_b64 v[60:61], v68
	ds_read_b64 v[58:59], v69
	v_add_u32_e32 v70, s7, v68
	v_add_u32_e32 v71, s10, v68
	v_add_u32_e32 v76, s27, v68
	v_add_u32_e32 v77, s30, v68
	v_add_u32_e32 v78, s38, v68
	v_add_u32_e32 v79, s39, v68
	ds_read_b64 v[54:55], v70
	ds_read_b64 v[50:51], v71
	ds_read_b64 v[66:67], v76
	ds_read_b64 v[64:65], v77
	ds_read_b64 v[62:63], v78
	ds_read_b64 v[56:57], v79
	s_waitcnt lgkmcnt(3)
	v_add_f32_e32 v90, v60, v66
	v_sub_f32_e32 v60, v60, v66
	v_add_u32_e32 v72, s11, v68
	v_add_u32_e32 v73, s24, v68
	v_add_u32_e32 v74, s25, v68
	v_add_u32_e32 v75, s26, v68
	v_add_u32_e32 v80, s55, v68
	v_add_u32_e32 v81, s64, v68
	v_add_u32_e32 v82, s65, v68
	v_add_u32_e32 v83, s80, v68
	v_mov_b32_e32 v84, 0x3f3504f3
	v_mov_b32_e32 v85, 0x3f6c835e
	v_mov_b32_e32 v86, 0x3ec3ef15
	v_add_f32_e32 v91, v61, v67
	v_sub_f32_e32 v61, v61, v67
	v_mul_f32_e32 v66, v60, v34
	v_mul_f32_e32 v60, v60, v35
	ds_read_b64 v[46:47], v72
	ds_read_b64 v[40:41], v73
	ds_read_b64 v[38:39], v74
	ds_read_b64 v[36:37], v75
	ds_read_b64 v[52:53], v80
	ds_read_b64 v[48:49], v81
	ds_read_b64 v[44:45], v82
	ds_read_b64 v[42:43], v83
	v_fma_f32 v66, -v61, v35, v66
	v_fma_f32 v60, v61, v34, v60
	s_waitcnt lgkmcnt(10)
	v_add_f32_e32 v61, v58, v64
	v_sub_f32_e32 v58, v58, v64
	v_add_f32_e32 v67, v59, v65
	v_mul_f32_e32 v64, v34, v85
	v_xor_b32_e32 v87, 0x80000000, v86
	v_xor_b32_e32 v88, 0x80000000, v85
	v_sub_f32_e32 v59, v59, v65
	v_fma_f32 v64, -v35, v87, v64
	v_mul_f32_e32 v65, v34, v87
	v_xor_b32_e32 v89, 0x80000000, v84
	v_fma_f32 v85, v35, v85, v65
	v_mul_f32_e32 v93, v58, v64
	v_mul_f32_e32 v58, v58, v85
	v_fma_f32 v93, -v59, v85, v93
	v_fma_f32 v58, v59, v64, v58
	s_waitcnt lgkmcnt(9)
	v_add_f32_e32 v59, v54, v62
	v_sub_f32_e32 v54, v54, v62
	v_mul_f32_e32 v62, v34, v84
	v_add_f32_e32 v64, v55, v63
	v_sub_f32_e32 v55, v55, v63
	v_mul_f32_e32 v63, v34, v89
	v_fma_f32 v62, -v35, v89, v62
	v_fma_f32 v85, v35, v84, v63
	v_mul_f32_e32 v94, v54, v62
	v_mul_f32_e32 v54, v54, v85
	v_fma_f32 v94, -v55, v85, v94
	v_fma_f32 v54, v55, v62, v54
	s_waitcnt lgkmcnt(8)
	v_add_f32_e32 v55, v50, v56
	v_sub_f32_e32 v50, v50, v56
	v_mul_f32_e32 v56, v34, v86
	v_add_f32_e32 v62, v51, v57
	v_sub_f32_e32 v51, v51, v57
	v_mul_f32_e32 v57, v34, v88
	v_fma_f32 v56, -v35, v88, v56
	v_fma_f32 v85, v35, v86, v57
	v_mul_f32_e32 v86, v50, v56
	v_mul_f32_e32 v50, v50, v85
	v_fma_f32 v86, -v51, v85, v86
	v_fma_f32 v50, v51, v56, v50
	s_waitcnt lgkmcnt(3)
	v_add_f32_e32 v51, v46, v52
	v_add_f32_e32 v56, v47, v53
	v_sub_f32_e32 v46, v46, v52
	v_sub_f32_e32 v47, v47, v53
	v_mul_f32_e32 v52, v34, v177
	v_mul_f32_e32 v53, v34, v197
	v_fma_f32 v52, -v35, v197, v52
	v_fma_f32 v53, v35, v177, v53
	v_mul_f32_e32 v85, v46, v52
	v_mul_f32_e32 v46, v46, v53
	v_fma_f32 v85, -v47, v53, v85
	v_fma_f32 v46, v47, v52, v46
	s_waitcnt lgkmcnt(2)
	v_add_f32_e32 v47, v40, v48
	v_sub_f32_e32 v40, v40, v48
	v_add_f32_e32 v52, v41, v49
	v_sub_f32_e32 v41, v41, v49
	v_fma_f32 v48, -v35, v88, v65
	v_fma_f32 v49, v35, v87, v57
	v_mul_f32_e32 v53, v40, v48
	v_mul_f32_e32 v40, v40, v49
	v_fma_f32 v53, -v41, v49, v53
	v_fma_f32 v40, v41, v48, v40
	s_waitcnt lgkmcnt(1)
	v_add_f32_e32 v41, v38, v44
	v_sub_f32_e32 v38, v38, v44
	v_add_f32_e32 v48, v39, v45
	v_sub_f32_e32 v39, v39, v45
	v_fma_f32 v44, -v35, v89, v63
	v_fma_f32 v45, v35, v89, v63
	v_mul_f32_e32 v49, v38, v44
	v_mul_f32_e32 v38, v38, v45
	v_fma_f32 v49, -v39, v45, v49
	v_fma_f32 v38, v39, v44, v38
	s_waitcnt lgkmcnt(0)
; template <int R, bool UNIT> __device__ __forceinline__ void dif_regs(f32x2* v, f32x2 wb) {
;     float k1 = 0.92387953251128674f, k2 = 0.70710678118654752f, k3 = 0.38268343236508977f; asm volatile("" : "+v"(k1), "+v"(k2), "+v"(k3));
; #pragma unroll
;     for (int t = 0; t < R; ++t) { constexpr int dummy = 0; (void)dummy; const int half = 1 << (R - 1 - t);
; #pragma unroll
;         for (int k = 0; k < (1 << R); ++k) if (!(k & half)) { const int kk = k & (half - 1), m = kk * (8 / half);
;             const f32x2 a = v[k], b = v[k + half]; v[k] = cadd(a, b); const f32x2 d = csub(a, b);
;             if (UNIT) { v[k + half] = (m == 0) ? d : (m == 4) ? (f32x2){d.y, -d.x} : cmul(d, CW16(m)); }
;             else { const f32x2 tw = (m == 0) ? wb : cmul(wb, CW16(m)); v[k + half] = cmul(d, tw); } }
;         if (!UNIT) wb = cmul(wb, wb); }
; }
; template <int R> __device__ __forceinline__ void dif_pass_rt(LAS f32x2* X, int sl, const f32x2 wb_in, int tid) {
;     float wbx = wb_in.x, wby = wb_in.y; asm volatile("" : "+v"(wbx), "+v"(wby)); const f32x2 wb = {wbx, wby};
;     const int r = tid & ((1 << sl) - 1), base = ((tid >> sl) << (sl + R)) + r;
;     LAS f32x2* Xb = X + PADI(base); f32x2 v[1 << R];
; #pragma unroll
;     for (int k = 0; k < (1 << R); ++k) v[k] = Xb[(k << sl) + ((k << sl) >> 4)];
;     dif_regs<R, false>(v, wb);
; #pragma unroll
;     for (int k = 0; k < (1 << R); ++k) Xb[(k << sl) + ((k << sl) >> 4)] = v[k];
; }
; template <int R> __device__ __forceinline__ void dit_pass_rt(LAS f32x2* X, int sl, const f32x2 wb_in, int tid) {
;     float wbx = wb_in.x, wby = wb_in.y; asm volatile("" : "+v"(wbx), "+v"(wby)); const f32x2 wbig = {wbx, wby};
;     const int r = tid & ((1 << sl) - 1), base = ((tid >> sl) << (sl + R)) + r;
;     LAS f32x2* Xb = X + PADI(base); f32x2 v[1 << R];
; #pragma unroll
;     for (int k = 0; k < (1 << R); ++k) v[k] = Xb[(k << sl) + ((k << sl) >> 4)];
;     dit_regs<R, false>(v, wbig);
; #pragma unroll
;     for (int k = 0; k < (1 << R); ++k) Xb[(k << sl) + ((k << sl) >> 4)] = v[k];
; }
; template <int NPT> __device__ __forceinline__ void fwd2_to_lds(LAS f32x2* Xe, LAS f32x2* Xo, const f32x2* tw, int tid, f32x2* ve, f32x2* vo) {
;     constexpr int R = NPT == 16 ? 4 : 3;
;     asm volatile("" : "+v"(tid)); __syncthreads();
;     { LAS f32x2* Pe = Xe + PADI(tid); LAS f32x2* Po = Xo + PADI(tid);
; #pragma unroll
	v_add_f32_e32 v39, v36, v42
	v_sub_f32_e32 v36, v36, v42
	v_add_f32_e32 v44, v37, v43
	v_sub_f32_e32 v37, v37, v43
	v_fma_f32 v42, -v35, v87, v57
	v_fma_f32 v43, v35, v88, v65
	v_add_f32_e32 v57, v67, v52
	v_sub_f32_e32 v52, v67, v52
	v_add_f32_e32 v88, v62, v44
	v_sub_f32_e32 v44, v62, v44
	v_mul_f32_e32 v45, v36, v42
	v_mul_f32_e32 v36, v36, v43
	v_fma_f32 v45, -v37, v43, v45
	v_fma_f32 v36, v37, v42, v36
	v_mul_f32_e32 v37, v34, v34
	v_mul_f32_e32 v42, v34, v35
	v_sub_f32_e32 v43, v90, v51
	v_fma_f32 v37, -v35, v35, v37
	v_fma_f32 v34, v35, v34, v42
	v_add_f32_e32 v35, v90, v51
	v_add_f32_e32 v42, v91, v56
	v_sub_f32_e32 v51, v91, v56
	v_mul_f32_e32 v56, v43, v37
	v_mul_f32_e32 v43, v43, v34
	v_mul_f32_e32 v63, v37, v89
	v_fma_f32 v56, -v51, v34, v56
	v_fma_f32 v43, v51, v37, v43
	v_add_f32_e32 v51, v61, v47
	v_sub_f32_e32 v47, v61, v47
	v_mul_f32_e32 v61, v37, v84
	v_fma_f32 v65, v34, v84, v63
	v_add_f32_e32 v84, v64, v48
	v_sub_f32_e32 v48, v64, v48
	v_mul_f32_e32 v64, v37, v197
	v_fma_f32 v62, v34, v89, v63
	v_fma_f32 v61, -v34, v89, v61
	v_mul_f32_e32 v67, v47, v61
	v_mul_f32_e32 v47, v47, v65
	v_fma_f32 v64, v34, v177, v64
	v_fma_f32 v67, -v52, v65, v67
	v_fma_f32 v47, v52, v61, v47
	v_add_f32_e32 v52, v59, v41
	v_sub_f32_e32 v41, v59, v41
	v_mul_f32_e32 v59, v37, v177
	v_fma_f32 v59, -v34, v197, v59
	v_mul_f32_e32 v87, v41, v59
	v_mul_f32_e32 v41, v41, v64
	v_fma_f32 v87, -v48, v64, v87
	v_fma_f32 v41, v48, v59, v41
	v_add_f32_e32 v48, v55, v39
	v_sub_f32_e32 v39, v55, v39
	v_fma_f32 v55, -v34, v89, v63
	v_add_f32_e32 v89, v60, v46
	v_sub_f32_e32 v46, v60, v46
	v_mul_f32_e32 v63, v39, v55
	v_mul_f32_e32 v39, v39, v62
	v_fma_f32 v63, -v44, v62, v63
	v_fma_f32 v39, v44, v55, v39
	v_add_f32_e32 v44, v66, v85
	v_sub_f32_e32 v66, v66, v85
	v_add_f32_e32 v85, v58, v40
	v_sub_f32_e32 v40, v58, v40
	v_mul_f32_e32 v60, v66, v37
	v_mul_f32_e32 v66, v66, v34
	v_add_f32_e32 v90, v47, v39
	v_sub_f32_e32 v39, v47, v39
	v_fma_f32 v60, -v46, v34, v60
	v_fma_f32 v46, v46, v37, v66
	v_add_f32_e32 v66, v93, v53
	v_sub_f32_e32 v53, v93, v53
	v_mul_f32_e32 v58, v53, v61
	v_mul_f32_e32 v53, v53, v65
	v_fma_f32 v58, -v40, v65, v58
	v_fma_f32 v40, v40, v61, v53
	v_add_f32_e32 v53, v94, v49
	v_sub_f32_e32 v49, v94, v49
	v_add_f32_e32 v61, v54, v38
	v_sub_f32_e32 v38, v54, v38
	v_mul_f32_e32 v54, v49, v59
	v_mul_f32_e32 v49, v49, v64
	v_add_f32_e32 v93, v89, v61
	v_add_f32_e32 v91, v44, v53
	v_fma_f32 v54, -v38, v64, v54
	v_fma_f32 v38, v38, v59, v49
	v_add_f32_e32 v49, v86, v45
	v_sub_f32_e32 v45, v86, v45
	v_add_f32_e32 v59, v50, v36
	v_sub_f32_e32 v36, v50, v36
	v_add_f32_e32 v64, v57, v88
	v_add_f32_e32 v86, v43, v41
	v_sub_f32_e32 v41, v43, v41
	v_mul_f32_e32 v50, v45, v55
	v_mul_f32_e32 v45, v45, v62
	v_add_f32_e32 v94, v85, v59
	v_add_f32_e32 v95, v46, v38
	v_sub_f32_e32 v38, v46, v38
	v_sub_f32_e32 v46, v86, v90
	v_fma_f32 v50, -v36, v62, v50
	v_fma_f32 v36, v36, v55, v45
	v_mul_f32_e32 v45, v37, v37
	v_mul_f32_e32 v55, v37, v34
	v_add_f32_e32 v62, v51, v48
	v_fma_f32 v45, -v34, v34, v45
	v_fma_f32 v34, v34, v37, v55
	v_add_f32_e32 v37, v35, v52
	v_sub_f32_e32 v35, v35, v52
	v_add_f32_e32 v55, v42, v84
	v_sub_f32_e32 v42, v42, v84
	v_add_f32_e32 v84, v56, v87
	v_add_f32_e32 v98, v40, v36
	v_sub_f32_e32 v36, v40, v36
	v_mul_f32_e32 v52, v35, v45
	v_mul_f32_e32 v35, v35, v34
	v_fma_f32 v52, -v42, v34, v52
	v_fma_f32 v42, v42, v45, v35
	v_sub_f32_e32 v35, v51, v48
	v_sub_f32_e32 v48, v57, v88
	v_mul_f32_e32 v51, v45, v177
	v_mul_f32_e32 v57, v45, v197
	v_add_f32_e32 v88, v67, v63
	v_fma_f32 v51, -v34, v197, v51
	v_fma_f32 v57, v34, v177, v57
	v_mul_f32_e32 v65, v35, v51
	v_mul_f32_e32 v35, v35, v57
	v_fma_f32 v65, -v48, v57, v65
	v_fma_f32 v48, v48, v51, v35
	v_sub_f32_e32 v35, v56, v87
	v_mul_f32_e32 v43, v35, v45
	v_mul_f32_e32 v35, v35, v34
	v_fma_f32 v87, v41, v45, v35
	v_sub_f32_e32 v35, v67, v63
	v_fma_f32 v56, -v41, v34, v43
	v_add_f32_e32 v43, v86, v90
	v_mul_f32_e32 v41, v35, v51
	v_mul_f32_e32 v35, v35, v57
	v_fma_f32 v67, v39, v51, v35
	v_sub_f32_e32 v35, v44, v53
	v_fma_f32 v63, -v39, v57, v41
	v_sub_f32_e32 v39, v89, v61
	v_add_f32_e32 v53, v66, v49
	v_mul_f32_e32 v41, v35, v45
	v_mul_f32_e32 v35, v35, v34
	v_add_f32_e32 v47, v87, v67
	v_fma_f32 v89, v39, v45, v35
	v_sub_f32_e32 v35, v66, v49
	v_fma_f32 v61, -v39, v34, v41
	v_sub_f32_e32 v39, v85, v59
	v_sub_f32_e32 v49, v56, v63
	v_add_f32_e32 v85, v60, v54
	v_mul_f32_e32 v41, v35, v51
	v_mul_f32_e32 v35, v35, v57
	v_fma_f32 v66, v39, v51, v35
	v_sub_f32_e32 v35, v60, v54
	v_fma_f32 v59, -v39, v57, v41
	v_add_f32_e32 v60, v58, v50
	v_sub_f32_e32 v41, v52, v65
	v_sub_f32_e32 v54, v93, v94
	v_mul_f32_e32 v39, v35, v45
	v_mul_f32_e32 v35, v35, v34
	v_fma_f32 v97, v38, v45, v35
	v_sub_f32_e32 v35, v58, v50
	v_fma_f32 v96, -v38, v34, v39
	v_add_f32_e32 v39, v42, v48
	v_sub_f32_e32 v42, v42, v48
	v_sub_f32_e32 v50, v87, v67
	v_sub_f32_e32 v58, v89, v66
	v_mul_f32_e32 v38, v35, v51
	v_mul_f32_e32 v35, v35, v57
	v_fma_f32 v100, v36, v51, v35
	v_mul_f32_e32 v35, v45, v45
	v_fma_f32 v99, -v36, v57, v38
	v_sub_f32_e32 v38, v55, v64
	v_sub_f32_e32 v57, v61, v59
	v_add_f32_e32 v51, v93, v94
	v_fma_f32 v101, -v34, v34, v35
	v_mul_f32_e32 v35, v45, v34
	v_fma_f32 v102, v34, v45, v35
	v_add_f32_e32 v34, v37, v62
	v_sub_f32_e32 v37, v37, v62
	v_mul_f32_e32 v48, v49, v101
	v_sub_f32_e32 v45, v84, v88
	v_add_f32_e32 v35, v55, v64
	v_mul_f32_e32 v49, v49, v102
	v_mul_f32_e32 v40, v41, v101
	v_mul_f32_e32 v36, v37, v101
	v_mul_f32_e32 v37, v37, v102
	v_fma_f32 v48, -v50, v102, v48
	v_mul_f32_e32 v44, v45, v101
	v_fma_f32 v49, v50, v101, v49
	v_add_f32_e32 v50, v91, v53
	v_sub_f32_e32 v53, v91, v53
; template <int R, bool UNIT> __device__ __forceinline__ void dif_regs(f32x2* v, f32x2 wb) {
;     float k1 = 0.92387953251128674f, k2 = 0.70710678118654752f, k3 = 0.38268343236508977f; asm volatile("" : "+v"(k1), "+v"(k2), "+v"(k3));
; #pragma unroll
;     for (int t = 0; t < R; ++t) { constexpr int dummy = 0; (void)dummy; const int half = 1 << (R - 1 - t);
; #pragma unroll
;         for (int k = 0; k < (1 << R); ++k) if (!(k & half)) { const int kk = k & (half - 1), m = kk * (8 / half);
;             const f32x2 a = v[k], b = v[k + half]; v[k] = cadd(a, b); const f32x2 d = csub(a, b);
;             if (UNIT) { v[k + half] = (m == 0) ? d : (m == 4) ? (f32x2){d.y, -d.x} : cmul(d, CW16(m)); }
;             else { const f32x2 tw = (m == 0) ? wb : cmul(wb, CW16(m)); v[k + half] = cmul(d, tw); } }
;         if (!UNIT) wb = cmul(wb, wb); }
; }
; template <int R> __device__ __forceinline__ void dif_pass_rt(LAS f32x2* X, int sl, const f32x2 wb_in, int tid) {
;     float wbx = wb_in.x, wby = wb_in.y; asm volatile("" : "+v"(wbx), "+v"(wby)); const f32x2 wb = {wbx, wby};
;     const int r = tid & ((1 << sl) - 1), base = ((tid >> sl) << (sl + R)) + r;
;     LAS f32x2* Xb = X + PADI(base); f32x2 v[1 << R];
; #pragma unroll
;     for (int k = 0; k < (1 << R); ++k) v[k] = Xb[(k << sl) + ((k << sl) >> 4)];
;     dif_regs<R, false>(v, wb);
; #pragma unroll
;     for (int k = 0; k < (1 << R); ++k) Xb[(k << sl) + ((k << sl) >> 4)] = v[k];
; }
; template <int R> __device__ __forceinline__ void dit_pass_rt(LAS f32x2* X, int sl, const f32x2 wb_in, int tid) {
;     float wbx = wb_in.x, wby = wb_in.y; asm volatile("" : "+v"(wbx), "+v"(wby)); const f32x2 wbig = {wbx, wby};
;     const int r = tid & ((1 << sl) - 1), base = ((tid >> sl) << (sl + R)) + r;
;     LAS f32x2* Xb = X + PADI(base); f32x2 v[1 << R];
; #pragma unroll
;     for (int k = 0; k < (1 << R); ++k) v[k] = Xb[(k << sl) + ((k << sl) >> 4)];
;     dit_regs<R, false>(v, wbig);
; #pragma unroll
;     for (int k = 0; k < (1 << R); ++k) Xb[(k << sl) + ((k << sl) >> 4)] = v[k];
; }
; template <int NPT> __device__ __forceinline__ void fwd2_to_lds(LAS f32x2* Xe, LAS f32x2* Xo, const f32x2* tw, int tid, f32x2* ve, f32x2* vo) {
;     constexpr int R = NPT == 16 ? 4 : 3;
;     asm volatile("" : "+v"(tid)); __syncthreads();
;     { LAS f32x2* Pe = Xe + PADI(tid); LAS f32x2* Po = Xo + PADI(tid);
; #pragma unroll
	v_fma_f32 v36, -v38, v102, v36
	v_fma_f32 v37, v38, v101, v37
	v_add_f32_e32 v38, v52, v65
	v_mul_f32_e32 v45, v45, v102
	v_fma_f32 v44, -v46, v102, v44
	v_mul_f32_e32 v52, v53, v101
	v_mul_f32_e32 v53, v53, v102
	v_sub_f32_e32 v65, v96, v99
	v_mul_f32_e32 v41, v41, v102
	v_fma_f32 v45, v46, v101, v45
	v_add_f32_e32 v46, v56, v63
	v_fma_f32 v52, -v54, v102, v52
	v_fma_f32 v53, v54, v101, v53
	v_add_f32_e32 v54, v61, v59
	v_mul_f32_e32 v56, v57, v101
	v_mul_f32_e32 v57, v57, v102
	v_sub_f32_e32 v61, v85, v60
	v_sub_f32_e32 v62, v95, v98
	v_mul_f32_e32 v64, v65, v101
	v_mul_f32_e32 v65, v65, v102
	v_fma_f32 v56, -v58, v102, v56
	v_fma_f32 v57, v58, v101, v57
	v_add_f32_e32 v58, v85, v60
	v_mul_f32_e32 v60, v61, v101
	v_mul_f32_e32 v61, v61, v102
	v_fma_f32 v40, -v42, v102, v40
	v_fma_f32 v41, v42, v101, v41
	v_add_f32_e32 v42, v84, v88
	v_add_f32_e32 v55, v89, v66
	v_add_f32_e32 v59, v95, v98
	v_fma_f32 v60, -v62, v102, v60
	v_fma_f32 v61, v62, v101, v61
	v_add_f32_e32 v62, v96, v99
	v_add_f32_e32 v63, v97, v100
	v_sub_f32_e32 v66, v97, v100
	v_fma_f32 v64, -v66, v102, v64
	v_fma_f32 v65, v66, v101, v65
	ds_write_b64 v68, v[34:35]
	ds_write_b64 v69, v[36:37]
	ds_write_b64 v70, v[38:39]
	ds_write_b64 v71, v[40:41]
	ds_write_b64 v72, v[42:43]
	ds_write_b64 v73, v[44:45]
	ds_write_b64 v74, v[46:47]
	ds_write_b64 v75, v[48:49]
	ds_write_b64 v76, v[50:51]
	ds_write_b64 v77, v[52:53]
	ds_write_b64 v78, v[54:55]
	ds_write_b64 v79, v[56:57]
	ds_write_b64 v80, v[58:59]
	ds_write_b64 v81, v[60:61]
	ds_write_b64 v82, v[62:63]
	ds_write_b64 v83, v[64:65]
	s_waitcnt lgkmcnt(0)
	s_barrier
	s_cbranch_scc1 .LBB0_688
; #define LAS __attribute__((address_space(3)))
; __device__ __forceinline__ f32x2 cadd(f32x2 a, f32x2 b) { return (f32x2){fadd_(a.x, b.x), fadd_(a.y, b.y)}; }
; __device__ __forceinline__ f32x2 csub(f32x2 a, f32x2 b) { return (f32x2){fsub_(a.x, b.x), fsub_(a.y, b.y)}; }
; __device__ __forceinline__ f32x2 cscale(f32x2 a, float s) { return (f32x2){fmul_(a.x, s), fmul_(a.y, s)}; }
; template <int NPT> __device__ __forceinline__ void mid_spectrum(const LAS f32x2* X, int tid, f32x2* K, float sc) {
;     if (NPT == 16) {
; #pragma unroll
;         for (int u = 0; u < 8; ++u) { const LAS f32x2* Xb = X + PADI(2 * tid) + 1088 * u; const f32x2 a = Xb[0], b = Xb[1]; K[2 * u] = cscale(cadd(a, b), sc); K[2 * u + 1] = cscale(csub(a, b), sc); } }
; template <int NPT>
; __device__ __forceinline__ void hyena_unit(LAS unsigned char* lds, int ch, int rowbase, int nb, const float* H2, const float* w3, const float* bias, bf16_t* ST, const f32x2* T2, int tid_in) {
;     ...
;     for (int p = 0; p < nb / 2; ++p) {
;         bf16_t* s0 = ST + (size_t)(rowbase + 2 * p * N) * 512 + (size_t)ch * N; bf16_t* s1 = s0 + (size_t)N * 512;
	v_and_b32_e32 v38, -8, v32
	v_add_u32_e32 v34, 0, v38
	v_lshlrev_b32_e32 v39, 4, v32
	v_add_u32_e32 v120, v34, v39
	ds_read2_b64 v[34:37], v120 offset1:1
	s_waitcnt lgkmcnt(0)
	v_add_f32_e32 v40, v34, v36
	v_add_f32_e32 v41, v35, v37
	v_sub_f32_e32 v34, v34, v36
	v_sub_f32_e32 v35, v35, v37
	v_add_u32_e32 v125, 0x2200, v120
	v_mov_b32_e32 v42, 0x38800000
	v_mul_f32_e32 v123, v34, v42
	v_mul_f32_e32 v124, v35, v42
	ds_read2_b64 v[34:37], v125 offset1:1
	v_mul_f32_e32 v121, v40, v42
	v_mul_f32_e32 v122, v41, v42
	s_waitcnt lgkmcnt(0)
	v_add_f32_e32 v40, v34, v36
	v_add_f32_e32 v41, v35, v37
	v_sub_f32_e32 v34, v34, v36
	v_sub_f32_e32 v35, v35, v37
	v_add_u32_e32 v130, 0x4400, v120
	v_mul_f32_e32 v128, v34, v42
	v_mul_f32_e32 v129, v35, v42
	ds_read2_b64 v[34:37], v130 offset1:1
	v_mul_f32_e32 v126, v40, v42
	v_mul_f32_e32 v127, v41, v42
	s_waitcnt lgkmcnt(0)
	v_add_f32_e32 v40, v34, v36
	v_add_f32_e32 v41, v35, v37
	v_sub_f32_e32 v34, v34, v36
	v_sub_f32_e32 v35, v35, v37
	v_add_u32_e32 v135, 0x6600, v120
	v_mul_f32_e32 v133, v34, v42
	v_mul_f32_e32 v134, v35, v42
	ds_read2_b64 v[34:37], v135 offset1:1
	v_mul_f32_e32 v131, v40, v42
	v_mul_f32_e32 v132, v41, v42
	s_waitcnt lgkmcnt(0)
	v_add_f32_e32 v40, v34, v36
	v_add_f32_e32 v41, v35, v37
	v_sub_f32_e32 v34, v34, v36
	v_sub_f32_e32 v35, v35, v37
	v_add_u32_e32 v140, 0x8800, v120
	v_mul_f32_e32 v138, v34, v42
	v_mul_f32_e32 v139, v35, v42
	ds_read2_b64 v[34:37], v140 offset1:1
	v_mul_f32_e32 v136, v40, v42
	v_mul_f32_e32 v137, v41, v42
	s_waitcnt lgkmcnt(0)
	v_add_f32_e32 v40, v34, v36
	v_add_f32_e32 v41, v35, v37
	v_sub_f32_e32 v34, v34, v36
	v_sub_f32_e32 v35, v35, v37
	v_add_u32_e32 v145, 0xaa00, v120
	v_mul_f32_e32 v143, v34, v42
	v_mul_f32_e32 v144, v35, v42
	ds_read2_b64 v[34:37], v145 offset1:1
	v_mul_f32_e32 v141, v40, v42
	v_mul_f32_e32 v142, v41, v42
	s_waitcnt lgkmcnt(0)
	v_add_f32_e32 v40, v34, v36
	v_add_f32_e32 v41, v35, v37
	v_sub_f32_e32 v34, v34, v36
	v_sub_f32_e32 v35, v35, v37
	v_add_u32_e32 v150, 0xcc00, v120
	v_mul_f32_e32 v148, v34, v42
	v_mul_f32_e32 v149, v35, v42
	ds_read2_b64 v[34:37], v150 offset1:1
	v_mul_f32_e32 v146, v40, v42
	v_mul_f32_e32 v147, v41, v42
	s_waitcnt lgkmcnt(0)
	v_add_f32_e32 v40, v34, v36
	v_add_f32_e32 v41, v35, v37
	v_sub_f32_e32 v34, v34, v36
	v_sub_f32_e32 v35, v35, v37
	v_add_u32_e32 v155, 0xee00, v120
	v_mul_f32_e32 v153, v34, v42
	v_mul_f32_e32 v154, v35, v42
	ds_read2_b64 v[34:37], v155 offset1:1
	v_mul_f32_e32 v151, v40, v42
	s_waitcnt lgkmcnt(0)
	v_add_f32_e32 v40, v34, v36
	v_sub_f32_e32 v34, v34, v36
	v_mul_f32_e32 v152, v41, v42
	v_add_f32_e32 v41, v35, v37
	v_sub_f32_e32 v35, v35, v37
	s_lshl_b64 s[6:7], s[62:63], 14
	v_mul_f32_e32 v158, v34, v42
	v_add_u32_e32 v34, s2, v38
	v_add_u32_e32 v160, v34, v39
	v_mul_f32_e32 v159, v35, v42
	ds_read2_b64 v[34:37], v160 offset1:1
	s_waitcnt lgkmcnt(0)
	v_add_f32_e32 v38, v34, v36
	v_add_f32_e32 v39, v35, v37
	v_sub_f32_e32 v34, v34, v36
	v_sub_f32_e32 v35, v35, v37
	v_add_u32_e32 v165, 0x2200, v160
	v_mul_f32_e32 v163, v34, v42
	v_mul_f32_e32 v164, v35, v42
	ds_read2_b64 v[34:37], v165 offset1:1
	v_mul_f32_e32 v161, v38, v42
	v_mul_f32_e32 v162, v39, v42
	s_waitcnt lgkmcnt(0)
	v_add_f32_e32 v38, v34, v36
	v_add_f32_e32 v39, v35, v37
	v_sub_f32_e32 v34, v34, v36
	v_sub_f32_e32 v35, v35, v37
	v_add_u32_e32 v170, 0x4400, v160
	v_mul_f32_e32 v168, v34, v42
	v_mul_f32_e32 v169, v35, v42
	ds_read2_b64 v[34:37], v170 offset1:1
	v_mul_f32_e32 v166, v38, v42
	v_mul_f32_e32 v167, v39, v42
	s_waitcnt lgkmcnt(0)
	v_add_f32_e32 v38, v34, v36
	v_add_f32_e32 v39, v35, v37
	v_sub_f32_e32 v34, v34, v36
	v_sub_f32_e32 v35, v35, v37
	v_add_u32_e32 v175, 0x6600, v160
	v_mul_f32_e32 v173, v34, v42
	v_mul_f32_e32 v174, v35, v42
	ds_read2_b64 v[34:37], v175 offset1:1
	v_mul_f32_e32 v171, v38, v42
	v_mul_f32_e32 v172, v39, v42
	s_waitcnt lgkmcnt(0)
	v_add_f32_e32 v38, v34, v36
	v_add_f32_e32 v39, v35, v37
	v_sub_f32_e32 v34, v34, v36
	v_sub_f32_e32 v35, v35, v37
	v_add_u32_e32 v190, 0x8800, v160
	v_mul_f32_e32 v188, v34, v42
	v_mul_f32_e32 v189, v35, v42
	ds_read2_b64 v[34:37], v190 offset1:1
	v_mul_f32_e32 v186, v38, v42
	v_mul_f32_e32 v187, v39, v42
	s_waitcnt lgkmcnt(0)
	v_add_f32_e32 v38, v34, v36
	v_add_f32_e32 v39, v35, v37
	v_sub_f32_e32 v34, v34, v36
	v_sub_f32_e32 v35, v35, v37
	v_add_u32_e32 v203, 0xaa00, v160
	v_mul_f32_e32 v193, v34, v42
	v_mul_f32_e32 v202, v35, v42
	ds_read2_b64 v[34:37], v203 offset1:1
	v_mul_f32_e32 v191, v38, v42
	v_mul_f32_e32 v192, v39, v42
	s_waitcnt lgkmcnt(0)
	v_add_f32_e32 v38, v34, v36
	v_add_f32_e32 v39, v35, v37
	v_sub_f32_e32 v34, v34, v36
	v_sub_f32_e32 v35, v35, v37
	v_add_u32_e32 v208, 0xcc00, v160
	v_mul_f32_e32 v206, v34, v42
	v_mul_f32_e32 v207, v35, v42
	ds_read2_b64 v[34:37], v208 offset1:1
	v_mul_f32_e32 v204, v38, v42
	v_mul_f32_e32 v205, v39, v42
	s_waitcnt lgkmcnt(0)
	v_add_f32_e32 v38, v34, v36
	v_add_f32_e32 v39, v35, v37
	v_sub_f32_e32 v34, v34, v36
	v_sub_f32_e32 v35, v35, v37
	v_add_u32_e32 v213, 0xee00, v160
	v_mul_f32_e32 v211, v34, v42
	v_mul_f32_e32 v212, v35, v42
	ds_read2_b64 v[34:37], v213 offset1:1
	v_mul_f32_e32 v209, v38, v42
	s_waitcnt lgkmcnt(0)
	v_add_f32_e32 v38, v34, v36
	v_sub_f32_e32 v34, v34, v36
	s_add_u32 s3, s49, s6
	v_mul_f32_e32 v216, v34, v42
	v_ashrrev_i32_e32 v34, 4, v32
	v_add_lshl_u32 v34, v34, v32, 3
	s_addc_u32 s6, s54, s7
	v_add_u32_e32 v218, 0, v34
	v_add_u32_e32 v219, s2, v34
	s_mov_b32 s7, 0
	v_mul_f32_e32 v156, v40, v42
	v_mul_f32_e32 v157, v41, v42
	v_mul_f32_e32 v210, v39, v42
	v_add_f32_e32 v39, v35, v37
	v_mul_f32_e32 v214, v38, v42
	v_sub_f32_e32 v35, v35, v37
	v_mul_f32_e32 v215, v39, v42
	v_mul_f32_e32 v217, v35, v42

; template <int R, bool UNIT> __device__ __forceinline__ void dif_regs(f32x2* v, f32x2 wb) {
;     float k1 = 0.92387953251128674f, k2 = 0.70710678118654752f, k3 = 0.38268343236508977f; asm volatile("" : "+v"(k1), "+v"(k2), "+v"(k3));
; #pragma unroll
;     for (int t = 0; t < R; ++t) { constexpr int dummy = 0; (void)dummy; const int half = 1 << (R - 1 - t);
; #pragma unroll
;         for (int k = 0; k < (1 << R); ++k) if (!(k & half)) { const int kk = k & (half - 1), m = kk * (8 / half);
;             const f32x2 a = v[k], b = v[k + half]; v[k] = cadd(a, b); const f32x2 d = csub(a, b);
;             if (UNIT) { v[k + half] = (m == 0) ? d : (m == 4) ? (f32x2){d.y, -d.x} : cmul(d, CW16(m)); }
;             else { const f32x2 tw = (m == 0) ? wb : cmul(wb, CW16(m)); v[k + half] = cmul(d, tw); } }
;         if (!UNIT) wb = cmul(wb, wb); }
; }
; template <int R> __device__ __forceinline__ void dif_pass_rt(LAS f32x2* X, int sl, const f32x2 wb_in, int tid) {
;     float wbx = wb_in.x, wby = wb_in.y; asm volatile("" : "+v"(wbx), "+v"(wby)); const f32x2 wb = {wbx, wby};
;     const int r = tid & ((1 << sl) - 1), base = ((tid >> sl) << (sl + R)) + r;
;     LAS f32x2* Xb = X + PADI(base); f32x2 v[1 << R];
; #pragma unroll
;     for (int k = 0; k < (1 << R); ++k) v[k] = Xb[(k << sl) + ((k << sl) >> 4)];
;     dif_regs<R, false>(v, wb);
; #pragma unroll
;     for (int k = 0; k < (1 << R); ++k) Xb[(k << sl) + ((k << sl) >> 4)] = v[k];
; }
; template <int R> __device__ __forceinline__ void dit_pass_rt(LAS f32x2* X, int sl, const f32x2 wb_in, int tid) {
;     float wbx = wb_in.x, wby = wb_in.y; asm volatile("" : "+v"(wbx), "+v"(wby)); const f32x2 wbig = {wbx, wby};
;     const int r = tid & ((1 << sl) - 1), base = ((tid >> sl) << (sl + R)) + r;
;     LAS f32x2* Xb = X + PADI(base); f32x2 v[1 << R];
; #pragma unroll
;     for (int k = 0; k < (1 << R); ++k) v[k] = Xb[(k << sl) + ((k << sl) >> 4)];
;     dit_regs<R, false>(v, wbig);
; #pragma unroll
;     for (int k = 0; k < (1 << R); ++k) Xb[(k << sl) + ((k << sl) >> 4)] = v[k];
; }
; template <int NPT> __device__ __forceinline__ void fwd2_to_lds(LAS f32x2* Xe, LAS f32x2* Xo, const f32x2* tw, int tid, f32x2* ve, f32x2* vo) {
;     constexpr int R = NPT == 16 ? 4 : 3;
;     asm volatile("" : "+v"(tid)); __syncthreads();
;     { LAS f32x2* Pe = Xe + PADI(tid); LAS f32x2* Po = Xo + PADI(tid);
; #pragma unroll
.LBB0_691:
	s_cmp_eq_u32 s10, 1
	s_cselect_b32 s11, 5, 1
	s_cmp_lg_u32 s10, 0
	s_cselect_b32 s83, s11, 9
	s_sub_i32 s11, 10, s83
	v_lshlrev_b32_e32 v86, s11, v220
	v_and_b32_e32 v86, 0x3ff, v86
	v_lshlrev_b32_e32 v176, 3, v86
	v_lshl_add_u64 v[86:87], s[50:51], 0, v[176:177]
	global_load_dwordx2 v[86:87], v[86:87], off
	v_bfe_u32 v88, v220, 0, s83
	v_ashrrev_i32_e32 v89, s83, v220
	s_add_i32 s11, s83, 4
	v_lshl_add_u32 v88, v89, s11, v88
	s_lshl_b32 s11, 1, s83
	s_ashr_i32 s24, s11, 4
	s_lshl_b32 s11, s11, 3
	s_lshl_b32 s24, s24, 3
	s_add_i32 s11, s24, s11
	s_lshl_b32 s24, 2, s83
	s_ashr_i32 s25, s24, 4
	s_lshl_b32 s24, s24, 3
	s_lshl_b32 s25, s25, 3
	s_add_i32 s24, s25, s24
	s_lshl_b32 s25, 3, s83
	s_ashr_i32 s26, s25, 4
	s_lshl_b32 s25, s25, 3
	s_lshl_b32 s26, s26, 3
	s_add_i32 s25, s26, s25
	s_lshl_b32 s26, 4, s83
	s_ashr_i32 s27, s26, 4
	s_lshl_b32 s26, s26, 3
	s_lshl_b32 s27, s27, 3
	s_add_i32 s26, s27, s26
	s_lshl_b32 s27, 5, s83
	s_ashr_i32 s30, s27, 4
	s_lshl_b32 s27, s27, 3
	s_lshl_b32 s30, s30, 3
	s_add_i32 s27, s30, s27
	s_lshl_b32 s30, 6, s83
	s_ashr_i32 s38, s30, 4
	s_lshl_b32 s30, s30, 3
	s_lshl_b32 s38, s38, 3
	s_add_i32 s30, s38, s30
	s_lshl_b32 s38, 7, s83
	s_ashr_i32 s39, s38, 4
	s_lshl_b32 s38, s38, 3
	s_lshl_b32 s39, s39, 3
	s_add_i32 s38, s39, s38
	s_lshl_b32 s39, 8, s83
	s_ashr_i32 s55, s39, 4
	s_lshl_b32 s39, s39, 3
	s_lshl_b32 s55, s55, 3
	s_add_i32 s39, s55, s39
	s_lshl_b32 s55, 9, s83
	s_ashr_i32 s63, s55, 4
	s_lshl_b32 s55, s55, 3
	s_lshl_b32 s63, s63, 3
	s_add_i32 s55, s63, s55
	s_lshl_b32 s63, 10, s83
	s_ashr_i32 s64, s63, 4
	s_lshl_b32 s63, s63, 3
	s_lshl_b32 s64, s64, 3
	s_add_i32 s63, s64, s63
	s_lshl_b32 s64, 11, s83
	s_ashr_i32 s65, s64, 4
	s_lshl_b32 s64, s64, 3
	s_lshl_b32 s65, s65, 3
	s_add_i32 s64, s65, s64
	s_lshl_b32 s65, 12, s83
	s_ashr_i32 s80, s65, 4
	s_lshl_b32 s65, s65, 3
	s_lshl_b32 s80, s80, 3
	s_add_i32 s65, s80, s65
	s_lshl_b32 s80, 13, s83
	s_ashr_i32 s82, s80, 4
	s_lshl_b32 s80, s80, 3
	s_lshl_b32 s82, s82, 3
	s_add_i32 s80, s82, s80
	s_lshl_b32 s82, 14, s83
	v_ashrrev_i32_e32 v89, 4, v88
	s_ashr_i32 s84, s82, 4
	v_lshlrev_b32_e32 v176, 3, v89
	v_lshlrev_b32_e32 v221, 3, v88
	s_lshl_b32 s82, s82, 3
	s_lshl_b32 s84, s84, 3
	s_lshl_b32 s83, 15, s83
	v_add3_u32 v222, 0, v176, v221
	s_add_i32 s82, s84, s82
	s_waitcnt vmcnt(0) lgkmcnt(0)
	v_mov_b32_e32 v238, v86
	v_mov_b32_e32 v239, v87
	s_ashr_i32 s84, s83, 4
	ds_read_b64 v[102:103], v222
	v_add_u32_e32 v223, s11, v222
	v_add_u32_e32 v224, s24, v222
	v_add_u32_e32 v225, s25, v222
	v_add_u32_e32 v230, s39, v222
	v_add_u32_e32 v231, s55, v222
	v_add_u32_e32 v232, s63, v222
	v_add_u32_e32 v233, s64, v222
	s_lshl_b32 s83, s83, 3
	s_lshl_b32 s84, s84, 3
	ds_read_b64 v[100:101], v223
	ds_read_b64 v[98:99], v224
	ds_read_b64 v[96:97], v225
	ds_read_b64 v[118:119], v230
	ds_read_b64 v[116:117], v231
	ds_read_b64 v[114:115], v232
	ds_read_b64 v[112:113], v233
	s_add_i32 s83, s84, s83
	s_waitcnt lgkmcnt(3)
	v_add_f32_e32 v184, v102, v118
	v_sub_f32_e32 v102, v102, v118
	v_add_u32_e32 v226, s26, v222
	v_add_u32_e32 v227, s27, v222
	v_add_u32_e32 v228, s30, v222
	v_add_u32_e32 v229, s38, v222
	v_add_u32_e32 v234, s65, v222
	v_add_u32_e32 v235, s80, v222
	v_add_u32_e32 v236, s82, v222
	v_add_u32_e32 v237, s83, v222
	v_mov_b32_e32 v178, 0x3f3504f3
	v_mov_b32_e32 v179, 0x3f6c835e
	v_mov_b32_e32 v180, 0x3ec3ef15
	v_add_f32_e32 v185, v103, v119
	v_sub_f32_e32 v103, v103, v119
	v_mul_f32_e32 v118, v102, v238
	v_mul_f32_e32 v102, v102, v239
	ds_read_b64 v[94:95], v226
	ds_read_b64 v[92:93], v227
	ds_read_b64 v[90:91], v228
	ds_read_b64 v[88:89], v229
	ds_read_b64 v[110:111], v234
	ds_read_b64 v[108:109], v235
	ds_read_b64 v[106:107], v236
	ds_read_b64 v[104:105], v237
	v_fma_f32 v118, -v103, v239, v118
	v_fma_f32 v102, v103, v238, v102
	s_waitcnt lgkmcnt(10)
	v_add_f32_e32 v103, v100, v116
	v_sub_f32_e32 v100, v100, v116
	v_add_f32_e32 v119, v101, v117
	v_mul_f32_e32 v116, v238, v179
	v_xor_b32_e32 v181, 0x80000000, v180
	v_xor_b32_e32 v182, 0x80000000, v179
	v_sub_f32_e32 v101, v101, v117
	v_fma_f32 v116, -v239, v181, v116
	v_mul_f32_e32 v117, v238, v181
	v_xor_b32_e32 v183, 0x80000000, v178
	v_fma_f32 v179, v239, v179, v117
	v_mul_f32_e32 v198, v100, v116
	v_add3_u32 v176, s2, v176, v221
	v_mul_f32_e32 v100, v100, v179
	v_fma_f32 v198, -v101, v179, v198
	v_add_u32_e32 v221, s11, v176
	v_fma_f32 v100, v101, v116, v100
	s_waitcnt lgkmcnt(9)
	v_add_f32_e32 v101, v98, v114
	v_sub_f32_e32 v98, v98, v114
	v_mul_f32_e32 v114, v238, v178
	v_add_f32_e32 v116, v99, v115
	v_sub_f32_e32 v99, v99, v115
	v_mul_f32_e32 v115, v238, v183
	s_add_i32 s10, s10, 1
	v_fma_f32 v114, -v239, v183, v114
	v_fma_f32 v179, v239, v178, v115
	s_cmp_lg_u32 s10, 3
	v_mul_f32_e32 v199, v98, v114
	v_mul_f32_e32 v98, v98, v179
	v_fma_f32 v199, -v99, v179, v199
	v_fma_f32 v98, v99, v114, v98
	s_waitcnt lgkmcnt(8)
	v_add_f32_e32 v99, v96, v112
	v_sub_f32_e32 v96, v96, v112
	v_mul_f32_e32 v112, v238, v180
	v_add_f32_e32 v114, v97, v113
	v_sub_f32_e32 v97, v97, v113
	v_mul_f32_e32 v113, v238, v182
	v_fma_f32 v112, -v239, v182, v112
	v_fma_f32 v179, v239, v180, v113
	v_mul_f32_e32 v180, v96, v112
	v_mul_f32_e32 v96, v96, v179
	v_fma_f32 v180, -v97, v179, v180
	v_fma_f32 v96, v97, v112, v96
	s_waitcnt lgkmcnt(3)
	v_add_f32_e32 v97, v94, v110
	v_add_f32_e32 v112, v95, v111
	v_sub_f32_e32 v94, v94, v110
	v_sub_f32_e32 v95, v95, v111
	v_mul_f32_e32 v110, v238, v177
	v_mul_f32_e32 v111, v238, v197
	v_fma_f32 v110, -v239, v197, v110
	v_fma_f32 v111, v239, v177, v111
	v_mul_f32_e32 v179, v94, v110
	v_mul_f32_e32 v94, v94, v111
	v_fma_f32 v179, -v95, v111, v179
	v_fma_f32 v94, v95, v110, v94
	s_waitcnt lgkmcnt(2)
; template <int R, bool UNIT> __device__ __forceinline__ void dif_regs(f32x2* v, f32x2 wb) {
;     float k1 = 0.92387953251128674f, k2 = 0.70710678118654752f, k3 = 0.38268343236508977f; asm volatile("" : "+v"(k1), "+v"(k2), "+v"(k3));
; #pragma unroll
;     for (int t = 0; t < R; ++t) { constexpr int dummy = 0; (void)dummy; const int half = 1 << (R - 1 - t);
; #pragma unroll
;         for (int k = 0; k < (1 << R); ++k) if (!(k & half)) { const int kk = k & (half - 1), m = kk * (8 / half);
;             const f32x2 a = v[k], b = v[k + half]; v[k] = cadd(a, b); const f32x2 d = csub(a, b);
;             if (UNIT) { v[k + half] = (m == 0) ? d : (m == 4) ? (f32x2){d.y, -d.x} : cmul(d, CW16(m)); }
;             else { const f32x2 tw = (m == 0) ? wb : cmul(wb, CW16(m)); v[k + half] = cmul(d, tw); } }
;         if (!UNIT) wb = cmul(wb, wb); }
; }
; template <int R> __device__ __forceinline__ void dif_pass_rt(LAS f32x2* X, int sl, const f32x2 wb_in, int tid) {
;     float wbx = wb_in.x, wby = wb_in.y; asm volatile("" : "+v"(wbx), "+v"(wby)); const f32x2 wb = {wbx, wby};
;     const int r = tid & ((1 << sl) - 1), base = ((tid >> sl) << (sl + R)) + r;
;     LAS f32x2* Xb = X + PADI(base); f32x2 v[1 << R];
; #pragma unroll
;     for (int k = 0; k < (1 << R); ++k) v[k] = Xb[(k << sl) + ((k << sl) >> 4)];
;     dif_regs<R, false>(v, wb);
; #pragma unroll
;     for (int k = 0; k < (1 << R); ++k) Xb[(k << sl) + ((k << sl) >> 4)] = v[k];
; }
; template <int R> __device__ __forceinline__ void dit_pass_rt(LAS f32x2* X, int sl, const f32x2 wb_in, int tid) {
;     float wbx = wb_in.x, wby = wb_in.y; asm volatile("" : "+v"(wbx), "+v"(wby)); const f32x2 wbig = {wbx, wby};
;     const int r = tid & ((1 << sl) - 1), base = ((tid >> sl) << (sl + R)) + r;
;     LAS f32x2* Xb = X + PADI(base); f32x2 v[1 << R];
; #pragma unroll
;     for (int k = 0; k < (1 << R); ++k) v[k] = Xb[(k << sl) + ((k << sl) >> 4)];
;     dit_regs<R, false>(v, wbig);
; #pragma unroll
;     for (int k = 0; k < (1 << R); ++k) Xb[(k << sl) + ((k << sl) >> 4)] = v[k];
; }
; template <int NPT> __device__ __forceinline__ void fwd2_to_lds(LAS f32x2* Xe, LAS f32x2* Xo, const f32x2* tw, int tid, f32x2* ve, f32x2* vo) {
;     constexpr int R = NPT == 16 ? 4 : 3;
;     asm volatile("" : "+v"(tid)); __syncthreads();
;     { LAS f32x2* Pe = Xe + PADI(tid); LAS f32x2* Po = Xo + PADI(tid);
; #pragma unroll
	v_add_f32_e32 v95, v92, v108
	v_sub_f32_e32 v92, v92, v108
	v_add_f32_e32 v110, v93, v109
	v_sub_f32_e32 v93, v93, v109
	v_fma_f32 v108, -v239, v182, v117
	v_fma_f32 v109, v239, v181, v113
	v_mul_f32_e32 v111, v92, v108
	v_mul_f32_e32 v92, v92, v109
	v_fma_f32 v111, -v93, v109, v111
	v_fma_f32 v92, v93, v108, v92
	s_waitcnt lgkmcnt(1)
	v_add_f32_e32 v93, v90, v106
	v_sub_f32_e32 v90, v90, v106
	v_add_f32_e32 v108, v91, v107
	v_sub_f32_e32 v91, v91, v107
	v_fma_f32 v106, -v239, v183, v115
	v_fma_f32 v107, v239, v183, v115
	v_mul_f32_e32 v109, v90, v106
	v_mul_f32_e32 v90, v90, v107
	v_fma_f32 v109, -v91, v107, v109
	v_fma_f32 v90, v91, v106, v90
	s_waitcnt lgkmcnt(0)
	v_add_f32_e32 v91, v88, v104
	v_sub_f32_e32 v88, v88, v104
	v_add_f32_e32 v106, v89, v105
	v_sub_f32_e32 v89, v89, v105
	v_fma_f32 v104, -v239, v181, v113
	v_fma_f32 v105, v239, v182, v117
	v_add_f32_e32 v113, v185, v112
	v_sub_f32_e32 v112, v185, v112
	v_add_f32_e32 v117, v119, v110
	v_add_f32_e32 v182, v116, v108
	v_mul_f32_e32 v107, v88, v104
	v_mul_f32_e32 v88, v88, v105
	v_add_f32_e32 v185, v114, v106
	v_fma_f32 v107, -v89, v105, v107
	v_fma_f32 v88, v89, v104, v88
	v_mul_f32_e32 v89, v238, v238
	v_mul_f32_e32 v104, v238, v239
	v_add_f32_e32 v105, v184, v97
	v_sub_f32_e32 v97, v184, v97
	v_fma_f32 v89, -v239, v239, v89
	v_fma_f32 v104, v239, v238, v104
	v_mul_f32_e32 v115, v97, v89
	v_mul_f32_e32 v97, v97, v104
	v_fma_f32 v115, -v112, v104, v115
	v_fma_f32 v97, v112, v89, v97
	v_add_f32_e32 v112, v103, v95
	v_sub_f32_e32 v95, v103, v95
	v_sub_f32_e32 v103, v119, v110
	v_mul_f32_e32 v110, v89, v178
	v_mul_f32_e32 v119, v89, v183
	v_fma_f32 v110, -v104, v183, v110
	v_fma_f32 v178, v104, v178, v119
	v_mul_f32_e32 v181, v95, v110
	v_mul_f32_e32 v95, v95, v178
	v_fma_f32 v181, -v103, v178, v181
	v_fma_f32 v95, v103, v110, v95
	v_add_f32_e32 v103, v101, v93
	v_sub_f32_e32 v93, v101, v93
	v_sub_f32_e32 v101, v116, v108
	v_mul_f32_e32 v108, v89, v177
	v_mul_f32_e32 v116, v89, v197
	v_fma_f32 v108, -v104, v197, v108
	v_fma_f32 v116, v104, v177, v116
	v_mul_f32_e32 v184, v93, v108
	v_mul_f32_e32 v93, v93, v116
	v_fma_f32 v184, -v101, v116, v184
	v_fma_f32 v93, v101, v108, v93
	v_add_f32_e32 v101, v99, v91
	v_sub_f32_e32 v91, v99, v91
	v_sub_f32_e32 v99, v114, v106
	v_fma_f32 v106, -v104, v183, v119
	v_fma_f32 v114, v104, v183, v119
	v_add_f32_e32 v183, v102, v94
	v_sub_f32_e32 v94, v102, v94
	v_mul_f32_e32 v119, v91, v106
	v_mul_f32_e32 v91, v91, v114
	v_fma_f32 v119, -v99, v114, v119
	v_fma_f32 v91, v99, v106, v91
	v_add_f32_e32 v99, v118, v179
	v_sub_f32_e32 v118, v118, v179
	v_add_f32_e32 v179, v100, v92
	v_sub_f32_e32 v92, v100, v92
	v_mul_f32_e32 v102, v118, v89
	v_mul_f32_e32 v118, v118, v104
	v_fma_f32 v102, -v94, v104, v102
	v_fma_f32 v94, v94, v89, v118
	v_add_f32_e32 v118, v198, v111
	v_sub_f32_e32 v111, v198, v111
	v_mul_f32_e32 v100, v111, v110
	v_mul_f32_e32 v111, v111, v178
	v_fma_f32 v100, -v92, v178, v100
	v_fma_f32 v92, v92, v110, v111
	v_add_f32_e32 v110, v199, v109
	v_sub_f32_e32 v109, v199, v109
	v_add_f32_e32 v111, v98, v90
	v_sub_f32_e32 v90, v98, v90
	v_mul_f32_e32 v98, v109, v108
	v_mul_f32_e32 v109, v109, v116
	v_add_f32_e32 v199, v183, v111
	v_add_f32_e32 v198, v99, v110
	v_fma_f32 v98, -v90, v116, v98
	v_fma_f32 v90, v90, v108, v109
	v_add_f32_e32 v108, v180, v107
	v_add_f32_e32 v109, v96, v88
	v_sub_f32_e32 v107, v180, v107
	v_sub_f32_e32 v88, v96, v88
	v_add_f32_e32 v180, v97, v93
	v_sub_f32_e32 v93, v97, v93
	v_add_f32_e32 v238, v94, v90
	v_add_f32_e32 v200, v179, v109
	v_mul_f32_e32 v96, v107, v106
	v_mul_f32_e32 v107, v107, v114
	v_sub_f32_e32 v90, v94, v90
	v_add_f32_e32 v201, v102, v98
	v_fma_f32 v96, -v88, v114, v96
	v_fma_f32 v88, v88, v106, v107
	v_mul_f32_e32 v106, v89, v89
	v_mul_f32_e32 v107, v89, v104
	v_add_f32_e32 v114, v117, v185
	v_fma_f32 v106, -v104, v104, v106
	v_fma_f32 v89, v104, v89, v107
	v_add_f32_e32 v104, v105, v103
	v_sub_f32_e32 v103, v105, v103
	v_add_f32_e32 v107, v113, v182
	v_sub_f32_e32 v105, v113, v182
	v_mul_f32_e32 v116, v106, v177
	v_add_f32_e32 v242, v92, v88
	v_sub_f32_e32 v88, v92, v88
	v_mul_f32_e32 v113, v103, v106
	v_mul_f32_e32 v103, v103, v89
	v_add_f32_e32 v241, v100, v96
	v_fma_f32 v116, -v89, v197, v116
	v_sub_f32_e32 v92, v107, v114
	v_fma_f32 v113, -v105, v89, v113
	v_fma_f32 v103, v105, v106, v103
	v_add_f32_e32 v105, v112, v101
	v_sub_f32_e32 v101, v112, v101
	v_sub_f32_e32 v112, v117, v185
	v_mul_f32_e32 v117, v106, v197
	v_add_f32_e32 v185, v95, v91
	v_sub_f32_e32 v91, v95, v91
	v_fma_f32 v117, v89, v177, v117
	v_mul_f32_e32 v178, v101, v116
	v_mul_f32_e32 v101, v101, v117
	v_fma_f32 v178, -v112, v117, v178
	v_fma_f32 v101, v112, v116, v101
	v_add_f32_e32 v112, v115, v184
	v_sub_f32_e32 v115, v115, v184
	v_add_f32_e32 v184, v181, v119
	v_mul_f32_e32 v97, v115, v106
	v_fma_f32 v182, -v93, v89, v97
	v_mul_f32_e32 v97, v115, v89
	v_fma_f32 v115, v93, v106, v97
	v_sub_f32_e32 v93, v181, v119
	v_add_f32_e32 v97, v180, v185
	v_mul_f32_e32 v95, v93, v116
	v_mul_f32_e32 v93, v93, v117
	v_fma_f32 v119, -v91, v117, v95
	v_fma_f32 v181, v91, v116, v93
	v_sub_f32_e32 v91, v99, v110
	v_sub_f32_e32 v93, v183, v111
	v_add_f32_e32 v183, v118, v108
	v_sub_f32_e32 v99, v112, v184
	v_mul_f32_e32 v95, v91, v106
	v_mul_f32_e32 v91, v91, v89
	v_fma_f32 v111, v93, v106, v91
	v_sub_f32_e32 v91, v118, v108
	v_fma_f32 v110, -v93, v89, v95
	v_sub_f32_e32 v93, v179, v109
	v_sub_f32_e32 v108, v199, v200
	v_mul_f32_e32 v95, v91, v116
	v_mul_f32_e32 v91, v91, v117
	v_fma_f32 v179, v93, v116, v91
	v_sub_f32_e32 v91, v102, v98
	v_fma_f32 v118, -v93, v117, v95
	v_sub_f32_e32 v95, v113, v178
	v_mul_f32_e32 v93, v91, v106
; template <int R, bool UNIT> __device__ __forceinline__ void dif_regs(f32x2* v, f32x2 wb) {
;     float k1 = 0.92387953251128674f, k2 = 0.70710678118654752f, k3 = 0.38268343236508977f; asm volatile("" : "+v"(k1), "+v"(k2), "+v"(k3));
; #pragma unroll
;     for (int t = 0; t < R; ++t) { constexpr int dummy = 0; (void)dummy; const int half = 1 << (R - 1 - t);
; #pragma unroll
;         for (int k = 0; k < (1 << R); ++k) if (!(k & half)) { const int kk = k & (half - 1), m = kk * (8 / half);
;             const f32x2 a = v[k], b = v[k + half]; v[k] = cadd(a, b); const f32x2 d = csub(a, b);
;             if (UNIT) { v[k + half] = (m == 0) ? d : (m == 4) ? (f32x2){d.y, -d.x} : cmul(d, CW16(m)); }
;             else { const f32x2 tw = (m == 0) ? wb : cmul(wb, CW16(m)); v[k + half] = cmul(d, tw); } }
;         if (!UNIT) wb = cmul(wb, wb); }
; }
; template <int R> __device__ __forceinline__ void dif_pass_rt(LAS f32x2* X, int sl, const f32x2 wb_in, int tid) {
;     float wbx = wb_in.x, wby = wb_in.y; asm volatile("" : "+v"(wbx), "+v"(wby)); const f32x2 wb = {wbx, wby};
;     const int r = tid & ((1 << sl) - 1), base = ((tid >> sl) << (sl + R)) + r;
;     LAS f32x2* Xb = X + PADI(base); f32x2 v[1 << R];
; #pragma unroll
;     for (int k = 0; k < (1 << R); ++k) v[k] = Xb[(k << sl) + ((k << sl) >> 4)];
;     dif_regs<R, false>(v, wb);
; #pragma unroll
;     for (int k = 0; k < (1 << R); ++k) Xb[(k << sl) + ((k << sl) >> 4)] = v[k];
; }
; template <int R> __device__ __forceinline__ void dit_pass_rt(LAS f32x2* X, int sl, const f32x2 wb_in, int tid) {
;     float wbx = wb_in.x, wby = wb_in.y; asm volatile("" : "+v"(wbx), "+v"(wby)); const f32x2 wbig = {wbx, wby};
;     const int r = tid & ((1 << sl) - 1), base = ((tid >> sl) << (sl + R)) + r;
;     LAS f32x2* Xb = X + PADI(base); f32x2 v[1 << R];
; #pragma unroll
;     for (int k = 0; k < (1 << R); ++k) v[k] = Xb[(k << sl) + ((k << sl) >> 4)];
;     dit_regs<R, false>(v, wbig);
; #pragma unroll
;     for (int k = 0; k < (1 << R); ++k) Xb[(k << sl) + ((k << sl) >> 4)] = v[k];
; }
; template <int NPT> __device__ __forceinline__ void fwd2_to_lds(LAS f32x2* Xe, LAS f32x2* Xo, const f32x2* tw, int tid, f32x2* ve, f32x2* vo) {
;     constexpr int R = NPT == 16 ? 4 : 3;
;     asm volatile("" : "+v"(tid)); __syncthreads();
;     { LAS f32x2* Pe = Xe + PADI(tid); LAS f32x2* Po = Xo + PADI(tid);
; #pragma unroll
	v_mul_f32_e32 v91, v91, v89
	v_add_f32_e32 v109, v111, v179
	v_sub_f32_e32 v111, v111, v179
	v_mov_b32_e32 v179, 0x3f6c835e
	v_fma_f32 v239, -v90, v89, v93
	v_fma_f32 v240, v90, v106, v91
	v_sub_f32_e32 v90, v100, v96
	v_sub_f32_e32 v96, v103, v101
	v_sub_f32_e32 v100, v180, v185
	v_add_f32_e32 v93, v103, v101
	v_add_f32_e32 v101, v115, v181
	v_sub_f32_e32 v103, v182, v119
	v_mul_f32_e32 v91, v90, v116
	v_mul_f32_e32 v90, v90, v117
	v_mov_b32_e32 v180, 0x3ec3ef15
	v_fma_f32 v243, -v88, v117, v91
	v_fma_f32 v244, v88, v116, v90
	v_mul_f32_e32 v88, v106, v106
	v_sub_f32_e32 v91, v104, v105
	v_sub_f32_e32 v116, v238, v242
	v_fma_f32 v245, -v89, v89, v88
	v_mul_f32_e32 v88, v106, v89
	v_add_f32_e32 v117, v240, v244
	v_fma_f32 v246, v89, v106, v88
	v_add_f32_e32 v89, v107, v114
	v_mul_f32_e32 v94, v95, v245
	v_sub_f32_e32 v107, v198, v183
	v_mul_f32_e32 v98, v99, v245
	v_add_f32_e32 v88, v104, v105
	v_mul_f32_e32 v95, v95, v246
	v_mul_f32_e32 v99, v99, v246
	v_fma_f32 v94, -v96, v246, v94
	v_mul_f32_e32 v106, v107, v245
	v_mul_f32_e32 v107, v107, v246
	v_mul_f32_e32 v90, v91, v245
	v_fma_f32 v95, v96, v245, v95
	v_add_f32_e32 v96, v112, v184
	v_sub_f32_e32 v112, v110, v118
	v_mul_f32_e32 v91, v91, v246
	v_fma_f32 v98, -v100, v246, v98
	v_fma_f32 v99, v100, v245, v99
	v_add_f32_e32 v100, v182, v119
	v_sub_f32_e32 v104, v115, v181
	v_fma_f32 v106, -v108, v246, v106
	v_fma_f32 v107, v108, v245, v107
	v_add_f32_e32 v108, v110, v118
	v_mul_f32_e32 v110, v112, v245
	v_mul_f32_e32 v112, v112, v246
	v_sub_f32_e32 v115, v201, v241
	v_sub_f32_e32 v119, v239, v243
	v_fma_f32 v90, -v92, v246, v90
	v_fma_f32 v91, v92, v245, v91
	v_add_f32_e32 v92, v113, v178
	v_mul_f32_e32 v102, v103, v245
	v_mul_f32_e32 v103, v103, v246
	v_fma_f32 v110, -v111, v246, v110
	v_fma_f32 v111, v111, v245, v112
	v_add_f32_e32 v112, v201, v241
	v_add_f32_e32 v113, v238, v242
	v_mul_f32_e32 v114, v115, v245
	v_mul_f32_e32 v115, v115, v246
	v_mul_f32_e32 v118, v119, v245
	v_mul_f32_e32 v119, v119, v246
	v_fma_f32 v102, -v104, v246, v102
	v_fma_f32 v103, v104, v245, v103
	v_add_f32_e32 v104, v198, v183
	v_add_f32_e32 v105, v199, v200
	v_fma_f32 v114, -v116, v246, v114
	v_fma_f32 v115, v116, v245, v115
	v_add_f32_e32 v116, v239, v243
	v_sub_f32_e32 v178, v240, v244
	v_fma_f32 v118, -v178, v246, v118
	v_fma_f32 v119, v178, v245, v119
	ds_write_b64 v222, v[88:89]
	ds_write_b64 v223, v[90:91]
	ds_write_b64 v224, v[92:93]
	ds_write_b64 v225, v[94:95]
	ds_write_b64 v226, v[96:97]
	ds_write_b64 v227, v[98:99]
	ds_write_b64 v228, v[100:101]
	ds_write_b64 v229, v[102:103]
	ds_write_b64 v230, v[104:105]
	ds_write_b64 v231, v[106:107]
	ds_write_b64 v232, v[108:109]
	ds_write_b64 v233, v[110:111]
	ds_write_b64 v234, v[112:113]
	ds_write_b64 v235, v[114:115]
	ds_write_b64 v236, v[116:117]
	ds_write_b64 v237, v[118:119]
	ds_read_b64 v[112:113], v176
	ds_read_b64 v[110:111], v221
	v_add_u32_e32 v222, s24, v176
	v_add_u32_e32 v223, s25, v176
	v_add_u32_e32 v228, s39, v176
	v_add_u32_e32 v229, s55, v176
	v_add_u32_e32 v230, s63, v176
	v_add_u32_e32 v231, s64, v176
	ds_read_b64 v[106:107], v222
	ds_read_b64 v[102:103], v223
	ds_read_b64 v[118:119], v228
	ds_read_b64 v[116:117], v229
	ds_read_b64 v[114:115], v230
	ds_read_b64 v[108:109], v231
	s_waitcnt lgkmcnt(3)
	v_add_f32_e32 v184, v112, v118
	v_sub_f32_e32 v112, v112, v118
	v_add_u32_e32 v224, s26, v176
	v_add_u32_e32 v225, s27, v176
	v_add_u32_e32 v226, s30, v176
	v_add_u32_e32 v227, s38, v176
	v_add_u32_e32 v232, s65, v176
	v_add_u32_e32 v233, s80, v176
	v_add_u32_e32 v234, s82, v176
	v_add_u32_e32 v235, s83, v176
	v_mov_b32_e32 v178, 0x3f3504f3
	v_add_f32_e32 v185, v113, v119
	v_sub_f32_e32 v113, v113, v119
	v_mul_f32_e32 v118, v112, v86
	v_mul_f32_e32 v112, v112, v87
	ds_read_b64 v[98:99], v224
	ds_read_b64 v[92:93], v225
	ds_read_b64 v[90:91], v226
	ds_read_b64 v[88:89], v227
	ds_read_b64 v[104:105], v232
	ds_read_b64 v[100:101], v233
	ds_read_b64 v[96:97], v234
	ds_read_b64 v[94:95], v235
	v_fma_f32 v118, -v113, v87, v118
	v_fma_f32 v112, v113, v86, v112
	s_waitcnt lgkmcnt(10)
	v_add_f32_e32 v113, v110, v116
	v_sub_f32_e32 v110, v110, v116
	v_add_f32_e32 v119, v111, v117
	v_mul_f32_e32 v116, v86, v179
	v_xor_b32_e32 v181, 0x80000000, v180
	v_xor_b32_e32 v182, 0x80000000, v179
	v_sub_f32_e32 v111, v111, v117
	v_fma_f32 v116, -v87, v181, v116
	v_mul_f32_e32 v117, v86, v181
	v_xor_b32_e32 v183, 0x80000000, v178
	v_fma_f32 v179, v87, v179, v117
	v_mul_f32_e32 v198, v110, v116
	v_mul_f32_e32 v110, v110, v179
	v_fma_f32 v198, -v111, v179, v198
	v_fma_f32 v110, v111, v116, v110
	s_waitcnt lgkmcnt(9)
	v_add_f32_e32 v111, v106, v114
	v_sub_f32_e32 v106, v106, v114
	v_mul_f32_e32 v114, v86, v178
	v_add_f32_e32 v116, v107, v115
	v_sub_f32_e32 v107, v107, v115
	v_mul_f32_e32 v115, v86, v183
	v_fma_f32 v114, -v87, v183, v114
	v_fma_f32 v179, v87, v178, v115
	v_mul_f32_e32 v199, v106, v114
	v_mul_f32_e32 v106, v106, v179
	v_fma_f32 v199, -v107, v179, v199
	v_fma_f32 v106, v107, v114, v106
	s_waitcnt lgkmcnt(8)
	v_add_f32_e32 v107, v102, v108
	v_sub_f32_e32 v102, v102, v108
	v_mul_f32_e32 v108, v86, v180
	v_add_f32_e32 v114, v103, v109
	v_sub_f32_e32 v103, v103, v109
	v_mul_f32_e32 v109, v86, v182
	v_fma_f32 v108, -v87, v182, v108
	v_fma_f32 v179, v87, v180, v109
	v_mul_f32_e32 v180, v102, v108
	v_mul_f32_e32 v102, v102, v179
	v_fma_f32 v180, -v103, v179, v180
	v_fma_f32 v102, v103, v108, v102
	s_waitcnt lgkmcnt(3)
	v_add_f32_e32 v103, v98, v104
	v_add_f32_e32 v108, v99, v105
	v_sub_f32_e32 v98, v98, v104
	v_sub_f32_e32 v99, v99, v105
	v_mul_f32_e32 v104, v86, v177
	v_mul_f32_e32 v105, v86, v197
	v_fma_f32 v104, -v87, v197, v104
	v_fma_f32 v105, v87, v177, v105
	v_mul_f32_e32 v179, v98, v104
	v_mul_f32_e32 v98, v98, v105
	v_fma_f32 v179, -v99, v105, v179
	v_fma_f32 v98, v99, v104, v98
	s_waitcnt lgkmcnt(2)
; template <int R, bool UNIT> __device__ __forceinline__ void dif_regs(f32x2* v, f32x2 wb) {
;     float k1 = 0.92387953251128674f, k2 = 0.70710678118654752f, k3 = 0.38268343236508977f; asm volatile("" : "+v"(k1), "+v"(k2), "+v"(k3));
; #pragma unroll
;     for (int t = 0; t < R; ++t) { constexpr int dummy = 0; (void)dummy; const int half = 1 << (R - 1 - t);
; #pragma unroll
;         for (int k = 0; k < (1 << R); ++k) if (!(k & half)) { const int kk = k & (half - 1), m = kk * (8 / half);
;             const f32x2 a = v[k], b = v[k + half]; v[k] = cadd(a, b); const f32x2 d = csub(a, b);
;             if (UNIT) { v[k + half] = (m == 0) ? d : (m == 4) ? (f32x2){d.y, -d.x} : cmul(d, CW16(m)); }
;             else { const f32x2 tw = (m == 0) ? wb : cmul(wb, CW16(m)); v[k + half] = cmul(d, tw); } }
;         if (!UNIT) wb = cmul(wb, wb); }
; }
; template <int R> __device__ __forceinline__ void dif_pass_rt(LAS f32x2* X, int sl, const f32x2 wb_in, int tid) {
;     float wbx = wb_in.x, wby = wb_in.y; asm volatile("" : "+v"(wbx), "+v"(wby)); const f32x2 wb = {wbx, wby};
;     const int r = tid & ((1 << sl) - 1), base = ((tid >> sl) << (sl + R)) + r;
;     LAS f32x2* Xb = X + PADI(base); f32x2 v[1 << R];
; #pragma unroll
;     for (int k = 0; k < (1 << R); ++k) v[k] = Xb[(k << sl) + ((k << sl) >> 4)];
;     dif_regs<R, false>(v, wb);
; #pragma unroll
;     for (int k = 0; k < (1 << R); ++k) Xb[(k << sl) + ((k << sl) >> 4)] = v[k];
; }
; template <int R> __device__ __forceinline__ void dit_pass_rt(LAS f32x2* X, int sl, const f32x2 wb_in, int tid) {
;     float wbx = wb_in.x, wby = wb_in.y; asm volatile("" : "+v"(wbx), "+v"(wby)); const f32x2 wbig = {wbx, wby};
;     const int r = tid & ((1 << sl) - 1), base = ((tid >> sl) << (sl + R)) + r;
;     LAS f32x2* Xb = X + PADI(base); f32x2 v[1 << R];
; #pragma unroll
;     for (int k = 0; k < (1 << R); ++k) v[k] = Xb[(k << sl) + ((k << sl) >> 4)];
;     dit_regs<R, false>(v, wbig);
; #pragma unroll
;     for (int k = 0; k < (1 << R); ++k) Xb[(k << sl) + ((k << sl) >> 4)] = v[k];
; }
; template <int NPT> __device__ __forceinline__ void fwd2_to_lds(LAS f32x2* Xe, LAS f32x2* Xo, const f32x2* tw, int tid, f32x2* ve, f32x2* vo) {
;     constexpr int R = NPT == 16 ? 4 : 3;
;     asm volatile("" : "+v"(tid)); __syncthreads();
;     { LAS f32x2* Pe = Xe + PADI(tid); LAS f32x2* Po = Xo + PADI(tid);
; #pragma unroll
	v_add_f32_e32 v99, v92, v100
	v_sub_f32_e32 v92, v92, v100
	v_add_f32_e32 v104, v93, v101
	v_sub_f32_e32 v93, v93, v101
	v_fma_f32 v100, -v87, v182, v117
	v_fma_f32 v101, v87, v181, v109
	v_mul_f32_e32 v105, v92, v100
	v_mul_f32_e32 v92, v92, v101
	v_fma_f32 v105, -v93, v101, v105
	v_fma_f32 v92, v93, v100, v92
	s_waitcnt lgkmcnt(1)
	v_add_f32_e32 v93, v90, v96
	v_sub_f32_e32 v90, v90, v96
	v_add_f32_e32 v100, v91, v97
	v_sub_f32_e32 v91, v91, v97
	v_fma_f32 v96, -v87, v183, v115
	v_fma_f32 v97, v87, v183, v115
	v_mul_f32_e32 v101, v90, v96
	v_mul_f32_e32 v90, v90, v97
	v_fma_f32 v101, -v91, v97, v101
	v_fma_f32 v90, v91, v96, v90
	s_waitcnt lgkmcnt(0)
	v_add_f32_e32 v91, v88, v94
	v_sub_f32_e32 v88, v88, v94
	v_add_f32_e32 v96, v89, v95
	v_sub_f32_e32 v89, v89, v95
	v_fma_f32 v94, -v87, v181, v109
	v_fma_f32 v95, v87, v182, v117
	v_add_f32_e32 v109, v119, v104
	v_sub_f32_e32 v104, v119, v104
	v_add_f32_e32 v182, v114, v96
	v_sub_f32_e32 v96, v114, v96
	v_mul_f32_e32 v97, v88, v94
	v_mul_f32_e32 v88, v88, v95
	v_fma_f32 v97, -v89, v95, v97
	v_fma_f32 v88, v89, v94, v88
	v_mul_f32_e32 v89, v86, v86
	v_mul_f32_e32 v94, v86, v87
	v_sub_f32_e32 v95, v184, v103
	v_fma_f32 v89, -v87, v87, v89
	v_fma_f32 v86, v87, v86, v94
	v_add_f32_e32 v87, v184, v103
	v_add_f32_e32 v94, v185, v108
	v_sub_f32_e32 v103, v185, v108
	v_mul_f32_e32 v108, v95, v89
	v_mul_f32_e32 v95, v95, v86
	v_mul_f32_e32 v115, v89, v183
	v_fma_f32 v108, -v103, v86, v108
	v_fma_f32 v95, v103, v89, v95
	v_add_f32_e32 v103, v113, v99
	v_sub_f32_e32 v99, v113, v99
	v_mul_f32_e32 v113, v89, v178
	v_fma_f32 v117, v86, v178, v115
	v_add_f32_e32 v178, v116, v100
	v_sub_f32_e32 v100, v116, v100
	v_mul_f32_e32 v116, v89, v197
	v_fma_f32 v114, v86, v183, v115
	v_fma_f32 v113, -v86, v183, v113
	v_mul_f32_e32 v119, v99, v113
	v_mul_f32_e32 v99, v99, v117
	v_fma_f32 v116, v86, v177, v116
	v_fma_f32 v119, -v104, v117, v119
	v_fma_f32 v99, v104, v113, v99
	v_add_f32_e32 v104, v111, v93
	v_sub_f32_e32 v93, v111, v93
	v_mul_f32_e32 v111, v89, v177
	v_fma_f32 v111, -v86, v197, v111
	v_mul_f32_e32 v181, v93, v111
	v_mul_f32_e32 v93, v93, v116
	v_fma_f32 v181, -v100, v116, v181
	v_fma_f32 v93, v100, v111, v93
	v_add_f32_e32 v100, v107, v91
	v_sub_f32_e32 v91, v107, v91
	v_fma_f32 v107, -v86, v183, v115
	v_add_f32_e32 v183, v112, v98
	v_sub_f32_e32 v98, v112, v98
	v_mul_f32_e32 v115, v91, v107
	v_mul_f32_e32 v91, v91, v114
	v_fma_f32 v115, -v96, v114, v115
	v_fma_f32 v91, v96, v107, v91
	v_add_f32_e32 v96, v118, v179
	v_sub_f32_e32 v118, v118, v179
	v_add_f32_e32 v179, v110, v92
	v_sub_f32_e32 v92, v110, v92
	v_mul_f32_e32 v112, v118, v89
	v_mul_f32_e32 v118, v118, v86
	v_add_f32_e32 v184, v99, v91
	v_sub_f32_e32 v91, v99, v91
	v_fma_f32 v112, -v98, v86, v112
	v_fma_f32 v98, v98, v89, v118
	v_add_f32_e32 v118, v198, v105
	v_sub_f32_e32 v105, v198, v105
	v_mul_f32_e32 v110, v105, v113
	v_mul_f32_e32 v105, v105, v117
	v_fma_f32 v110, -v92, v117, v110
	v_fma_f32 v92, v92, v113, v105
	v_add_f32_e32 v105, v199, v101
	v_sub_f32_e32 v101, v199, v101
	v_add_f32_e32 v113, v106, v90
	v_sub_f32_e32 v90, v106, v90
	v_mul_f32_e32 v106, v101, v111
	v_mul_f32_e32 v101, v101, v116
	v_add_f32_e32 v198, v183, v113
	v_add_f32_e32 v185, v96, v105
	v_fma_f32 v106, -v90, v116, v106
	v_fma_f32 v90, v90, v111, v101
	v_add_f32_e32 v101, v180, v97
	v_sub_f32_e32 v97, v180, v97
	v_add_f32_e32 v111, v102, v88
	v_sub_f32_e32 v88, v102, v88
	v_add_f32_e32 v116, v109, v182
	v_add_f32_e32 v180, v95, v93
	v_sub_f32_e32 v93, v95, v93
	v_mul_f32_e32 v102, v97, v107
	v_mul_f32_e32 v97, v97, v114
	v_add_f32_e32 v199, v179, v111
	v_add_f32_e32 v200, v98, v90
	v_sub_f32_e32 v90, v98, v90
	v_sub_f32_e32 v98, v180, v184
	v_fma_f32 v102, -v88, v114, v102
	v_fma_f32 v88, v88, v107, v97
	v_mul_f32_e32 v97, v89, v89
	v_mul_f32_e32 v107, v89, v86
	v_add_f32_e32 v114, v103, v100
	v_fma_f32 v97, -v86, v86, v97
	v_fma_f32 v86, v86, v89, v107
	v_add_f32_e32 v89, v87, v104
	v_sub_f32_e32 v87, v87, v104
	v_add_f32_e32 v107, v94, v178
	v_sub_f32_e32 v94, v94, v178
	v_add_f32_e32 v178, v108, v181
	v_add_f32_e32 v237, v92, v88
	v_sub_f32_e32 v88, v92, v88
	v_mul_f32_e32 v104, v87, v97
	v_mul_f32_e32 v87, v87, v86
	v_fma_f32 v104, -v94, v86, v104
	v_fma_f32 v94, v94, v97, v87
	v_sub_f32_e32 v87, v103, v100
	v_sub_f32_e32 v100, v109, v182
	v_mul_f32_e32 v103, v97, v177
	v_mul_f32_e32 v109, v97, v197
	v_add_f32_e32 v182, v119, v115
	v_fma_f32 v103, -v86, v197, v103
	v_fma_f32 v109, v86, v177, v109
	v_mul_f32_e32 v117, v87, v103
	v_mul_f32_e32 v87, v87, v109
	v_fma_f32 v117, -v100, v109, v117
	v_fma_f32 v100, v100, v103, v87
	v_sub_f32_e32 v87, v108, v181
	v_mul_f32_e32 v95, v87, v97
	v_mul_f32_e32 v87, v87, v86
	v_fma_f32 v181, v93, v97, v87
	v_sub_f32_e32 v87, v119, v115
	v_fma_f32 v108, -v93, v86, v95
	v_add_f32_e32 v95, v180, v184
	v_mul_f32_e32 v93, v87, v103
	v_mul_f32_e32 v87, v87, v109
	v_fma_f32 v119, v91, v103, v87
	v_sub_f32_e32 v87, v96, v105
	v_fma_f32 v115, -v91, v109, v93
	v_sub_f32_e32 v91, v183, v113
	v_add_f32_e32 v105, v118, v101
	v_mul_f32_e32 v93, v87, v97
	v_mul_f32_e32 v87, v87, v86
	v_add_f32_e32 v99, v181, v119
	v_fma_f32 v183, v91, v97, v87
	v_sub_f32_e32 v87, v118, v101
	v_fma_f32 v113, -v91, v86, v93
	v_sub_f32_e32 v91, v179, v111
	v_sub_f32_e32 v101, v108, v115
	v_add_f32_e32 v179, v112, v106
	v_mul_f32_e32 v93, v87, v103
	v_mul_f32_e32 v87, v87, v109
	v_fma_f32 v118, v91, v103, v87
	v_sub_f32_e32 v87, v112, v106
	v_fma_f32 v111, -v91, v109, v93
	v_add_f32_e32 v112, v110, v102
	v_sub_f32_e32 v93, v104, v117
	v_sub_f32_e32 v106, v198, v199
	v_mul_f32_e32 v91, v87, v97
	v_mul_f32_e32 v87, v87, v86
	v_fma_f32 v236, v90, v97, v87
; #define LAS __attribute__((address_space(3)))
; __device__ __forceinline__ f32x2 cadd(f32x2 a, f32x2 b) { return (f32x2){fadd_(a.x, b.x), fadd_(a.y, b.y)}; }
; __device__ __forceinline__ f32x2 csub(f32x2 a, f32x2 b) { return (f32x2){fsub_(a.x, b.x), fsub_(a.y, b.y)}; }
; __device__ __forceinline__ f32x2 cmul(f32x2 a, f32x2 b) { return (f32x2){fnma_(a.y, b.y, fmul_(a.x, b.x)), ffma_(a.y, b.x, fmul_(a.x, b.y))}; }
; template <int R, bool UNIT> __device__ __forceinline__ void dif_regs(f32x2* v, f32x2 wb) {
;     float k1 = 0.92387953251128674f, k2 = 0.70710678118654752f, k3 = 0.38268343236508977f; asm volatile("" : "+v"(k1), "+v"(k2), "+v"(k3));
; #pragma unroll
;     for (int t = 0; t < R; ++t) { constexpr int dummy = 0; (void)dummy; const int half = 1 << (R - 1 - t);
; #pragma unroll
;         for (int k = 0; k < (1 << R); ++k) if (!(k & half)) { const int kk = k & (half - 1), m = kk * (8 / half);
;             const f32x2 a = v[k], b = v[k + half]; v[k] = cadd(a, b); const f32x2 d = csub(a, b);
;             if (UNIT) { v[k + half] = (m == 0) ? d : (m == 4) ? (f32x2){d.y, -d.x} : cmul(d, CW16(m)); }
;             else { const f32x2 tw = (m == 0) ? wb : cmul(wb, CW16(m)); v[k + half] = cmul(d, tw); } }
;         if (!UNIT) wb = cmul(wb, wb); }
; template <int NPT> __device__ __forceinline__ void mid_mul(LAS f32x2* X, int tid, const f32x2* K) {
;     if (NPT == 16) {
; #pragma unroll
;         for (int u = 0; u < 8; ++u) { LAS f32x2* Xb = X + PADI(2 * tid) + 1088 * u; const f32x2 a = Xb[0], b = Xb[1];
;             const f32x2 s = cmul(cadd(a, b), K[2 * u]), d = cmul(csub(a, b), K[2 * u + 1]); Xb[0] = cadd(s, d); Xb[1] = csub(s, d); } }
	v_sub_f32_e32 v87, v110, v102
	v_fma_f32 v201, -v90, v86, v91
	v_add_f32_e32 v91, v94, v100
	v_sub_f32_e32 v94, v94, v100
	v_sub_f32_e32 v102, v181, v119
	v_sub_f32_e32 v110, v183, v118
	v_mul_f32_e32 v90, v87, v103
	v_mul_f32_e32 v87, v87, v109
	v_fma_f32 v239, v88, v103, v87
	v_mul_f32_e32 v87, v97, v97
	v_fma_f32 v238, -v88, v109, v90
	v_sub_f32_e32 v90, v107, v116
	v_sub_f32_e32 v109, v113, v111
	v_add_f32_e32 v103, v198, v199
	v_fma_f32 v240, -v86, v86, v87
	v_mul_f32_e32 v87, v97, v86
	v_fma_f32 v241, v86, v97, v87
	v_add_f32_e32 v86, v89, v114
	v_sub_f32_e32 v89, v89, v114
	v_mul_f32_e32 v100, v101, v240
	v_sub_f32_e32 v97, v178, v182
	v_add_f32_e32 v87, v107, v116
	v_mul_f32_e32 v101, v101, v241
	v_mul_f32_e32 v92, v93, v240
	v_mul_f32_e32 v88, v89, v240
	v_mul_f32_e32 v89, v89, v241
	v_fma_f32 v100, -v102, v241, v100
	v_mul_f32_e32 v96, v97, v240
	v_fma_f32 v101, v102, v240, v101
	v_add_f32_e32 v102, v185, v105
	v_sub_f32_e32 v105, v185, v105
	v_fma_f32 v88, -v90, v241, v88
	v_fma_f32 v89, v90, v240, v89
	v_add_f32_e32 v90, v104, v117
	v_mul_f32_e32 v97, v97, v241
	v_fma_f32 v96, -v98, v241, v96
	v_mul_f32_e32 v104, v105, v240
	v_mul_f32_e32 v105, v105, v241
	v_sub_f32_e32 v117, v201, v238
	v_mul_f32_e32 v93, v93, v241
	v_fma_f32 v97, v98, v240, v97
	v_add_f32_e32 v98, v108, v115
	v_fma_f32 v104, -v106, v241, v104
	v_fma_f32 v105, v106, v240, v105
	v_add_f32_e32 v106, v113, v111
	v_mul_f32_e32 v108, v109, v240
	v_mul_f32_e32 v109, v109, v241
	v_sub_f32_e32 v113, v179, v112
	v_sub_f32_e32 v114, v200, v237
	v_mul_f32_e32 v116, v117, v240
	v_mul_f32_e32 v117, v117, v241
	v_fma_f32 v108, -v110, v241, v108
	v_fma_f32 v109, v110, v240, v109
	v_add_f32_e32 v110, v179, v112
	v_mul_f32_e32 v112, v113, v240
	v_mul_f32_e32 v113, v113, v241
	v_fma_f32 v92, -v94, v241, v92
	v_fma_f32 v93, v94, v240, v93
	v_add_f32_e32 v94, v178, v182
	v_add_f32_e32 v107, v183, v118
	v_add_f32_e32 v111, v200, v237
	v_fma_f32 v112, -v114, v241, v112
	v_fma_f32 v113, v114, v240, v113
	v_add_f32_e32 v114, v201, v238
	v_add_f32_e32 v115, v236, v239
	v_sub_f32_e32 v118, v236, v239
	v_fma_f32 v116, -v118, v241, v116
	v_fma_f32 v117, v118, v240, v117
	ds_write_b64 v176, v[86:87]
	ds_write_b64 v221, v[88:89]
	ds_write_b64 v222, v[90:91]
	ds_write_b64 v223, v[92:93]
	ds_write_b64 v224, v[94:95]
	ds_write_b64 v225, v[96:97]
	ds_write_b64 v226, v[98:99]
	ds_write_b64 v227, v[100:101]
	ds_write_b64 v228, v[102:103]
	ds_write_b64 v229, v[104:105]
	ds_write_b64 v230, v[106:107]
	ds_write_b64 v231, v[108:109]
	ds_write_b64 v232, v[110:111]
	ds_write_b64 v233, v[112:113]
	ds_write_b64 v234, v[114:115]
	ds_write_b64 v235, v[116:117]
	s_waitcnt lgkmcnt(0)
	s_barrier
	s_cbranch_scc1 .LBB0_691
	ds_read2_b64 v[86:89], v120 offset1:1
	s_waitcnt lgkmcnt(0)
	v_add_f32_e32 v90, v86, v88
	v_sub_f32_e32 v86, v86, v88
	v_add_f32_e32 v91, v87, v89
	v_sub_f32_e32 v87, v87, v89
	s_mov_b32 s10, -1
	v_mul_f32_e32 v88, v86, v123
	v_mul_f32_e32 v92, v90, v121
	v_mul_f32_e32 v90, v90, v122
	v_mul_f32_e32 v86, v86, v124
	v_fma_f32 v88, -v87, v124, v88
	v_fma_f32 v89, v87, v123, v86
	v_fma_f32 v92, -v91, v122, v92
	v_fma_f32 v90, v91, v121, v90
	v_add_f32_e32 v86, v92, v88
	v_add_f32_e32 v87, v90, v89
	v_sub_f32_e32 v88, v92, v88
	v_sub_f32_e32 v89, v90, v89
	ds_write2_b64 v120, v[86:87], v[88:89] offset1:1
	ds_read2_b64 v[86:89], v125 offset1:1
	s_waitcnt lgkmcnt(0)
	v_add_f32_e32 v90, v86, v88
	v_sub_f32_e32 v86, v86, v88
	v_add_f32_e32 v91, v87, v89
	v_sub_f32_e32 v87, v87, v89
	v_mul_f32_e32 v92, v90, v126
	v_mul_f32_e32 v90, v90, v127
	v_mul_f32_e32 v88, v86, v128
	v_mul_f32_e32 v86, v86, v129
	v_fma_f32 v90, v91, v126, v90
	v_fma_f32 v88, -v87, v129, v88
	v_fma_f32 v89, v87, v128, v86
	v_fma_f32 v92, -v91, v127, v92
	v_add_f32_e32 v86, v92, v88
	v_add_f32_e32 v87, v90, v89
	v_sub_f32_e32 v88, v92, v88
	v_sub_f32_e32 v89, v90, v89
	v_add_u32_e32 v90, 0x2000, v120
	ds_write2_b64 v90, v[86:87], v[88:89] offset0:64 offset1:65
	ds_read2_b64 v[86:89], v130 offset1:1
	s_waitcnt lgkmcnt(0)
	v_add_f32_e32 v90, v86, v88
	v_sub_f32_e32 v86, v86, v88
	v_add_f32_e32 v91, v87, v89
	v_sub_f32_e32 v87, v87, v89
	v_mul_f32_e32 v92, v90, v131
	v_mul_f32_e32 v90, v90, v132
	v_mul_f32_e32 v88, v86, v133
	v_mul_f32_e32 v86, v86, v134
	v_fma_f32 v90, v91, v131, v90
	v_fma_f32 v88, -v87, v134, v88
	v_fma_f32 v89, v87, v133, v86
	v_fma_f32 v92, -v91, v132, v92
	v_add_f32_e32 v86, v92, v88
	v_add_f32_e32 v87, v90, v89
	v_sub_f32_e32 v88, v92, v88
	v_sub_f32_e32 v89, v90, v89
	v_add_u32_e32 v90, 0x4000, v120
	ds_write2_b64 v90, v[86:87], v[88:89] offset0:128 offset1:129
	ds_read2_b64 v[86:89], v135 offset1:1
	s_waitcnt lgkmcnt(0)
	v_add_f32_e32 v90, v86, v88
	v_sub_f32_e32 v86, v86, v88
	v_add_f32_e32 v91, v87, v89
	v_sub_f32_e32 v87, v87, v89
	v_mul_f32_e32 v92, v90, v136
	v_mul_f32_e32 v90, v90, v137
	v_mul_f32_e32 v88, v86, v138
	v_mul_f32_e32 v86, v86, v139
	v_fma_f32 v90, v91, v136, v90
	v_fma_f32 v88, -v87, v139, v88
	v_fma_f32 v89, v87, v138, v86
	v_fma_f32 v92, -v91, v137, v92
	v_add_f32_e32 v86, v92, v88
	v_add_f32_e32 v87, v90, v89
	v_sub_f32_e32 v88, v92, v88
	v_sub_f32_e32 v89, v90, v89
	v_add_u32_e32 v90, 0x6000, v120
	ds_write2_b64 v90, v[86:87], v[88:89] offset0:192 offset1:193
	ds_read2_b64 v[86:89], v140 offset1:1
	s_waitcnt lgkmcnt(0)
	v_add_f32_e32 v90, v86, v88
	v_sub_f32_e32 v86, v86, v88
	v_add_f32_e32 v91, v87, v89
	v_sub_f32_e32 v87, v87, v89
	v_mul_f32_e32 v88, v86, v143
	v_mul_f32_e32 v92, v90, v141
	v_mul_f32_e32 v90, v90, v142
	v_mul_f32_e32 v86, v86, v144
	v_fma_f32 v88, -v87, v144, v88
	v_fma_f32 v89, v87, v143, v86
	v_fma_f32 v92, -v91, v142, v92
	v_fma_f32 v90, v91, v141, v90
	v_add_f32_e32 v86, v92, v88
	v_add_f32_e32 v87, v90, v89
	v_sub_f32_e32 v88, v92, v88
	v_sub_f32_e32 v89, v90, v89
	ds_write2_b64 v140, v[86:87], v[88:89] offset1:1
	ds_read2_b64 v[86:89], v145 offset1:1
	s_waitcnt lgkmcnt(0)
; #define LAS __attribute__((address_space(3)))
; __device__ __forceinline__ f32x2 cadd(f32x2 a, f32x2 b) { return (f32x2){fadd_(a.x, b.x), fadd_(a.y, b.y)}; }
; __device__ __forceinline__ f32x2 csub(f32x2 a, f32x2 b) { return (f32x2){fsub_(a.x, b.x), fsub_(a.y, b.y)}; }
; __device__ __forceinline__ f32x2 cmul(f32x2 a, f32x2 b) { return (f32x2){fnma_(a.y, b.y, fmul_(a.x, b.x)), ffma_(a.y, b.x, fmul_(a.x, b.y))}; }
; template <int NPT> __device__ __forceinline__ void mid_mul(LAS f32x2* X, int tid, const f32x2* K) {
;     if (NPT == 16) {
; #pragma unroll
;         for (int u = 0; u < 8; ++u) { LAS f32x2* Xb = X + PADI(2 * tid) + 1088 * u; const f32x2 a = Xb[0], b = Xb[1];
;             const f32x2 s = cmul(cadd(a, b), K[2 * u]), d = cmul(csub(a, b), K[2 * u + 1]); Xb[0] = cadd(s, d); Xb[1] = csub(s, d); } }
; template <int NPT> __device__ __forceinline__ void conv2(LAS f32x2* Xe, LAS f32x2* Xo, const f32x2* tw, int tid, f32x2* ve, f32x2* vo, const f32x2* KE, const f32x2* KO) {
;     ...
;     mid_mul<NPT>(Xe, tid, KE); mid_mul<NPT>(Xo, tid, KO);
;     __syncthreads();
	v_add_f32_e32 v90, v86, v88
	v_sub_f32_e32 v86, v86, v88
	v_add_f32_e32 v91, v87, v89
	v_sub_f32_e32 v87, v87, v89
	v_mul_f32_e32 v92, v90, v146
	v_mul_f32_e32 v90, v90, v147
	v_mul_f32_e32 v88, v86, v148
	v_mul_f32_e32 v86, v86, v149
	v_fma_f32 v90, v91, v146, v90
	v_fma_f32 v88, -v87, v149, v88
	v_fma_f32 v89, v87, v148, v86
	v_fma_f32 v92, -v91, v147, v92
	v_add_f32_e32 v86, v92, v88
	v_add_f32_e32 v87, v90, v89
	v_sub_f32_e32 v88, v92, v88
	v_sub_f32_e32 v89, v90, v89
	v_add_u32_e32 v90, 0xa800, v120
	ds_write2_b64 v90, v[86:87], v[88:89] offset0:64 offset1:65
	ds_read2_b64 v[86:89], v150 offset1:1
	s_waitcnt lgkmcnt(0)
	v_add_f32_e32 v90, v86, v88
	v_sub_f32_e32 v86, v86, v88
	v_add_f32_e32 v91, v87, v89
	v_sub_f32_e32 v87, v87, v89
	v_mul_f32_e32 v92, v90, v151
	v_mul_f32_e32 v90, v90, v152
	v_mul_f32_e32 v88, v86, v153
	v_mul_f32_e32 v86, v86, v154
	v_fma_f32 v90, v91, v151, v90
	v_fma_f32 v88, -v87, v154, v88
	v_fma_f32 v89, v87, v153, v86
	v_fma_f32 v92, -v91, v152, v92
	v_add_f32_e32 v86, v92, v88
	v_add_f32_e32 v87, v90, v89
	v_sub_f32_e32 v88, v92, v88
	v_sub_f32_e32 v89, v90, v89
	v_add_u32_e32 v90, 0xc800, v120
	ds_write2_b64 v90, v[86:87], v[88:89] offset0:128 offset1:129
	ds_read2_b64 v[86:89], v155 offset1:1
	s_waitcnt lgkmcnt(0)
	v_add_f32_e32 v90, v86, v88
	v_sub_f32_e32 v86, v86, v88
	v_add_f32_e32 v91, v87, v89
	v_sub_f32_e32 v87, v87, v89
	v_mul_f32_e32 v92, v90, v156
	v_mul_f32_e32 v90, v90, v157
	v_mul_f32_e32 v88, v86, v158
	v_mul_f32_e32 v86, v86, v159
	v_fma_f32 v90, v91, v156, v90
	v_fma_f32 v88, -v87, v159, v88
	v_fma_f32 v89, v87, v158, v86
	v_fma_f32 v92, -v91, v157, v92
	v_add_f32_e32 v86, v92, v88
	v_add_f32_e32 v87, v90, v89
	v_sub_f32_e32 v88, v92, v88
	v_sub_f32_e32 v89, v90, v89
	v_add_u32_e32 v90, 0xe800, v120
	ds_write2_b64 v90, v[86:87], v[88:89] offset0:192 offset1:193
	ds_read2_b64 v[86:89], v160 offset1:1
	s_waitcnt lgkmcnt(0)
	v_add_f32_e32 v90, v86, v88
	v_sub_f32_e32 v86, v86, v88
	v_add_f32_e32 v91, v87, v89
	v_sub_f32_e32 v87, v87, v89
	v_mul_f32_e32 v88, v86, v163
	v_mul_f32_e32 v92, v90, v161
	v_mul_f32_e32 v90, v90, v162
	v_mul_f32_e32 v86, v86, v164
	v_fma_f32 v88, -v87, v164, v88
	v_fma_f32 v89, v87, v163, v86
	v_fma_f32 v92, -v91, v162, v92
	v_fma_f32 v90, v91, v161, v90
	v_add_f32_e32 v86, v92, v88
	v_add_f32_e32 v87, v90, v89
	v_sub_f32_e32 v88, v92, v88
	v_sub_f32_e32 v89, v90, v89
	ds_write2_b64 v160, v[86:87], v[88:89] offset1:1
	ds_read2_b64 v[86:89], v165 offset1:1
	s_waitcnt lgkmcnt(0)
	v_add_f32_e32 v90, v86, v88
	v_sub_f32_e32 v86, v86, v88
	v_add_f32_e32 v91, v87, v89
	v_sub_f32_e32 v87, v87, v89
	v_mul_f32_e32 v92, v90, v166
	v_mul_f32_e32 v90, v90, v167
	v_mul_f32_e32 v88, v86, v168
	v_mul_f32_e32 v86, v86, v169
	v_fma_f32 v90, v91, v166, v90
	v_fma_f32 v88, -v87, v169, v88
	v_fma_f32 v89, v87, v168, v86
	v_fma_f32 v92, -v91, v167, v92
	v_add_f32_e32 v86, v92, v88
	v_add_f32_e32 v87, v90, v89
	v_sub_f32_e32 v88, v92, v88
	v_sub_f32_e32 v89, v90, v89
	v_add_u32_e32 v90, 0x2000, v160
	ds_write2_b64 v90, v[86:87], v[88:89] offset0:64 offset1:65
	ds_read2_b64 v[86:89], v170 offset1:1
	s_waitcnt lgkmcnt(0)
	v_add_f32_e32 v90, v86, v88
	v_sub_f32_e32 v86, v86, v88
	v_add_f32_e32 v91, v87, v89
	v_sub_f32_e32 v87, v87, v89
	v_mul_f32_e32 v92, v90, v171
	v_mul_f32_e32 v90, v90, v172
	v_mul_f32_e32 v88, v86, v173
	v_mul_f32_e32 v86, v86, v174
	v_fma_f32 v90, v91, v171, v90
	v_fma_f32 v88, -v87, v174, v88
	v_fma_f32 v89, v87, v173, v86
	v_fma_f32 v92, -v91, v172, v92
	v_add_f32_e32 v86, v92, v88
	v_add_f32_e32 v87, v90, v89
	v_sub_f32_e32 v88, v92, v88
	v_sub_f32_e32 v89, v90, v89
	v_add_u32_e32 v90, 0x4000, v160
	ds_write2_b64 v90, v[86:87], v[88:89] offset0:128 offset1:129
	ds_read2_b64 v[86:89], v175 offset1:1
	s_waitcnt lgkmcnt(0)
	v_add_f32_e32 v90, v86, v88
	v_sub_f32_e32 v86, v86, v88
	v_add_f32_e32 v91, v87, v89
	v_sub_f32_e32 v87, v87, v89
	v_mul_f32_e32 v92, v90, v186
	v_mul_f32_e32 v90, v90, v187
	v_mul_f32_e32 v88, v86, v188
	v_mul_f32_e32 v86, v86, v189
	v_fma_f32 v90, v91, v186, v90
	v_fma_f32 v88, -v87, v189, v88
	v_fma_f32 v89, v87, v188, v86
	v_fma_f32 v92, -v91, v187, v92
	v_add_f32_e32 v86, v92, v88
	v_add_f32_e32 v87, v90, v89
	v_sub_f32_e32 v88, v92, v88
	v_sub_f32_e32 v89, v90, v89
	v_add_u32_e32 v90, 0x6000, v160
	ds_write2_b64 v90, v[86:87], v[88:89] offset0:192 offset1:193
	ds_read2_b64 v[86:89], v190 offset1:1
	s_waitcnt lgkmcnt(0)
	v_add_f32_e32 v90, v86, v88
	v_sub_f32_e32 v86, v86, v88
	v_add_f32_e32 v91, v87, v89
	v_sub_f32_e32 v87, v87, v89
	v_mul_f32_e32 v88, v86, v193
	v_mul_f32_e32 v92, v90, v191
	v_mul_f32_e32 v90, v90, v192
	v_mul_f32_e32 v86, v86, v202
	v_fma_f32 v88, -v87, v202, v88
	v_fma_f32 v89, v87, v193, v86
	v_fma_f32 v92, -v91, v192, v92
	v_fma_f32 v90, v91, v191, v90
	v_add_f32_e32 v86, v92, v88
	v_add_f32_e32 v87, v90, v89
	v_sub_f32_e32 v88, v92, v88
	v_sub_f32_e32 v89, v90, v89
	ds_write2_b64 v190, v[86:87], v[88:89] offset1:1
	ds_read2_b64 v[86:89], v203 offset1:1
	s_waitcnt lgkmcnt(0)
	v_add_f32_e32 v90, v86, v88
	v_sub_f32_e32 v86, v86, v88
	v_add_f32_e32 v91, v87, v89
	v_sub_f32_e32 v87, v87, v89
	v_mul_f32_e32 v92, v90, v204
	v_mul_f32_e32 v90, v90, v205
	v_mul_f32_e32 v88, v86, v206
	v_mul_f32_e32 v86, v86, v207
	v_fma_f32 v90, v91, v204, v90
	v_fma_f32 v88, -v87, v207, v88
	v_fma_f32 v89, v87, v206, v86
	v_fma_f32 v92, -v91, v205, v92
	v_add_f32_e32 v86, v92, v88
	v_add_f32_e32 v87, v90, v89
	v_sub_f32_e32 v88, v92, v88
	v_sub_f32_e32 v89, v90, v89
	v_add_u32_e32 v90, 0xa800, v160
	ds_write2_b64 v90, v[86:87], v[88:89] offset0:64 offset1:65
	ds_read2_b64 v[86:89], v208 offset1:1
	s_waitcnt lgkmcnt(0)
	v_add_f32_e32 v90, v86, v88
	v_sub_f32_e32 v86, v86, v88
	v_add_f32_e32 v91, v87, v89
	v_sub_f32_e32 v87, v87, v89
	v_mul_f32_e32 v92, v90, v209
	v_mul_f32_e32 v90, v90, v210
	v_mul_f32_e32 v88, v86, v211
	v_mul_f32_e32 v86, v86, v212
	v_fma_f32 v90, v91, v209, v90
	v_fma_f32 v88, -v87, v212, v88
	v_fma_f32 v89, v87, v211, v86
	v_fma_f32 v92, -v91, v210, v92
	v_add_f32_e32 v86, v92, v88
	v_add_f32_e32 v87, v90, v89
	v_sub_f32_e32 v88, v92, v88
	v_sub_f32_e32 v89, v90, v89
	v_add_u32_e32 v90, 0xc800, v160
	ds_write2_b64 v90, v[86:87], v[88:89] offset0:128 offset1:129
	ds_read2_b64 v[86:89], v213 offset1:1
	s_waitcnt lgkmcnt(0)
	v_add_f32_e32 v90, v86, v88
	v_sub_f32_e32 v86, v86, v88
	v_add_f32_e32 v91, v87, v89
	v_sub_f32_e32 v87, v87, v89
	v_mul_f32_e32 v92, v90, v214
	v_mul_f32_e32 v90, v90, v215
	v_mul_f32_e32 v88, v86, v216
	v_mul_f32_e32 v86, v86, v217
	v_fma_f32 v90, v91, v214, v90
	v_fma_f32 v89, v87, v216, v86
	v_fma_f32 v88, -v87, v217, v88
	v_fma_f32 v92, -v91, v215, v92
	v_add_f32_e32 v87, v90, v89
	v_sub_f32_e32 v89, v90, v89
	v_add_u32_e32 v90, 0xe800, v160
	v_add_f32_e32 v86, v92, v88
	v_sub_f32_e32 v88, v92, v88
	ds_write2_b64 v90, v[86:87], v[88:89] offset0:192 offset1:193
	s_waitcnt lgkmcnt(0)
	s_barrier
; template <int R, bool UNIT> __device__ __forceinline__ void dit_regs(f32x2* v, f32x2 wbig) {
;     float k1 = 0.92387953251128674f, k2 = 0.70710678118654752f, k3 = 0.38268343236508977f; asm volatile("" : "+v"(k1), "+v"(k2), "+v"(k3));
;     f32x2 wbs[R]; wbs[R - 1] = wbig;
; #pragma unroll
;     for (int t = R - 2; t >= 0; --t) wbs[t] = cmul(wbs[t + 1], wbs[t + 1]);
; #pragma unroll
;     for (int t = 0; t < R; ++t) { const int half = 1 << t;
; #pragma unroll
;         for (int k = 0; k < (1 << R); ++k) if (!(k & half)) { const int kk = k & (half - 1), m = kk * (8 / half);
;             const f32x2 a = v[k]; f32x2 b = v[k + half];
;             if (UNIT) { if (m == 4) b = (f32x2){-b.y, b.x}; else if (m != 0) b = cmulc(b, CW16(m)); }
;             else { const f32x2 tw = (m == 0) ? wbs[t] : cmul(wbs[t], CW16(m)); b = cmulc(b, tw); }
;             v[k] = cadd(a, b); v[k + half] = csub(a, b); } }
; }
; template <int R> __device__ __forceinline__ void dif_pass_rt(LAS f32x2* X, int sl, const f32x2 wb_in, int tid) {
;     float wbx = wb_in.x, wby = wb_in.y; asm volatile("" : "+v"(wbx), "+v"(wby)); const f32x2 wb = {wbx, wby};
;     const int r = tid & ((1 << sl) - 1), base = ((tid >> sl) << (sl + R)) + r;
;     LAS f32x2* Xb = X + PADI(base); f32x2 v[1 << R];
; #pragma unroll
;     for (int k = 0; k < (1 << R); ++k) v[k] = Xb[(k << sl) + ((k << sl) >> 4)];
;     dif_regs<R, false>(v, wb);
; #pragma unroll
;     for (int k = 0; k < (1 << R); ++k) Xb[(k << sl) + ((k << sl) >> 4)] = v[k];
; }
; template <int R> __device__ __forceinline__ void dit_pass_rt(LAS f32x2* X, int sl, const f32x2 wb_in, int tid) {
;     float wbx = wb_in.x, wby = wb_in.y; asm volatile("" : "+v"(wbx), "+v"(wby)); const f32x2 wbig = {wbx, wby};
;     const int r = tid & ((1 << sl) - 1), base = ((tid >> sl) << (sl + R)) + r;
;     LAS f32x2* Xb = X + PADI(base); f32x2 v[1 << R];
; #pragma unroll
;     for (int k = 0; k < (1 << R); ++k) v[k] = Xb[(k << sl) + ((k << sl) >> 4)];
;     dit_regs<R, false>(v, wbig);
; #pragma unroll
;     for (int k = 0; k < (1 << R); ++k) Xb[(k << sl) + ((k << sl) >> 4)] = v[k];
; template <int NPT> __device__ __forceinline__ void conv2(LAS f32x2* Xe, LAS f32x2* Xo, const f32x2* tw, int tid, f32x2* ve, f32x2* vo, const f32x2* KE, const f32x2* KO) {
;     ...
;         const f32x2 wb = tw[(tid & ((1 << sl) - 1)) << (14 - R - sl)];
.LBB0_693:
	s_cmp_eq_u32 s10, 0
	s_cselect_b32 s11, 5, 1
	s_cmp_lg_u32 s10, 1
	s_cselect_b32 s83, s11, 9
	s_sub_i32 s11, 10, s83
	v_lshlrev_b32_e32 v86, s11, v32
	v_and_b32_e32 v86, 0x3ff, v86
	v_lshlrev_b32_e32 v176, 3, v86
	v_lshl_add_u64 v[86:87], s[50:51], 0, v[176:177]
	global_load_dwordx2 v[86:87], v[86:87], off
	v_bfe_u32 v88, v32, 0, s83
	v_ashrrev_i32_e32 v89, s83, v32
	s_add_i32 s11, s83, 4
	v_lshl_add_u32 v88, v89, s11, v88
	s_lshl_b32 s11, 1, s83
	s_ashr_i32 s24, s11, 4
	s_lshl_b32 s11, s11, 3
	s_lshl_b32 s24, s24, 3
	s_add_i32 s11, s24, s11
	s_lshl_b32 s24, 2, s83
	s_ashr_i32 s25, s24, 4
	s_lshl_b32 s24, s24, 3
	s_lshl_b32 s25, s25, 3
	s_add_i32 s24, s25, s24
	s_lshl_b32 s25, 3, s83
	s_ashr_i32 s26, s25, 4
	s_lshl_b32 s25, s25, 3
	s_lshl_b32 s26, s26, 3
	s_add_i32 s25, s26, s25
	s_lshl_b32 s26, 4, s83
	s_ashr_i32 s27, s26, 4
	s_lshl_b32 s26, s26, 3
	s_lshl_b32 s27, s27, 3
	s_add_i32 s26, s27, s26
	s_lshl_b32 s27, 5, s83
	s_ashr_i32 s30, s27, 4
	s_lshl_b32 s27, s27, 3
	s_lshl_b32 s30, s30, 3
	s_add_i32 s27, s30, s27
	s_lshl_b32 s30, 6, s83
	s_ashr_i32 s38, s30, 4
	s_lshl_b32 s30, s30, 3
	s_lshl_b32 s38, s38, 3
	s_add_i32 s30, s38, s30
	s_lshl_b32 s38, 7, s83
	s_ashr_i32 s39, s38, 4
	s_lshl_b32 s38, s38, 3
	s_lshl_b32 s39, s39, 3
	s_add_i32 s38, s39, s38
	s_lshl_b32 s39, 8, s83
	s_ashr_i32 s55, s39, 4
	s_lshl_b32 s39, s39, 3
	s_lshl_b32 s55, s55, 3
	s_add_i32 s39, s55, s39
	s_lshl_b32 s55, 9, s83
	s_ashr_i32 s63, s55, 4
	s_lshl_b32 s55, s55, 3
	s_lshl_b32 s63, s63, 3
	s_add_i32 s55, s63, s55
	s_lshl_b32 s63, 10, s83
	s_ashr_i32 s64, s63, 4
	s_lshl_b32 s63, s63, 3
	s_lshl_b32 s64, s64, 3
	v_ashrrev_i32_e32 v89, 4, v88
	s_add_i32 s63, s64, s63
	s_lshl_b32 s64, 11, s83
	v_lshlrev_b32_e32 v176, 3, v89
	v_lshlrev_b32_e32 v220, 3, v88
	s_ashr_i32 s65, s64, 4
	v_add3_u32 v222, 0, v176, v220
	s_lshl_b32 s64, s64, 3
	s_lshl_b32 s65, s65, 3
	v_add_u32_e32 v223, s11, v222
	v_add_u32_e32 v224, s24, v222
	v_add_u32_e32 v225, s25, v222
	s_add_i32 s64, s65, s64
	s_lshl_b32 s65, 12, s83
	s_ashr_i32 s80, s65, 4
	s_lshl_b32 s65, s65, 3
	s_lshl_b32 s80, s80, 3
	s_add_i32 s65, s80, s65
	s_lshl_b32 s80, 13, s83
	v_add_u32_e32 v226, s26, v222
	v_add_u32_e32 v227, s27, v222
	v_add_u32_e32 v229, s30, v222
	v_add_u32_e32 v230, s38, v222
	s_ashr_i32 s82, s80, 4
	s_lshl_b32 s80, s80, 3
	s_lshl_b32 s82, s82, 3
	s_waitcnt vmcnt(0) lgkmcnt(0)
	v_mov_b32_e32 v221, v87
	v_mov_b32_e32 v228, v86
	ds_read_b64 v[88:89], v222
	ds_read_b64 v[92:93], v223
	ds_read_b64 v[90:91], v224
	ds_read_b64 v[96:97], v225
	v_mul_f32_e32 v181, v228, v228
	v_mul_f32_e32 v182, v228, v221
	ds_read_b64 v[94:95], v226
	ds_read_b64 v[100:101], v227
	ds_read_b64 v[98:99], v229
	ds_read_b64 v[104:105], v230
	v_fma_f32 v181, -v221, v221, v181
	v_fma_f32 v182, v221, v228, v182
	s_add_i32 s80, s82, s80
	v_mul_f32_e32 v183, v181, v181
	v_mul_f32_e32 v184, v181, v182
	s_lshl_b32 s82, 14, s83
	v_fma_f32 v183, -v182, v182, v183
	v_fma_f32 v184, v182, v181, v184
	s_ashr_i32 s84, s82, 4
	v_mul_f32_e32 v185, v183, v183
	v_mul_f32_e32 v198, v183, v184
	v_add_u32_e32 v231, s39, v222
	v_fma_f32 v185, -v184, v184, v185
	v_fma_f32 v198, v184, v183, v198
	v_add_u32_e32 v232, s55, v222
	s_waitcnt lgkmcnt(6)
	v_mul_f32_e32 v239, v92, v185
	v_add_u32_e32 v233, s63, v222
	v_fma_f32 v239, v93, v198, v239
	v_mul_f32_e32 v93, v93, v185
	v_add_u32_e32 v234, s64, v222
	v_fma_f32 v92, -v92, v198, v93
	v_add_f32_e32 v93, v88, v239
	v_sub_f32_e32 v88, v88, v239
	s_lshl_b32 s82, s82, 3
	v_add_f32_e32 v240, v89, v92
	v_sub_f32_e32 v89, v89, v92
	s_waitcnt lgkmcnt(4)
	v_mul_f32_e32 v92, v96, v185
	s_lshl_b32 s84, s84, 3
	v_fma_f32 v92, v97, v198, v92
	v_mul_f32_e32 v97, v97, v185
	s_lshl_b32 s83, 15, s83
	v_fma_f32 v96, -v96, v198, v97
	v_add_f32_e32 v97, v90, v92
	v_sub_f32_e32 v90, v90, v92
	s_waitcnt lgkmcnt(2)
	v_mul_f32_e32 v92, v100, v185
	ds_read_b64 v[102:103], v231
	ds_read_b64 v[108:109], v232
	ds_read_b64 v[106:107], v233
	ds_read_b64 v[112:113], v234
	v_add_f32_e32 v239, v91, v96
	v_sub_f32_e32 v91, v91, v96
	v_fma_f32 v92, v101, v198, v92
	v_mul_f32_e32 v96, v101, v185
	s_add_i32 s82, s84, s82
	v_fma_f32 v96, -v100, v198, v96
	v_add_f32_e32 v100, v94, v92
	v_sub_f32_e32 v92, v94, v92
	s_ashr_i32 s84, s83, 4
	v_add_f32_e32 v101, v95, v96
	v_sub_f32_e32 v94, v95, v96
	s_waitcnt lgkmcnt(4)
	v_mul_f32_e32 v95, v104, v185
	v_mul_f32_e32 v96, v105, v185
	s_lshl_b32 s83, s83, 3
	v_fma_f32 v95, v105, v198, v95
	v_fma_f32 v96, -v104, v198, v96
	s_lshl_b32 s84, s84, 3
	v_add_f32_e32 v104, v98, v95
	v_sub_f32_e32 v95, v98, v95
	s_waitcnt lgkmcnt(2)
	v_mul_f32_e32 v98, v108, v185
	v_add_f32_e32 v105, v99, v96
	v_sub_f32_e32 v96, v99, v96
	v_mul_f32_e32 v99, v109, v185
	s_add_i32 s83, s84, s83
	v_fma_f32 v98, v109, v198, v98
	v_fma_f32 v99, -v108, v198, v99
	v_add_u32_e32 v235, s65, v222
	v_add_f32_e32 v108, v102, v98
	v_sub_f32_e32 v98, v102, v98
	s_waitcnt lgkmcnt(0)
	v_mul_f32_e32 v102, v112, v185
	v_add_u32_e32 v236, s80, v222
	v_add_u32_e32 v237, s82, v222
	v_add_u32_e32 v238, s83, v222
	v_add_f32_e32 v109, v103, v99
	v_sub_f32_e32 v99, v103, v99
	v_fma_f32 v102, v113, v198, v102
	v_mul_f32_e32 v103, v113, v185
	ds_read_b64 v[110:111], v235
	ds_read_b64 v[116:117], v236
	ds_read_b64 v[114:115], v237
	ds_read_b64 v[118:119], v238
	v_fma_f32 v103, -v112, v198, v103
	v_add_f32_e32 v112, v106, v102
	v_sub_f32_e32 v102, v106, v102
	s_waitcnt lgkmcnt(2)
	v_mul_f32_e32 v106, v116, v185
	v_mov_b32_e32 v178, 0x3f3504f3
	v_add_f32_e32 v113, v107, v103
	v_sub_f32_e32 v103, v107, v103
	v_fma_f32 v106, v117, v198, v106
	v_mul_f32_e32 v107, v117, v185
	v_mov_b32_e32 v179, 0x3f6c835e
	v_fma_f32 v107, -v116, v198, v107
	v_add_f32_e32 v116, v110, v106
	v_sub_f32_e32 v106, v110, v106
	s_waitcnt lgkmcnt(0)
; __device__ __forceinline__ f32x2 cadd(f32x2 a, f32x2 b) { return (f32x2){fadd_(a.x, b.x), fadd_(a.y, b.y)}; }
; __device__ __forceinline__ f32x2 csub(f32x2 a, f32x2 b) { return (f32x2){fsub_(a.x, b.x), fsub_(a.y, b.y)}; }
; __device__ __forceinline__ f32x2 cmul(f32x2 a, f32x2 b) { return (f32x2){fnma_(a.y, b.y, fmul_(a.x, b.x)), ffma_(a.y, b.x, fmul_(a.x, b.y))}; }
; __device__ __forceinline__ f32x2 cmulc(f32x2 a, f32x2 b) { return (f32x2){ffma_(a.y, b.y, fmul_(a.x, b.x)), fnma_(a.x, b.y, fmul_(a.y, b.x))}; }
; template <int R, bool UNIT> __device__ __forceinline__ void dit_regs(f32x2* v, f32x2 wbig) {
;     float k1 = 0.92387953251128674f, k2 = 0.70710678118654752f, k3 = 0.38268343236508977f; asm volatile("" : "+v"(k1), "+v"(k2), "+v"(k3));
;     f32x2 wbs[R]; wbs[R - 1] = wbig;
; #pragma unroll
;     for (int t = R - 2; t >= 0; --t) wbs[t] = cmul(wbs[t + 1], wbs[t + 1]);
; #pragma unroll
;     for (int t = 0; t < R; ++t) { const int half = 1 << t;
; #pragma unroll
;         for (int k = 0; k < (1 << R); ++k) if (!(k & half)) { const int kk = k & (half - 1), m = kk * (8 / half);
;             const f32x2 a = v[k]; f32x2 b = v[k + half];
;             if (UNIT) { if (m == 4) b = (f32x2){-b.y, b.x}; else if (m != 0) b = cmulc(b, CW16(m)); }
;             else { const f32x2 tw = (m == 0) ? wbs[t] : cmul(wbs[t], CW16(m)); b = cmulc(b, tw); }
;             v[k] = cadd(a, b); v[k + half] = csub(a, b); } }
	v_mul_f32_e32 v110, v118, v185
	v_mov_b32_e32 v180, 0x3ec3ef15
	v_add_f32_e32 v117, v111, v107
	v_sub_f32_e32 v107, v111, v107
	v_fma_f32 v110, v119, v198, v110
	v_mul_f32_e32 v111, v119, v185
	v_add3_u32 v176, s2, v176, v220
	v_fma_f32 v111, -v118, v198, v111
	v_add_f32_e32 v118, v114, v110
	v_sub_f32_e32 v110, v114, v110
	v_mul_f32_e32 v114, v97, v183
	v_mul_f32_e32 v198, v183, v197
	v_xor_b32_e32 v201, 0x80000000, v178
	v_add_f32_e32 v119, v115, v111
	v_sub_f32_e32 v111, v115, v111
	v_fma_f32 v114, v239, v184, v114
	v_mul_f32_e32 v115, v239, v183
	v_fma_f32 v198, v184, v177, v198
	v_xor_b32_e32 v199, 0x80000000, v180
	v_fma_f32 v97, -v97, v184, v115
	v_add_f32_e32 v115, v93, v114
	v_sub_f32_e32 v93, v93, v114
	v_mul_f32_e32 v114, v183, v177
	v_xor_b32_e32 v200, 0x80000000, v179
	v_fma_f32 v114, -v184, v197, v114
	v_add_f32_e32 v185, v240, v97
	v_sub_f32_e32 v97, v240, v97
	v_add_u32_e32 v220, s11, v176
	v_mul_f32_e32 v239, v90, v114
	s_add_i32 s10, s10, 1
	v_fma_f32 v239, v91, v198, v239
	v_mul_f32_e32 v91, v91, v114
	s_cmp_lg_u32 s10, 2
	v_fma_f32 v90, -v90, v198, v91
	v_add_f32_e32 v91, v88, v239
	v_sub_f32_e32 v88, v88, v239
	v_add_f32_e32 v240, v89, v90
	v_sub_f32_e32 v89, v89, v90
	v_mul_f32_e32 v90, v104, v183
	v_fma_f32 v90, v105, v184, v90
	v_mul_f32_e32 v105, v105, v183
	v_fma_f32 v104, -v104, v184, v105
	v_add_f32_e32 v105, v100, v90
	v_sub_f32_e32 v90, v100, v90
	v_add_f32_e32 v239, v101, v104
	v_sub_f32_e32 v100, v101, v104
	v_mul_f32_e32 v101, v95, v114
	v_fma_f32 v101, v96, v198, v101
	v_mul_f32_e32 v96, v96, v114
	v_fma_f32 v95, -v95, v198, v96
	v_add_f32_e32 v96, v92, v101
	v_sub_f32_e32 v92, v92, v101
	v_mul_f32_e32 v101, v113, v183
	v_add_f32_e32 v104, v94, v95
	v_sub_f32_e32 v94, v94, v95
	v_mul_f32_e32 v95, v112, v183
	v_fma_f32 v101, -v112, v184, v101
	v_fma_f32 v95, v113, v184, v95
	v_add_f32_e32 v113, v109, v101
	v_sub_f32_e32 v101, v109, v101
	v_add_f32_e32 v112, v108, v95
	v_sub_f32_e32 v95, v108, v95
	v_mul_f32_e32 v108, v102, v114
	v_fma_f32 v108, v103, v198, v108
	v_mul_f32_e32 v103, v103, v114
	v_fma_f32 v102, -v102, v198, v103
	v_add_f32_e32 v103, v98, v108
	v_sub_f32_e32 v98, v98, v108
	v_mul_f32_e32 v108, v119, v183
	v_add_f32_e32 v109, v99, v102
	v_sub_f32_e32 v99, v99, v102
	v_mul_f32_e32 v102, v118, v183
	v_fma_f32 v108, -v118, v184, v108
	v_mul_f32_e32 v183, v181, v201
	v_fma_f32 v102, v119, v184, v102
	v_add_f32_e32 v119, v117, v108
	v_sub_f32_e32 v108, v117, v108
	v_fma_f32 v184, v182, v178, v183
	v_add_f32_e32 v118, v116, v102
	v_sub_f32_e32 v102, v116, v102
	v_mul_f32_e32 v116, v110, v114
	v_fma_f32 v116, v111, v198, v116
	v_mul_f32_e32 v111, v111, v114
	v_fma_f32 v110, -v110, v198, v111
	v_add_f32_e32 v111, v106, v116
	v_sub_f32_e32 v106, v106, v116
	v_mul_f32_e32 v116, v239, v181
	v_add_f32_e32 v114, v107, v110
	v_sub_f32_e32 v107, v107, v110
	v_mul_f32_e32 v110, v105, v181
	v_fma_f32 v105, -v105, v182, v116
	v_fma_f32 v110, v239, v182, v110
	v_add_f32_e32 v117, v185, v105
	v_add_f32_e32 v116, v115, v110
	v_sub_f32_e32 v110, v115, v110
	v_sub_f32_e32 v115, v185, v105
	v_mul_f32_e32 v105, v181, v178
	v_fma_f32 v105, -v182, v201, v105
	v_mul_f32_e32 v185, v96, v105
	v_fma_f32 v185, v104, v184, v185
	v_mul_f32_e32 v104, v104, v105
	v_fma_f32 v96, -v96, v184, v104
	v_add_f32_e32 v104, v91, v185
	v_sub_f32_e32 v185, v91, v185
	v_mul_f32_e32 v91, v181, v177
	v_add_f32_e32 v198, v240, v96
	v_sub_f32_e32 v239, v240, v96
	v_fma_f32 v91, -v182, v197, v91
	v_mul_f32_e32 v96, v181, v197
	v_mul_f32_e32 v240, v90, v91
	v_fma_f32 v96, v182, v177, v96
	v_fma_f32 v240, v100, v96, v240
	v_mul_f32_e32 v100, v100, v91
	v_fma_f32 v90, -v90, v96, v100
	v_add_f32_e32 v100, v93, v240
	v_sub_f32_e32 v240, v93, v240
	v_fma_f32 v93, v182, v201, v183
	v_add_f32_e32 v241, v97, v90
	v_sub_f32_e32 v242, v97, v90
	v_fma_f32 v90, -v182, v201, v183
	v_mul_f32_e32 v97, v92, v90
	v_fma_f32 v97, v94, v93, v97
	v_mul_f32_e32 v94, v94, v90
	v_add_f32_e32 v183, v88, v97
	v_sub_f32_e32 v244, v88, v97
	v_mul_f32_e32 v88, v118, v181
	v_fma_f32 v92, -v92, v93, v94
	v_add_f32_e32 v243, v89, v92
	v_sub_f32_e32 v245, v89, v92
	v_fma_f32 v88, v119, v182, v88
	v_mul_f32_e32 v89, v119, v181
	v_fma_f32 v89, -v118, v182, v89
	v_add_f32_e32 v92, v112, v88
	v_sub_f32_e32 v112, v112, v88
	v_mul_f32_e32 v88, v111, v105
	v_add_f32_e32 v94, v113, v89
	v_sub_f32_e32 v113, v113, v89
	v_fma_f32 v88, v114, v184, v88
	v_mul_f32_e32 v89, v114, v105
	v_fma_f32 v89, -v111, v184, v89
	v_add_f32_e32 v97, v103, v88
	v_sub_f32_e32 v111, v103, v88
	v_mul_f32_e32 v88, v102, v91
	v_add_f32_e32 v105, v109, v89
	v_sub_f32_e32 v109, v109, v89
	v_fma_f32 v88, v108, v96, v88
	v_mul_f32_e32 v89, v108, v91
	v_fma_f32 v89, -v102, v96, v89
	v_add_f32_e32 v96, v95, v88
	v_sub_f32_e32 v114, v95, v88
	v_mul_f32_e32 v88, v106, v90
	v_fma_f32 v88, v107, v93, v88
	v_add_f32_e32 v102, v101, v89
	v_sub_f32_e32 v118, v101, v89
	v_mul_f32_e32 v89, v107, v90
	v_add_f32_e32 v101, v98, v88
	v_sub_f32_e32 v119, v98, v88
	v_mul_f32_e32 v88, v92, v228
	v_fma_f32 v89, -v106, v93, v89
	v_fma_f32 v90, v94, v221, v88
	v_mul_f32_e32 v88, v94, v228
	v_add_f32_e32 v103, v99, v89
	v_sub_f32_e32 v181, v99, v89
	v_fma_f32 v91, -v92, v221, v88
	v_mul_f32_e32 v92, v228, v179
	v_add_f32_e32 v88, v116, v90
	v_sub_f32_e32 v90, v116, v90
	v_mul_f32_e32 v116, v228, v199
	v_fma_f32 v92, -v221, v199, v92
	v_fma_f32 v93, v221, v179, v116
	v_add_f32_e32 v89, v117, v91
	v_sub_f32_e32 v91, v117, v91
	v_mul_f32_e32 v117, v228, v201
	v_fma_f32 v108, -v221, v200, v116
	v_mul_f32_e32 v94, v97, v92
	v_mul_f32_e32 v92, v105, v92
	v_fma_f32 v116, v221, v200, v116
	v_mov_b32_e32 v179, 0x3f6c835e
	v_fma_f32 v95, -v97, v93, v92
; #define LAS __attribute__((address_space(3)))
; __device__ __forceinline__ f32x2 cadd(f32x2 a, f32x2 b) { return (f32x2){fadd_(a.x, b.x), fadd_(a.y, b.y)}; }
; __device__ __forceinline__ f32x2 csub(f32x2 a, f32x2 b) { return (f32x2){fsub_(a.x, b.x), fsub_(a.y, b.y)}; }
; template <int R, bool UNIT> __device__ __forceinline__ void dit_regs(f32x2* v, f32x2 wbig) {
;     float k1 = 0.92387953251128674f, k2 = 0.70710678118654752f, k3 = 0.38268343236508977f; asm volatile("" : "+v"(k1), "+v"(k2), "+v"(k3));
;     f32x2 wbs[R]; wbs[R - 1] = wbig;
; #pragma unroll
;     for (int t = R - 2; t >= 0; --t) wbs[t] = cmul(wbs[t + 1], wbs[t + 1]);
; #pragma unroll
;     for (int t = 0; t < R; ++t) { const int half = 1 << t;
; #pragma unroll
;         for (int k = 0; k < (1 << R); ++k) if (!(k & half)) { const int kk = k & (half - 1), m = kk * (8 / half);
;             const f32x2 a = v[k]; f32x2 b = v[k + half];
;             if (UNIT) { if (m == 4) b = (f32x2){-b.y, b.x}; else if (m != 0) b = cmulc(b, CW16(m)); }
;             else { const f32x2 tw = (m == 0) ? wbs[t] : cmul(wbs[t], CW16(m)); b = cmulc(b, tw); }
;             v[k] = cadd(a, b); v[k + half] = csub(a, b); } }
; }
; template <int R> __device__ __forceinline__ void dif_pass_rt(LAS f32x2* X, int sl, const f32x2 wb_in, int tid) {
;     float wbx = wb_in.x, wby = wb_in.y; asm volatile("" : "+v"(wbx), "+v"(wby)); const f32x2 wb = {wbx, wby};
;     const int r = tid & ((1 << sl) - 1), base = ((tid >> sl) << (sl + R)) + r;
;     LAS f32x2* Xb = X + PADI(base); f32x2 v[1 << R];
; #pragma unroll
;     for (int k = 0; k < (1 << R); ++k) v[k] = Xb[(k << sl) + ((k << sl) >> 4)];
;     dif_regs<R, false>(v, wb);
; #pragma unroll
;     for (int k = 0; k < (1 << R); ++k) Xb[(k << sl) + ((k << sl) >> 4)] = v[k];
; }
; template <int R> __device__ __forceinline__ void dit_pass_rt(LAS f32x2* X, int sl, const f32x2 wb_in, int tid) {
;     float wbx = wb_in.x, wby = wb_in.y; asm volatile("" : "+v"(wbx), "+v"(wby)); const f32x2 wbig = {wbx, wby};
;     const int r = tid & ((1 << sl) - 1), base = ((tid >> sl) << (sl + R)) + r;
;     LAS f32x2* Xb = X + PADI(base); f32x2 v[1 << R];
; #pragma unroll
;     for (int k = 0; k < (1 << R); ++k) v[k] = Xb[(k << sl) + ((k << sl) >> 4)];
;     dit_regs<R, false>(v, wbig);
; #pragma unroll
;     for (int k = 0; k < (1 << R); ++k) Xb[(k << sl) + ((k << sl) >> 4)] = v[k];
	v_mul_f32_e32 v97, v228, v178
	v_fma_f32 v98, v221, v178, v117
	v_fma_f32 v94, v105, v93, v94
	v_mul_f32_e32 v178, v228, v200
	v_mul_f32_e32 v105, v228, v197
	v_add_f32_e32 v93, v198, v95
	v_fma_f32 v97, -v221, v201, v97
	v_sub_f32_e32 v95, v198, v95
	v_add_f32_e32 v92, v104, v94
	v_sub_f32_e32 v94, v104, v94
	v_fma_f32 v105, v221, v177, v105
	v_mul_f32_e32 v99, v96, v97
	v_mul_f32_e32 v97, v102, v97
	v_fma_f32 v99, v102, v98, v99
	v_fma_f32 v102, -v96, v98, v97
	v_add_f32_e32 v96, v100, v99
	v_sub_f32_e32 v98, v100, v99
	v_mul_f32_e32 v100, v228, v180
	v_add_f32_e32 v97, v241, v102
	v_sub_f32_e32 v99, v241, v102
	v_fma_f32 v102, v221, v180, v178
	v_mov_b32_e32 v180, 0x3ec3ef15
	v_fma_f32 v100, -v221, v200, v100
	v_mul_f32_e32 v104, v101, v100
	v_mul_f32_e32 v100, v103, v100
	v_fma_f32 v104, v103, v102, v104
	v_fma_f32 v103, -v101, v102, v100
	v_add_f32_e32 v100, v183, v104
	v_sub_f32_e32 v102, v183, v104
	v_mul_f32_e32 v104, v228, v177
	v_add_f32_e32 v101, v243, v103
	v_sub_f32_e32 v103, v243, v103
	v_add_u32_e32 v228, s55, v176
	v_fma_f32 v104, -v221, v197, v104
	v_mul_f32_e32 v106, v112, v104
	v_mul_f32_e32 v104, v113, v104
	v_fma_f32 v106, v113, v105, v106
	v_fma_f32 v107, -v112, v105, v104
	v_mul_f32_e32 v112, v111, v108
	v_mul_f32_e32 v108, v109, v108
	v_fma_f32 v113, v221, v201, v117
	v_add_f32_e32 v104, v110, v106
	v_sub_f32_e32 v106, v110, v106
	v_fma_f32 v110, v221, v199, v178
	v_add_f32_e32 v105, v115, v107
	v_sub_f32_e32 v107, v115, v107
	v_fma_f32 v112, v109, v110, v112
	v_fma_f32 v111, -v111, v110, v108
	v_add_f32_e32 v108, v185, v112
	v_sub_f32_e32 v110, v185, v112
	v_fma_f32 v112, -v221, v201, v117
	v_add_f32_e32 v109, v239, v111
	v_sub_f32_e32 v111, v239, v111
	v_mul_f32_e32 v115, v114, v112
	v_mul_f32_e32 v112, v118, v112
	v_fma_f32 v115, v118, v113, v115
	v_fma_f32 v117, -v114, v113, v112
	v_add_f32_e32 v112, v240, v115
	v_add_f32_e32 v113, v242, v117
	v_sub_f32_e32 v114, v240, v115
	v_sub_f32_e32 v115, v242, v117
	v_fma_f32 v117, -v221, v199, v178
	v_add_u32_e32 v221, s24, v176
	v_mul_f32_e32 v118, v119, v117
	v_mul_f32_e32 v117, v181, v117
	v_mov_b32_e32 v178, 0x3f3504f3
	v_fma_f32 v118, v181, v116, v118
	v_fma_f32 v119, -v119, v116, v117
	v_add_f32_e32 v116, v244, v118
	v_add_f32_e32 v117, v245, v119
	v_sub_f32_e32 v118, v244, v118
	v_sub_f32_e32 v119, v245, v119
	ds_write_b64 v222, v[88:89]
	ds_write_b64 v223, v[92:93]
	ds_write_b64 v224, v[96:97]
	ds_write_b64 v225, v[100:101]
	ds_write_b64 v226, v[104:105]
	ds_write_b64 v227, v[108:109]
	ds_write_b64 v229, v[112:113]
	ds_write_b64 v230, v[116:117]
	ds_write_b64 v231, v[90:91]
	ds_write_b64 v232, v[94:95]
	ds_write_b64 v233, v[98:99]
	ds_write_b64 v234, v[102:103]
	ds_write_b64 v235, v[106:107]
	ds_write_b64 v236, v[110:111]
	ds_write_b64 v237, v[114:115]
	ds_write_b64 v238, v[118:119]
	v_add_u32_e32 v222, s25, v176
	v_mul_f32_e32 v181, v86, v86
	v_mul_f32_e32 v182, v86, v87
	ds_read_b64 v[114:115], v176
	ds_read_b64 v[118:119], v220
	ds_read_b64 v[110:111], v221
	ds_read_b64 v[116:117], v222
	v_fma_f32 v181, -v87, v87, v181
	v_fma_f32 v182, v87, v86, v182
	v_add_u32_e32 v223, s26, v176
	v_mul_f32_e32 v183, v181, v181
	v_mul_f32_e32 v184, v181, v182
	v_add_u32_e32 v224, s27, v176
	v_fma_f32 v183, -v182, v182, v183
	v_fma_f32 v184, v182, v181, v184
	v_add_u32_e32 v225, s30, v176
	v_mul_f32_e32 v185, v183, v183
	v_mul_f32_e32 v198, v183, v184
	v_add_u32_e32 v226, s38, v176
	v_fma_f32 v185, -v184, v184, v185
	v_fma_f32 v198, v184, v183, v198
	ds_read_b64 v[106:107], v223
	ds_read_b64 v[112:113], v224
	ds_read_b64 v[102:103], v225
	ds_read_b64 v[108:109], v226
	s_waitcnt lgkmcnt(6)
	v_mul_f32_e32 v235, v118, v185
	v_add_u32_e32 v227, s39, v176
	v_fma_f32 v235, v119, v198, v235
	v_mul_f32_e32 v119, v119, v185
	v_add_u32_e32 v229, s63, v176
	v_fma_f32 v118, -v118, v198, v119
	v_add_f32_e32 v119, v114, v235
	v_sub_f32_e32 v114, v114, v235
	v_add_u32_e32 v230, s64, v176
	v_add_f32_e32 v236, v115, v118
	v_sub_f32_e32 v115, v115, v118
	s_waitcnt lgkmcnt(4)
	v_mul_f32_e32 v118, v116, v185
	ds_read_b64 v[98:99], v227
	ds_read_b64 v[104:105], v228
	ds_read_b64 v[94:95], v229
	ds_read_b64 v[100:101], v230
	v_fma_f32 v118, v117, v198, v118
	v_mul_f32_e32 v117, v117, v185
	v_add_u32_e32 v231, s65, v176
	v_fma_f32 v116, -v116, v198, v117
	v_add_f32_e32 v117, v110, v118
	v_sub_f32_e32 v110, v110, v118
	v_add_u32_e32 v232, s80, v176
	v_add_f32_e32 v235, v111, v116
	v_sub_f32_e32 v111, v111, v116
	s_waitcnt lgkmcnt(6)
	v_mul_f32_e32 v116, v112, v185
	v_add_u32_e32 v233, s82, v176
	v_fma_f32 v116, v113, v198, v116
	v_mul_f32_e32 v113, v113, v185
	v_add_u32_e32 v234, s83, v176
	v_fma_f32 v112, -v112, v198, v113
	v_add_f32_e32 v113, v106, v116
	v_sub_f32_e32 v106, v106, v116
	ds_read_b64 v[90:91], v231
	ds_read_b64 v[96:97], v232
	ds_read_b64 v[88:89], v233
	ds_read_b64 v[92:93], v234
	v_add_f32_e32 v118, v107, v112
	v_sub_f32_e32 v107, v107, v112
	s_waitcnt lgkmcnt(8)
	v_mul_f32_e32 v112, v108, v185
	v_fma_f32 v112, v109, v198, v112
	v_mul_f32_e32 v109, v109, v185
	v_xor_b32_e32 v201, 0x80000000, v178
	v_fma_f32 v108, -v108, v198, v109
	v_add_f32_e32 v109, v102, v112
	v_sub_f32_e32 v102, v102, v112
	v_xor_b32_e32 v199, 0x80000000, v180
	v_add_f32_e32 v116, v103, v108
	v_sub_f32_e32 v103, v103, v108
	s_waitcnt lgkmcnt(6)
	v_mul_f32_e32 v108, v104, v185
	v_xor_b32_e32 v200, 0x80000000, v179
	v_fma_f32 v108, v105, v198, v108
	v_mul_f32_e32 v105, v105, v185
	v_fma_f32 v104, -v104, v198, v105
	v_add_f32_e32 v105, v98, v108
	v_sub_f32_e32 v98, v98, v108
	v_add_f32_e32 v112, v99, v104
	v_sub_f32_e32 v99, v99, v104
	s_waitcnt lgkmcnt(4)
; __device__ __forceinline__ f32x2 cadd(f32x2 a, f32x2 b) { return (f32x2){fadd_(a.x, b.x), fadd_(a.y, b.y)}; }
; __device__ __forceinline__ f32x2 csub(f32x2 a, f32x2 b) { return (f32x2){fsub_(a.x, b.x), fsub_(a.y, b.y)}; }
; __device__ __forceinline__ f32x2 cmul(f32x2 a, f32x2 b) { return (f32x2){fnma_(a.y, b.y, fmul_(a.x, b.x)), ffma_(a.y, b.x, fmul_(a.x, b.y))}; }
; __device__ __forceinline__ f32x2 cmulc(f32x2 a, f32x2 b) { return (f32x2){ffma_(a.y, b.y, fmul_(a.x, b.x)), fnma_(a.x, b.y, fmul_(a.y, b.x))}; }
; template <int R, bool UNIT> __device__ __forceinline__ void dit_regs(f32x2* v, f32x2 wbig) {
;     float k1 = 0.92387953251128674f, k2 = 0.70710678118654752f, k3 = 0.38268343236508977f; asm volatile("" : "+v"(k1), "+v"(k2), "+v"(k3));
;     f32x2 wbs[R]; wbs[R - 1] = wbig;
; #pragma unroll
;     for (int t = R - 2; t >= 0; --t) wbs[t] = cmul(wbs[t + 1], wbs[t + 1]);
; #pragma unroll
;     for (int t = 0; t < R; ++t) { const int half = 1 << t;
; #pragma unroll
;         for (int k = 0; k < (1 << R); ++k) if (!(k & half)) { const int kk = k & (half - 1), m = kk * (8 / half);
;             const f32x2 a = v[k]; f32x2 b = v[k + half];
;             if (UNIT) { if (m == 4) b = (f32x2){-b.y, b.x}; else if (m != 0) b = cmulc(b, CW16(m)); }
;             else { const f32x2 tw = (m == 0) ? wbs[t] : cmul(wbs[t], CW16(m)); b = cmulc(b, tw); }
;             v[k] = cadd(a, b); v[k + half] = csub(a, b); } }
	v_mul_f32_e32 v104, v100, v185
	v_fma_f32 v104, v101, v198, v104
	v_mul_f32_e32 v101, v101, v185
	v_fma_f32 v100, -v100, v198, v101
	v_add_f32_e32 v101, v94, v104
	v_sub_f32_e32 v94, v94, v104
	v_add_f32_e32 v108, v95, v100
	v_sub_f32_e32 v95, v95, v100
	s_waitcnt lgkmcnt(2)
	v_mul_f32_e32 v100, v96, v185
	v_fma_f32 v100, v97, v198, v100
	v_mul_f32_e32 v97, v97, v185
	v_fma_f32 v96, -v96, v198, v97
	v_add_f32_e32 v97, v90, v100
	v_sub_f32_e32 v90, v90, v100
	v_add_f32_e32 v104, v91, v96
	v_sub_f32_e32 v91, v91, v96
	s_waitcnt lgkmcnt(0)
	v_mul_f32_e32 v96, v92, v185
	v_fma_f32 v96, v93, v198, v96
	v_mul_f32_e32 v93, v93, v185
	v_fma_f32 v92, -v92, v198, v93
	v_add_f32_e32 v93, v88, v96
	v_sub_f32_e32 v88, v88, v96
	v_mul_f32_e32 v96, v235, v183
	v_mul_f32_e32 v198, v183, v197
	v_add_f32_e32 v100, v89, v92
	v_sub_f32_e32 v89, v89, v92
	v_mul_f32_e32 v92, v117, v183
	v_fma_f32 v96, -v117, v184, v96
	v_fma_f32 v198, v184, v177, v198
	v_fma_f32 v92, v235, v184, v92
	v_add_f32_e32 v185, v236, v96
	v_sub_f32_e32 v96, v236, v96
	v_add_f32_e32 v117, v119, v92
	v_sub_f32_e32 v92, v119, v92
	v_mul_f32_e32 v119, v183, v177
	v_fma_f32 v119, -v184, v197, v119
	v_mul_f32_e32 v235, v110, v119
	v_fma_f32 v235, v111, v198, v235
	v_mul_f32_e32 v111, v111, v119
	v_fma_f32 v110, -v110, v198, v111
	v_add_f32_e32 v111, v114, v235
	v_sub_f32_e32 v114, v114, v235
	v_add_f32_e32 v236, v115, v110
	v_sub_f32_e32 v110, v115, v110
	v_mul_f32_e32 v115, v109, v183
	v_fma_f32 v115, v116, v184, v115
	v_mul_f32_e32 v116, v116, v183
	v_fma_f32 v109, -v109, v184, v116
	v_add_f32_e32 v116, v113, v115
	v_sub_f32_e32 v113, v113, v115
	v_mul_f32_e32 v115, v102, v119
	v_fma_f32 v115, v103, v198, v115
	v_mul_f32_e32 v103, v103, v119
	v_add_f32_e32 v235, v118, v109
	v_sub_f32_e32 v109, v118, v109
	v_fma_f32 v102, -v102, v198, v103
	v_add_f32_e32 v103, v106, v115
	v_sub_f32_e32 v106, v106, v115
	v_add_f32_e32 v118, v107, v102
	v_sub_f32_e32 v102, v107, v102
	v_mul_f32_e32 v107, v101, v183
	v_fma_f32 v107, v108, v184, v107
	v_mul_f32_e32 v108, v108, v183
	v_fma_f32 v101, -v101, v184, v108
	v_add_f32_e32 v108, v105, v107
	v_sub_f32_e32 v105, v105, v107
	v_mul_f32_e32 v107, v94, v119
	v_fma_f32 v107, v95, v198, v107
	v_mul_f32_e32 v95, v95, v119
	v_add_f32_e32 v115, v112, v101
	v_sub_f32_e32 v101, v112, v101
	v_fma_f32 v94, -v94, v198, v95
	v_add_f32_e32 v95, v98, v107
	v_sub_f32_e32 v98, v98, v107
	v_add_f32_e32 v112, v99, v94
	v_sub_f32_e32 v94, v99, v94
	v_mul_f32_e32 v99, v93, v183
	v_fma_f32 v99, v100, v184, v99
	v_mul_f32_e32 v100, v100, v183
	v_fma_f32 v93, -v93, v184, v100
	v_add_f32_e32 v100, v97, v99
	v_sub_f32_e32 v97, v97, v99
	v_mul_f32_e32 v99, v88, v119
	v_fma_f32 v99, v89, v198, v99
	v_mul_f32_e32 v89, v89, v119
	v_add_f32_e32 v107, v104, v93
	v_sub_f32_e32 v93, v104, v93
	v_fma_f32 v88, -v88, v198, v89
	v_add_f32_e32 v89, v90, v99
	v_sub_f32_e32 v90, v90, v99
	v_mul_f32_e32 v99, v235, v181
	v_add_f32_e32 v104, v91, v88
	v_sub_f32_e32 v88, v91, v88
	v_mul_f32_e32 v91, v116, v181
	v_fma_f32 v99, -v116, v182, v99
	v_fma_f32 v91, v235, v182, v91
	v_add_f32_e32 v119, v185, v99
	v_sub_f32_e32 v183, v185, v99
	v_mul_f32_e32 v99, v181, v201
	v_mul_f32_e32 v235, v181, v197
	v_add_f32_e32 v116, v117, v91
	v_sub_f32_e32 v117, v117, v91
	v_mul_f32_e32 v91, v181, v178
	v_fma_f32 v184, v182, v178, v99
	v_fma_f32 v235, v182, v177, v235
	v_fma_f32 v91, -v182, v201, v91
	v_mul_f32_e32 v185, v103, v91
	v_fma_f32 v185, v118, v184, v185
	v_mul_f32_e32 v118, v118, v91
	v_fma_f32 v103, -v103, v184, v118
	v_add_f32_e32 v118, v111, v185
	v_sub_f32_e32 v111, v111, v185
	v_add_f32_e32 v198, v236, v103
	v_sub_f32_e32 v185, v236, v103
	v_mul_f32_e32 v103, v181, v177
	v_fma_f32 v103, -v182, v197, v103
	v_mul_f32_e32 v236, v113, v103
	v_fma_f32 v236, v109, v235, v236
	v_mul_f32_e32 v109, v109, v103
	v_fma_f32 v109, -v113, v235, v109
	v_add_f32_e32 v113, v92, v236
	v_sub_f32_e32 v236, v92, v236
	v_fma_f32 v92, -v182, v201, v99
	v_add_f32_e32 v237, v96, v109
	v_sub_f32_e32 v238, v96, v109
	v_fma_f32 v96, v182, v201, v99
	v_mul_f32_e32 v99, v106, v92
	v_fma_f32 v99, v102, v96, v99
	v_mul_f32_e32 v102, v102, v92
	v_fma_f32 v102, -v106, v96, v102
	v_add_f32_e32 v106, v114, v99
	v_sub_f32_e32 v239, v114, v99
	v_mul_f32_e32 v99, v100, v181
	v_add_f32_e32 v109, v110, v102
	v_sub_f32_e32 v240, v110, v102
	v_fma_f32 v99, v107, v182, v99
	v_mul_f32_e32 v102, v107, v181
	v_fma_f32 v100, -v100, v182, v102
	v_add_f32_e32 v102, v108, v99
	v_sub_f32_e32 v108, v108, v99
	v_mul_f32_e32 v99, v89, v91
	v_mul_f32_e32 v91, v104, v91
	v_fma_f32 v89, -v89, v184, v91
	v_fma_f32 v99, v104, v184, v99
	v_mul_f32_e32 v91, v93, v103
	v_add_f32_e32 v107, v115, v100
	v_sub_f32_e32 v110, v115, v100
	v_add_f32_e32 v104, v112, v89
	v_sub_f32_e32 v112, v112, v89
	v_mul_f32_e32 v89, v97, v103
	v_fma_f32 v91, -v97, v235, v91
	v_add_f32_e32 v100, v95, v99
	v_sub_f32_e32 v114, v95, v99
	v_fma_f32 v89, v93, v235, v89
	v_add_f32_e32 v99, v101, v91
	v_sub_f32_e32 v181, v101, v91
	v_add_f32_e32 v97, v105, v89
	v_sub_f32_e32 v115, v105, v89
	v_mul_f32_e32 v89, v90, v92
	v_fma_f32 v89, v88, v96, v89
	v_mul_f32_e32 v88, v88, v92
	v_mul_f32_e32 v92, v86, v179
	v_fma_f32 v88, -v90, v96, v88
	v_fma_f32 v92, -v87, v199, v92
	v_mul_f32_e32 v96, v86, v178
	v_add_f32_e32 v101, v98, v89
	v_sub_f32_e32 v182, v98, v89
	v_add_f32_e32 v103, v94, v88
	v_sub_f32_e32 v184, v94, v88
	v_mul_f32_e32 v88, v102, v86
	v_mul_f32_e32 v94, v100, v92
	v_mul_f32_e32 v92, v104, v92
	v_fma_f32 v96, -v87, v201, v96
	v_fma_f32 v90, v107, v87, v88
	v_mul_f32_e32 v88, v107, v86
	v_fma_f32 v91, -v102, v87, v88
	v_add_f32_e32 v88, v116, v90
	v_sub_f32_e32 v90, v116, v90
; #define LAS __attribute__((address_space(3)))
; template <int R, bool UNIT> __device__ __forceinline__ void dit_regs(f32x2* v, f32x2 wbig) {
;     float k1 = 0.92387953251128674f, k2 = 0.70710678118654752f, k3 = 0.38268343236508977f; asm volatile("" : "+v"(k1), "+v"(k2), "+v"(k3));
;     f32x2 wbs[R]; wbs[R - 1] = wbig;
; #pragma unroll
;     for (int t = R - 2; t >= 0; --t) wbs[t] = cmul(wbs[t + 1], wbs[t + 1]);
; #pragma unroll
;     for (int t = 0; t < R; ++t) { const int half = 1 << t;
; #pragma unroll
;         for (int k = 0; k < (1 << R); ++k) if (!(k & half)) { const int kk = k & (half - 1), m = kk * (8 / half);
;             const f32x2 a = v[k]; f32x2 b = v[k + half];
;             if (UNIT) { if (m == 4) b = (f32x2){-b.y, b.x}; else if (m != 0) b = cmulc(b, CW16(m)); }
;             else { const f32x2 tw = (m == 0) ? wbs[t] : cmul(wbs[t], CW16(m)); b = cmulc(b, tw); }
;             v[k] = cadd(a, b); v[k + half] = csub(a, b); } }
; template <int NPT> __device__ __forceinline__ void conv2(LAS f32x2* Xe, LAS f32x2* Xo, const f32x2* tw, int tid, f32x2* ve, f32x2* vo, const f32x2* KE, const f32x2* KO) {
;     ...
;     { const LAS f32x2* Pe = Xe + PADI(tid); const LAS f32x2* Po = Xo + PADI(tid);
; #pragma unroll
;       for (int k = 0; k < NPT; ++k) { ve[k] = Pe[544 * k]; vo[k] = Po[544 * k]; } }
; }
; template <int NPT>
; __device__ __forceinline__ void hyena_unit(LAS unsigned char* lds, int ch, int rowbase, int nb, const float* H2, const float* w3, const float* bias, bf16_t* ST, const f32x2* T2, int tid_in) {
;     constexpr int N = 512 * NPT; int tid = tid_in; asm volatile("" : "+v"(tid));
;     LAS f32x2* Xe = (LAS f32x2*)lds; LAS f32x2* Xo = (LAS f32x2*)(lds + 69632); LAS float* wsm = (LAS float*)(lds + 139264);
;     __syncthreads();
;     if (tid < 128) wsm[tid] = w3[(tid & 63) * 1024 + (tid >> 6) * 512 + ch];
;     __syncthreads();
;     LAS float* FW = (LAS float*)Xe; LAS float* BW = FW + N;
;     const float dmin = -3.0701134573253945f, dmax = -15.350567286626973f;
;     const float delta = fabsf(dmin + (float)ch * ((dmax - dmin) / 511.0f));
;     const float bs = bias[ch];
;     {
;       const int lane = tid & 63, wv = tid >> 6, qs = lane & 3, rr = lane >> 2;
;       float wf[16], wb[16];
; #pragma unroll
;       for (int s4 = 0; s4 < 4; ++s4)
; #pragma unroll
	v_mul_f32_e32 v116, v86, v199
	v_fma_f32 v93, v87, v179, v116
	v_add_f32_e32 v89, v119, v91
	v_sub_f32_e32 v91, v119, v91
	v_mul_f32_e32 v119, v86, v200
	v_fma_f32 v94, v104, v93, v94
	v_fma_f32 v95, -v100, v93, v92
	v_mul_f32_e32 v100, v97, v96
	v_mul_f32_e32 v96, v99, v96
	v_fma_f32 v102, v87, v180, v119
	v_add_f32_e32 v92, v118, v94
	v_sub_f32_e32 v94, v118, v94
	v_mul_f32_e32 v118, v86, v201
	v_add_f32_e32 v93, v198, v95
	v_sub_f32_e32 v95, v198, v95
	v_fma_f32 v98, v87, v178, v118
	v_fma_f32 v100, v99, v98, v100
	v_fma_f32 v99, -v97, v98, v96
	v_add_f32_e32 v96, v113, v100
	v_sub_f32_e32 v98, v113, v100
	v_mul_f32_e32 v100, v86, v180
	v_add_f32_e32 v97, v237, v99
	v_sub_f32_e32 v99, v237, v99
	v_fma_f32 v100, -v87, v200, v100
	v_mul_f32_e32 v104, v101, v100
	v_mul_f32_e32 v100, v103, v100
	v_fma_f32 v104, v103, v102, v104
	v_fma_f32 v103, -v101, v102, v100
	v_add_f32_e32 v100, v106, v104
	v_sub_f32_e32 v102, v106, v104
	v_mul_f32_e32 v104, v86, v177
	v_mul_f32_e32 v86, v86, v197
	v_add_f32_e32 v101, v109, v103
	v_sub_f32_e32 v103, v109, v103
	v_fma_f32 v104, -v87, v197, v104
	v_fma_f32 v86, v87, v177, v86
	v_mul_f32_e32 v105, v108, v104
	v_mul_f32_e32 v104, v110, v104
	v_fma_f32 v106, v110, v86, v105
	v_fma_f32 v86, -v108, v86, v104
	v_fma_f32 v108, v87, v199, v119
	v_add_f32_e32 v105, v183, v86
	v_sub_f32_e32 v107, v183, v86
	v_fma_f32 v86, -v87, v200, v116
	v_add_f32_e32 v104, v117, v106
	v_sub_f32_e32 v106, v117, v106
	v_mul_f32_e32 v109, v114, v86
	v_mul_f32_e32 v86, v112, v86
	v_fma_f32 v110, v112, v108, v109
	v_fma_f32 v86, -v114, v108, v86
	v_fma_f32 v112, v87, v201, v118
	v_add_f32_e32 v108, v111, v110
	v_add_f32_e32 v109, v185, v86
	v_sub_f32_e32 v110, v111, v110
	v_sub_f32_e32 v111, v185, v86
	v_fma_f32 v86, -v87, v201, v118
	v_mul_f32_e32 v113, v115, v86
	v_mul_f32_e32 v86, v181, v86
	v_fma_f32 v86, -v115, v112, v86
	v_fma_f32 v114, v181, v112, v113
	v_add_f32_e32 v113, v238, v86
	v_sub_f32_e32 v115, v238, v86
	v_fma_f32 v86, -v87, v199, v119
	v_fma_f32 v87, v87, v200, v116
	v_add_f32_e32 v112, v236, v114
	v_sub_f32_e32 v114, v236, v114
	v_mul_f32_e32 v116, v182, v86
	v_mul_f32_e32 v86, v184, v86
	v_fma_f32 v116, v184, v87, v116
	v_fma_f32 v117, -v182, v87, v86
	v_add_f32_e32 v86, v239, v116
	v_add_f32_e32 v87, v240, v117
	v_sub_f32_e32 v116, v239, v116
	v_sub_f32_e32 v117, v240, v117
	ds_write_b64 v176, v[88:89]
	ds_write_b64 v220, v[92:93]
	ds_write_b64 v221, v[96:97]
	ds_write_b64 v222, v[100:101]
	ds_write_b64 v223, v[104:105]
	ds_write_b64 v224, v[108:109]
	ds_write_b64 v225, v[112:113]
	ds_write_b64 v226, v[86:87]
	ds_write_b64 v227, v[90:91]
	ds_write_b64 v228, v[94:95]
	ds_write_b64 v229, v[98:99]
	ds_write_b64 v230, v[102:103]
	ds_write_b64 v231, v[106:107]
	ds_write_b64 v232, v[110:111]
	ds_write_b64 v233, v[114:115]
	ds_write_b64 v234, v[116:117]
	s_waitcnt lgkmcnt(0)
	s_barrier
	s_cbranch_scc1 .LBB0_693
	global_load_dwordx2 v[114:115], v[0:1], off
	ds_read_b64 v[116:117], v218
	ds_read_b64 v[118:119], v218 offset:4352
	ds_read_b64 v[178:179], v218 offset:8704
	ds_read_b64 v[180:181], v218 offset:13056
	ds_read_b64 v[182:183], v219
	ds_read_b64 v[184:185], v219 offset:4352
	ds_read_b64 v[198:199], v219 offset:8704
	ds_read_b64 v[200:201], v219 offset:13056
	ds_read_b64 v[220:221], v218 offset:17408
	ds_read_b64 v[222:223], v218 offset:21760
	ds_read_b64 v[224:225], v218 offset:26112
	ds_read_b64 v[226:227], v218 offset:30464
	ds_read_b64 v[228:229], v219 offset:17408
	ds_read_b64 v[230:231], v219 offset:21760
	ds_read_b64 v[232:233], v219 offset:26112
	ds_read_b64 v[234:235], v219 offset:30464
	ds_read_b64 v[236:237], v218 offset:34816
	ds_read_b64 v[110:111], v218 offset:39168
	ds_read_b64 v[106:107], v218 offset:43520
	ds_read_b64 v[102:103], v218 offset:47872
	ds_read_b64 v[238:239], v219 offset:34816
	ds_read_b64 v[112:113], v219 offset:39168
	ds_read_b64 v[108:109], v219 offset:43520
	ds_read_b64 v[104:105], v219 offset:47872
	ds_read_b64 v[98:99], v218 offset:52224
	ds_read_b64 v[94:95], v218 offset:56576
	ds_read_b64 v[90:91], v218 offset:60928
	ds_read_b64 v[86:87], v218 offset:65280
	ds_read_b64 v[100:101], v219 offset:52224
	ds_read_b64 v[96:97], v219 offset:56576
	ds_read_b64 v[92:93], v219 offset:60928
	ds_read_b64 v[88:89], v219 offset:65280
	s_waitcnt vmcnt(0) lgkmcnt(0)
	v_mul_f32_e32 v176, v182, v114
	v_mul_f32_e32 v114, v183, v114
	s_add_i32 s7, s7, 1
	v_fma_f32 v176, v183, v115, v176
	v_fma_f32 v114, -v182, v115, v114
	s_cmp_lg_u32 s7, 4
	v_add_f32_e32 v115, v116, v176
	v_add_f32_e32 v114, v117, v114
	s_nop 0
	v_bfe_u32 v116, v115, 16, 1
	v_bfe_u32 v117, v114, 16, 1
	v_add3_u32 v115, v115, v116, s97
	v_add3_u32 v114, v114, v117, s97
	global_store_short_d16_hi v[34:35], v115, off
	global_store_short_d16_hi v[36:37], v114, off
	global_load_dwordx2 v[114:115], v[2:3], off
	s_waitcnt vmcnt(0) lgkmcnt(0)
	v_mul_f32_e32 v116, v184, v114
	v_mul_f32_e32 v114, v185, v114
	v_fma_f32 v116, v185, v115, v116
	v_fma_f32 v114, -v184, v115, v114
	v_add_f32_e32 v115, v118, v116
	v_add_f32_e32 v114, v119, v114
	s_nop 0
	v_bfe_u32 v116, v115, 16, 1
	v_bfe_u32 v117, v114, 16, 1
	v_add3_u32 v115, v115, v116, s97
	v_add3_u32 v114, v114, v117, s97
	global_store_short_d16_hi v[34:35], v115, off offset:1024
	global_store_short_d16_hi v[36:37], v114, off offset:1024
	global_load_dwordx2 v[114:115], v[4:5], off
	s_waitcnt vmcnt(0) lgkmcnt(0)
	v_mul_f32_e32 v116, v198, v114
	v_mul_f32_e32 v114, v199, v114
	v_fma_f32 v116, v199, v115, v116
	v_fma_f32 v114, -v198, v115, v114
	v_add_f32_e32 v115, v178, v116
	v_add_f32_e32 v114, v179, v114
	s_nop 0
	v_bfe_u32 v116, v115, 16, 1
	v_bfe_u32 v117, v114, 16, 1
	v_add3_u32 v115, v115, v116, s97
	v_add3_u32 v114, v114, v117, s97
	global_store_short_d16_hi v[34:35], v115, off offset:2048
	global_store_short_d16_hi v[36:37], v114, off offset:2048
	global_load_dwordx2 v[114:115], v[6:7], off
	s_waitcnt vmcnt(0) lgkmcnt(0)
; __device__ __forceinline__ int fresh_lane() { int l; asm volatile("v_mbcnt_lo_u32_b32 %0, -1, 0\n\tv_mbcnt_hi_u32_b32 %0, -1, %0" : "=v"(l)); return l; }
; __device__ __forceinline__ float bf2f(unsigned h) { return __uint_as_float(h << 16); }
; __device__ __forceinline__ unsigned f2bf(float f) { unsigned u = __float_as_uint(f); return (u + 0x7fffu + ((u >> 16) & 1u)) >> 16; }
; __device__ __forceinline__ f32x2 cadd(f32x2 a, f32x2 b) { return (f32x2){fadd_(a.x, b.x), fadd_(a.y, b.y)}; }
; __device__ __forceinline__ f32x2 cmul(f32x2 a, f32x2 b) { return (f32x2){fnma_(a.y, b.y, fmul_(a.x, b.x)), ffma_(a.y, b.x, fmul_(a.x, b.y))}; }
; __device__ __forceinline__ f32x2 cmulc(f32x2 a, f32x2 b) { return (f32x2){ffma_(a.y, b.y, fmul_(a.x, b.x)), fnma_(a.x, b.y, fmul_(a.y, b.x))}; }
; template <int NPT>
; __device__ __forceinline__ void hyena_unit(LAS unsigned char* lds, int ch, int rowbase, int nb, const float* H2, const float* w3, const float* bias, bf16_t* ST, const f32x2* T2, int tid_in) {
;     ...
;         for (int i = 0; i < NPT; ++i) { const int j = tid + 512 * i; ve[i] = (f32x2){bf2f(s0[j]), bf2f(s1[j])}; vo[i] = cmul(ve[i], T2[j * (8192 / N)]); }
;         conv2<NPT>(Xe, Xo, tw, tid, ve, vo, KE, KO);
; #pragma unroll
;         for (int i = 0; i < NPT; ++i) { const int j = tid + 512 * i; const f32x2 y = cadd(ve[i], cmulc(vo[i], T2[j * (8192 / N)]));
;             s0[j] = (bf16_t)f2bf(y.x); s1[j] = (bf16_t)f2bf(y.y); }
;     }
;     __syncthreads();
; __global__ void __launch_bounds__(512, 2) mk_fwd(Params p) {
;     ...
;           if (DO(4)) for (int u = c.bid; u < 1024; u += c.G) {
;               if (u < 512) hyena_unit<16>(lds, u, 0, 8, H2l, w3, hb, ST, T2, c.wave * 64 + fresh_lane());
;               else hyena_unit<8>(lds, u - 512, MP, 4, H2l + 8192 * 64, w3, hb, ST, T2, c.wave * 64 + fresh_lane()); } }
	v_mul_f32_e32 v116, v200, v114
	v_mul_f32_e32 v114, v201, v114
	v_fma_f32 v116, v201, v115, v116
	v_fma_f32 v114, -v200, v115, v114
	v_add_f32_e32 v115, v180, v116
	v_add_f32_e32 v114, v181, v114
	s_nop 0
	v_bfe_u32 v116, v115, 16, 1
	v_bfe_u32 v117, v114, 16, 1
	v_add3_u32 v115, v115, v116, s97
	v_add3_u32 v114, v114, v117, s97
	global_store_short_d16_hi v[34:35], v115, off offset:3072
	global_store_short_d16_hi v[36:37], v114, off offset:3072
	global_load_dwordx2 v[34:35], v[8:9], off
	s_waitcnt vmcnt(0) lgkmcnt(0)
	v_mul_f32_e32 v36, v228, v34
	v_mul_f32_e32 v34, v229, v34
	v_fma_f32 v36, v229, v35, v36
	v_fma_f32 v34, -v228, v35, v34
	v_add_f32_e32 v35, v220, v36
	v_add_f32_e32 v34, v221, v34
	s_nop 0
	v_bfe_u32 v36, v35, 16, 1
	v_bfe_u32 v37, v34, 16, 1
	v_add3_u32 v35, v35, v36, s97
	v_add3_u32 v34, v34, v37, s97
	global_store_short_d16_hi v[62:63], v35, off
	global_store_short_d16_hi v[64:65], v34, off
	global_load_dwordx2 v[34:35], v[10:11], off
	s_waitcnt vmcnt(0) lgkmcnt(0)
	v_mul_f32_e32 v36, v230, v34
	v_mul_f32_e32 v34, v231, v34
	v_fma_f32 v36, v231, v35, v36
	v_fma_f32 v34, -v230, v35, v34
	v_add_f32_e32 v35, v222, v36
	v_add_f32_e32 v34, v223, v34
	s_nop 0
	v_bfe_u32 v36, v35, 16, 1
	v_bfe_u32 v37, v34, 16, 1
	v_add3_u32 v35, v35, v36, s97
	v_add3_u32 v34, v34, v37, s97
	global_store_short_d16_hi v[76:77], v35, off
	global_store_short_d16_hi v[80:81], v34, off
	global_load_dwordx2 v[34:35], v[12:13], off
	s_waitcnt vmcnt(0) lgkmcnt(0)
	v_mul_f32_e32 v36, v232, v34
	v_mul_f32_e32 v34, v233, v34
	v_fma_f32 v36, v233, v35, v36
	v_fma_f32 v34, -v232, v35, v34
	v_add_f32_e32 v35, v224, v36
	v_add_f32_e32 v34, v225, v34
	s_nop 0
	v_bfe_u32 v36, v35, 16, 1
	v_bfe_u32 v37, v34, 16, 1
	v_add3_u32 v35, v35, v36, s97
	v_add3_u32 v34, v34, v37, s97
	global_store_short_d16_hi v[82:83], v35, off
	global_store_short_d16_hi v[84:85], v34, off
	global_load_dwordx2 v[34:35], v[14:15], off
	s_waitcnt vmcnt(0) lgkmcnt(0)
	v_mul_f32_e32 v36, v234, v34
	v_mul_f32_e32 v34, v235, v34
	v_fma_f32 v36, v235, v35, v36
	v_fma_f32 v34, -v234, v35, v34
	v_add_f32_e32 v35, v226, v36
	v_add_f32_e32 v34, v227, v34
	s_nop 0
	v_bfe_u32 v36, v35, 16, 1
	v_bfe_u32 v37, v34, 16, 1
	v_add3_u32 v35, v35, v36, s97
	v_add3_u32 v34, v34, v37, s97
	global_store_short_d16_hi v[74:75], v35, off
	global_store_short_d16_hi v[78:79], v34, off
	global_load_dwordx2 v[34:35], v[16:17], off
	s_waitcnt vmcnt(0) lgkmcnt(0)
	v_mul_f32_e32 v36, v238, v34
	v_mul_f32_e32 v34, v239, v34
	v_fma_f32 v36, v239, v35, v36
	v_fma_f32 v34, -v238, v35, v34
	v_add_f32_e32 v35, v236, v36
	v_add_f32_e32 v34, v237, v34
	s_nop 0
	v_bfe_u32 v36, v35, 16, 1
	v_bfe_u32 v37, v34, 16, 1
	v_add3_u32 v35, v35, v36, s97
	v_add3_u32 v34, v34, v37, s97
	global_store_short_d16_hi v[70:71], v35, off
	global_store_short_d16_hi v[72:73], v34, off
	global_load_dwordx2 v[34:35], v[18:19], off
	s_waitcnt vmcnt(0) lgkmcnt(0)
	v_mul_f32_e32 v36, v112, v34
	v_mul_f32_e32 v34, v113, v34
	v_fma_f32 v36, v113, v35, v36
	v_fma_f32 v34, -v112, v35, v34
	v_add_f32_e32 v35, v110, v36
	v_add_f32_e32 v34, v111, v34
	s_nop 0
	v_bfe_u32 v36, v35, 16, 1
	v_bfe_u32 v37, v34, 16, 1
	v_add3_u32 v35, v35, v36, s97
	v_add3_u32 v34, v34, v37, s97
	global_store_short_d16_hi v[66:67], v35, off
	global_store_short_d16_hi v[68:69], v34, off
	global_load_dwordx2 v[34:35], v[20:21], off
	s_waitcnt vmcnt(0) lgkmcnt(0)
	v_mul_f32_e32 v36, v108, v34
	v_mul_f32_e32 v34, v109, v34
	v_fma_f32 v36, v109, v35, v36
	v_fma_f32 v34, -v108, v35, v34
	v_add_f32_e32 v35, v106, v36
	v_add_f32_e32 v34, v107, v34
	s_nop 0
	v_bfe_u32 v36, v35, 16, 1
	v_bfe_u32 v37, v34, 16, 1
	v_add3_u32 v35, v35, v36, s97
	v_add3_u32 v34, v34, v37, s97
	global_store_short_d16_hi v[58:59], v35, off
	global_store_short_d16_hi v[60:61], v34, off
	global_load_dwordx2 v[34:35], v[22:23], off
	s_waitcnt vmcnt(0) lgkmcnt(0)
	v_mul_f32_e32 v36, v104, v34
	v_mul_f32_e32 v34, v105, v34
	v_fma_f32 v36, v105, v35, v36
	v_fma_f32 v34, -v104, v35, v34
	v_add_f32_e32 v35, v102, v36
	v_add_f32_e32 v34, v103, v34
	s_nop 0
	v_bfe_u32 v36, v35, 16, 1
	v_bfe_u32 v37, v34, 16, 1
	v_add3_u32 v35, v35, v36, s97
	v_add3_u32 v34, v34, v37, s97
	global_store_short_d16_hi v[54:55], v35, off
	global_store_short_d16_hi v[56:57], v34, off
	global_load_dwordx2 v[34:35], v[24:25], off
	s_waitcnt vmcnt(0) lgkmcnt(0)
	v_mul_f32_e32 v36, v100, v34
	v_mul_f32_e32 v34, v101, v34
	v_fma_f32 v36, v101, v35, v36
	v_fma_f32 v34, -v100, v35, v34
	v_add_f32_e32 v35, v98, v36
	v_add_f32_e32 v34, v99, v34
	s_nop 0
	v_bfe_u32 v36, v35, 16, 1
	v_bfe_u32 v37, v34, 16, 1
	v_add3_u32 v35, v35, v36, s97
	v_add3_u32 v34, v34, v37, s97
	global_store_short_d16_hi v[50:51], v35, off
	global_store_short_d16_hi v[52:53], v34, off
	global_load_dwordx2 v[34:35], v[26:27], off
	s_waitcnt vmcnt(0) lgkmcnt(0)
	v_mul_f32_e32 v36, v96, v34
	v_mul_f32_e32 v34, v97, v34
	v_fma_f32 v36, v97, v35, v36
	v_fma_f32 v34, -v96, v35, v34
	v_add_f32_e32 v35, v94, v36
	v_add_f32_e32 v34, v95, v34
	s_nop 0
	v_bfe_u32 v36, v35, 16, 1
	v_bfe_u32 v37, v34, 16, 1
	v_add3_u32 v35, v35, v36, s97
	v_add3_u32 v34, v34, v37, s97
	global_store_short_d16_hi v[46:47], v35, off
	global_store_short_d16_hi v[48:49], v34, off
	global_load_dwordx2 v[34:35], v[28:29], off
	s_waitcnt vmcnt(0) lgkmcnt(0)
	v_mul_f32_e32 v36, v92, v34
	v_mul_f32_e32 v34, v93, v34
	v_fma_f32 v36, v93, v35, v36
	v_fma_f32 v34, -v92, v35, v34
	v_add_f32_e32 v35, v90, v36
	v_add_f32_e32 v34, v91, v34
	s_nop 0
	v_bfe_u32 v36, v35, 16, 1
	v_bfe_u32 v37, v34, 16, 1
	v_add3_u32 v35, v35, v36, s97
	v_add3_u32 v34, v34, v37, s97
	global_store_short_d16_hi v[42:43], v35, off
	global_store_short_d16_hi v[44:45], v34, off
	global_load_dwordx2 v[34:35], v[30:31], off
	s_waitcnt vmcnt(0) lgkmcnt(0)
	v_mul_f32_e32 v36, v88, v34
	v_mul_f32_e32 v34, v89, v34
	v_fma_f32 v36, v89, v35, v36
	v_fma_f32 v34, -v88, v35, v34
	v_add_f32_e32 v35, v86, v36
	v_add_f32_e32 v34, v87, v34
	s_nop 0
	v_bfe_u32 v36, v35, 16, 1
	v_bfe_u32 v37, v34, 16, 1
	v_add3_u32 v35, v35, v36, s97
	v_add3_u32 v34, v34, v37, s97
	global_store_short_d16_hi v[38:39], v35, off
	global_store_short_d16_hi v[40:41], v34, off
	s_cbranch_scc1 .LBB0_690
	s_mov_b64 s[84:85], 0x40000
	v_mov_b64_e32 v[228:229], 0x500
	s_waitcnt lgkmcnt(0)
	s_barrier
	s_branch .LBB0_609
